# v12 + one-time L2 prefetch of the next GEMM tile's weight rows in the last K-loop iteration
# baseline (speedup 1.0000x reference)
; DI f32x16 zero16() { f32x16 z; for (int i = 0; i < 16; ++i) z[i] = 0.f; return z; }
; template <bool AT>
; DI void gemm_main(f32x16 (&acc)[2][4], const u16* __restrict__ R, int ldr, const u16* __restrict__ Cm, int ldc,
;                   const u16* __restrict__ RT, int ldrt, int K, char* smem, int tid) {
;   constexpr int STG = 2 * 256 * 72;
;   u16* S0 = (u16*)smem;
;   const int lane = tid & 63, wave = tid >> 6, wr = wave >> 1, wc = wave & 1;
;   const int li = lane & 31, g = lane >> 5;
;   u32x4 rr[4], cr[4];
; #pragma unroll
;   for (int a = 0; a < 2; ++a)
; #pragma unroll
;     for (int b = 0; b < 4; ++b) acc[a][b] = zero16();
;   const int nk = K / 64;
; #pragma unroll
;   for (int i = 0; i < 4; ++i) {
;     const int cid = tid + NT * i;
;     const int row = cid >> 3, kc = cid & 7;
;     if (AT) {
;       const int kr = cid >> 5, tc = cid & 31;
;       rr[i] = *(const u32x4*)(RT + (size_t)kr * ldrt + tc * 8);
;     } else {
;       rr[i] = *(const u32x4*)(R + (size_t)row * ldr + kc * 8);
;     }
;     cr[i] = *(const u32x4*)(Cm + (size_t)row * ldc + kc * 8);
;   }
;   for (int kt = -1; kt < nk; ++kt) {
;     if (kt + 1 < nk) {
;       const int ks1 = kt + 1;
;       u16* Rs = S0 + (ks1 & 1) * STG;
;       u16* Cs = Rs + 256 * 72;
; #pragma unroll
;       for (int i = 0; i < 4; ++i) {
;         const int cid = tid + NT * i;
;         const int row = cid >> 3, kc = cid & 7;
;         if (AT && ks1 < 8) {
;           const int kr = cid >> 5, tc = cid & 31;
;           *(u32x4*)(Rs + kr * 264 + tc * 8) = rr[i];
;         } else {
;           *(u32x4*)(Rs + row * 72 + kc * 8) = rr[i];
;         }
;         *(u32x4*)(Cs + row * 72 + kc * 8) = cr[i];
;       }
.LBB0_328:
	s_or_b64 exec, exec, s[8:9]
	v_lshlrev_b32_e32 v0, 3, v176
	v_and_b32_e32 v0, 56, v0
	s_lshr_b32 s77, s88, 6
	s_lshl_b32 s56, s74, 8
	s_lshl_b32 s8, s78, 19
	v_lshlrev_b32_e32 v188, 1, v0
	v_add_u32_e32 v0, 0x200, v176
	s_add_u32 s8, s36, s8
	v_ashrrev_i32_e32 v36, 3, v0
	v_add_u32_e32 v0, 0x400, v176
	s_addc_u32 s9, s37, 0
	s_lshl_b64 s[78:79], s[56:57], 11
	v_readlane_b32 s80, v248, 29
	v_ashrrev_i32_e32 v32, 3, v176
	v_ashrrev_i32_e32 v40, 3, v0
	v_add_u32_e32 v0, 0x600, v176
	s_add_u32 s78, s80, s78
	v_readlane_b32 s80, v248, 30
	v_ashrrev_i32_e32 v33, 31, v32
	v_ashrrev_i32_e32 v37, 31, v36
	v_ashrrev_i32_e32 v44, 3, v0
	s_addc_u32 s79, s80, s79
	v_lshl_add_u64 v[12:13], s[8:9], 0, v[188:189]
	v_lshlrev_b64 v[34:35], 11, v[32:33]
	v_lshlrev_b64 v[38:39], 11, v[36:37]
	v_ashrrev_i32_e32 v41, 31, v40
	v_ashrrev_i32_e32 v45, 31, v44
	v_lshl_add_u64 v[28:29], s[78:79], 0, v[188:189]
	v_lshlrev_b64 v[42:43], 11, v[40:41]
	v_lshlrev_b64 v[46:47], 11, v[44:45]
	v_lshl_add_u64 v[52:53], v[12:13], 0, v[38:39]
	v_lshl_add_u64 v[54:55], v[12:13], 0, v[34:35]
	v_lshl_add_u64 v[48:49], v[12:13], 0, v[46:47]
	v_lshl_add_u64 v[50:51], v[12:13], 0, v[42:43]
	global_load_dwordx4 v[8:11], v[52:53], off
	global_load_dwordx4 v[12:15], v[54:55], off
	v_lshl_add_u64 v[56:57], v[28:29], 0, v[34:35]
	global_load_dwordx4 v[16:19], v[56:57], off
	v_lshl_add_u64 v[58:59], v[28:29], 0, v[38:39]
	global_load_dwordx4 v[20:23], v[58:59], off
	s_waitcnt lgkmcnt(0)
	global_load_dwordx4 v[0:3], v[48:49], off
	global_load_dwordx4 v[4:7], v[50:51], off
	v_lshl_add_u64 v[60:61], v[28:29], 0, v[42:43]
	global_load_dwordx4 v[24:27], v[60:61], off
	v_lshl_add_u64 v[62:63], v[28:29], 0, v[46:47]
	global_load_dwordx4 v[28:31], v[62:63], off
	global_load_dwordx4 v[144:147], v[54:55], off offset:128
	global_load_dwordx4 v[136:139], v[52:53], off offset:128
	global_load_dwordx4 v[132:135], v[50:51], off offset:128
	global_load_dwordx4 v[128:131], v[48:49], off offset:128
	global_load_dwordx4 v[152:155], v[56:57], off offset:128
	global_load_dwordx4 v[148:151], v[58:59], off offset:128
	global_load_dwordx4 v[140:143], v[60:61], off offset:128
	global_load_dwordx4 v[156:159], v[62:63], off offset:128
	v_and_b32_e32 v177, 31, v176
	v_lshrrev_b32_e32 v33, 1, v176
	s_mov_b32 s8, 0xfffffc0
	v_and_or_b32 v45, v33, s8, v177
	s_movk_i32 s8, 0x48
	v_mul_lo_u32 v185, v32, s8
	v_mul_lo_u32 v184, v36, s8
	v_mul_lo_u32 v183, v40, s8
	v_mul_lo_u32 v182, v44, s8
	s_lshl_b32 s8, s11, 8
	s_and_b32 s8, s8, 0xfffffc00
	s_mov_b32 s9, s57
	v_add_u32_e32 v186, 0, v188
	s_or_b32 s8, s8, s10
	v_lshlrev_b32_e32 v37, 1, v176
	v_lshlrev_b32_e32 v41, 4, v176
	v_lshl_add_u32 v36, v185, 1, v186
	s_lshl_b64 s[8:9], s[8:9], 11
	v_and_b32_e32 v178, 16, v33
	v_and_or_b32 v33, v37, s95, v177
	v_lshl_add_u32 v37, v184, 1, v186
	v_lshl_add_u32 v40, v183, 1, v186
	v_lshl_add_u32 v44, v182, 1, v186
	v_mul_u32_u24_e32 v179, 0x90, v33
	v_lshl_add_u64 v[32:33], v[46:47], 0, s[8:9]
	v_mul_lo_u32 v180, v45, s94
	v_add_u32_e32 v181, 0, v178
	s_mov_b32 s78, 0
	s_waitcnt vmcnt(14)
	ds_write_b128 v36, v[12:15]
	s_waitcnt vmcnt(13)
	ds_write_b128 v36, v[16:19] offset:36864
	ds_write_b128 v37, v[8:11]
	s_waitcnt vmcnt(12)
	ds_write_b128 v37, v[20:23] offset:36864
	s_waitcnt vmcnt(10)
	ds_write_b128 v40, v[4:7]
	s_waitcnt vmcnt(9)
	ds_write_b128 v40, v[24:27] offset:36864
	ds_write_b128 v44, v[0:3]
	s_waitcnt vmcnt(8)
	ds_write_b128 v44, v[28:31] offset:36864
	v_and_b32_e32 v2, 0x70, v41
	v_lshl_add_u64 v[0:1], v[42:43], 0, s[8:9]
	v_or_b32_e32 v0, v0, v2
	v_lshl_add_u64 v[162:163], s[72:73], 0, v[0:1]
	v_lshl_add_u64 v[0:1], v[38:39], 0, s[8:9]
	v_or_b32_e32 v0, v0, v2
	v_lshl_add_u64 v[164:165], s[72:73], 0, v[0:1]
	v_lshl_add_u64 v[0:1], v[34:35], 0, s[8:9]
	v_readlane_b32 s8, v248, 36
	v_or_b32_e32 v0, v0, v2
	s_add_u32 s8, s8, s64
	v_readlane_b32 s9, v248, 38
	v_or_b32_e32 v32, v32, v2
	v_lshl_add_u64 v[166:167], s[72:73], 0, v[0:1]
	v_or_b32_e32 v46, v46, v2
	s_addc_u32 s9, s9, 0
	v_or_b32_e32 v42, v42, v2
	v_or_b32_e32 v38, v38, v2
	v_or_b32_e32 v34, v34, v2
	v_mov_b32_e32 v0, 0
	v_lshl_add_u64 v[160:161], s[72:73], 0, v[32:33]
	v_lshl_add_u64 v[168:169], s[8:9], 0, v[46:47]
	v_lshl_add_u64 v[170:171], s[8:9], 0, v[42:43]
	v_lshl_add_u64 v[172:173], s[8:9], 0, v[38:39]
	v_lshl_add_u64 v[174:175], s[8:9], 0, v[34:35]
	s_mov_b64 s[8:9], 0
	v_mov_b32_e32 v1, v0
	v_mov_b32_e32 v2, v0
	v_mov_b32_e32 v3, v0
	v_mov_b32_e32 v4, v0
	v_mov_b32_e32 v5, v0
	v_mov_b32_e32 v6, v0
	v_mov_b32_e32 v7, v0
	v_mov_b32_e32 v8, v0
	v_mov_b32_e32 v9, v0
	v_mov_b32_e32 v10, v0
	v_mov_b32_e32 v11, v0
	v_mov_b32_e32 v12, v0
	v_mov_b32_e32 v13, v0
	v_mov_b32_e32 v14, v0
	v_mov_b32_e32 v15, v0
	v_mov_b32_e32 v16, v0
	v_mov_b32_e32 v17, v0
	v_mov_b32_e32 v18, v0
	v_mov_b32_e32 v19, v0
	v_mov_b32_e32 v20, v0
	v_mov_b32_e32 v21, v0
	v_mov_b32_e32 v22, v0
	v_mov_b32_e32 v23, v0
	v_mov_b32_e32 v24, v0
	v_mov_b32_e32 v25, v0
	v_mov_b32_e32 v26, v0
	v_mov_b32_e32 v27, v0
	v_mov_b32_e32 v28, v0
	v_mov_b32_e32 v29, v0
	v_mov_b32_e32 v30, v0
	v_mov_b32_e32 v31, v0
	v_mov_b32_e32 v32, v0
	v_mov_b32_e32 v33, v0
	v_mov_b32_e32 v34, v0
	v_mov_b32_e32 v35, v0
	v_mov_b32_e32 v36, v0
	v_mov_b32_e32 v37, v0
	v_mov_b32_e32 v38, v0
	v_mov_b32_e32 v39, v0
	v_mov_b32_e32 v40, v0
	v_mov_b32_e32 v41, v0
	v_mov_b32_e32 v42, v0
	v_mov_b32_e32 v43, v0
	v_mov_b32_e32 v44, v0
	v_mov_b32_e32 v45, v0
	v_mov_b32_e32 v46, v0
	v_mov_b32_e32 v47, v0
	v_mov_b32_e32 v48, v0
	v_mov_b32_e32 v49, v0
	v_mov_b32_e32 v50, v0
	v_mov_b32_e32 v51, v0
	v_mov_b32_e32 v52, v0
	v_mov_b32_e32 v53, v0
	v_mov_b32_e32 v54, v0
	v_mov_b32_e32 v55, v0
	v_mov_b32_e32 v56, v0
	v_mov_b32_e32 v57, v0
; template <bool AT>
; DI void gemm_main(f32x16 (&acc)[2][4], const u16* __restrict__ R, int ldr, const u16* __restrict__ Cm, int ldc,
;                   const u16* __restrict__ RT, int ldrt, int K, char* smem, int tid) {
;     ...
;   for (int kt = -1; kt < nk; ++kt) {
;     if (kt + 1 < nk) {
;       const int ks1 = kt + 1;
;       u16* Rs = S0 + (ks1 & 1) * STG;
;       u16* Cs = Rs + 256 * 72;
; #pragma unroll
;       for (int i = 0; i < 4; ++i) {
;         const int cid = tid + NT * i;
;         const int row = cid >> 3, kc = cid & 7;
;         if (AT && ks1 < 8) {
;           const int kr = cid >> 5, tc = cid & 31;
;           *(u32x4*)(Rs + kr * 264 + tc * 8) = rr[i];
;         } else {
;           *(u32x4*)(Rs + row * 72 + kc * 8) = rr[i];
;         }
;         *(u32x4*)(Cs + row * 72 + kc * 8) = cr[i];
;       }
;     }
;     if (kt + 2 < nk) {
;       const int kn = kt + 2;
; #pragma unroll
;       for (int i = 0; i < 4; ++i) {
;         const int cid = tid + NT * i;
;         const int row = cid >> 3, kc = cid & 7;
;         if (AT && kn < 8) {
;           const int kr = cid >> 5, tc = cid & 31;
;           rr[i] = *(const u32x4*)(RT + (size_t)(kn * 64 + kr) * ldrt + tc * 8);
;         } else {
;           rr[i] = *(const u32x4*)(R + (size_t)row * ldr + kn * 64 + kc * 8);
;         }
;         cr[i] = *(const u32x4*)(Cm + (size_t)row * ldc + kn * 64 + kc * 8);
;       }
;     }
;     __builtin_amdgcn_sched_barrier(0x38F);
;     if (kt >= 0) {
;       const u16* Rs = S0 + (kt & 1) * STG;
;       const u16* Cs = Rs + 256 * 72;
;       const u16* RTs = Rs;
; #pragma unroll
;       for (int ks = 0; ks < 4; ++ks) {
;         bf16x8 rf[2];
; #pragma unroll
;         for (int rb = 0; rb < 2; ++rb) {
;           if (AT && kt < 8) {
;             const u16* src = RTs + (16 * ks + 8 * g) * 264 + 64 * wr + 32 * rb + li;
;             bf16x8 t;
; #pragma unroll
;             for (int j = 0; j < 8; ++j) t[j] = (short)src[j * 264];
;             rf[rb] = t;
;           } else {
;             rf[rb] = *(const bf16x8*)(Rs + (64 * wr + 32 * rb + li) * 72 + 16 * ks + 8 * g);
;           }
;         }
; #pragma unroll
;         for (int cb = 0; cb < 4; ++cb) {
;           const bf16x8 cfv = *(const bf16x8*)(Cs + (128 * wc + 32 * cb + li) * 72 + 16 * ks + 8 * g);
; #pragma unroll
;           for (int rb = 0; rb < 2; ++rb) acc[rb][cb] = MFMA(rf[rb], cfv, acc[rb][cb]);
	v_mov_b32_e32 v58, v0
	v_mov_b32_e32 v59, v0
	v_mov_b32_e32 v60, v0
	v_mov_b32_e32 v61, v0
	v_mov_b32_e32 v62, v0
	v_mov_b32_e32 v63, v0
	v_mov_b32_e32 v64, v0
	v_mov_b32_e32 v65, v0
	v_mov_b32_e32 v66, v0
	v_mov_b32_e32 v67, v0
	v_mov_b32_e32 v68, v0
	v_mov_b32_e32 v69, v0
	v_mov_b32_e32 v70, v0
	v_mov_b32_e32 v71, v0
	v_mov_b32_e32 v72, v0
	v_mov_b32_e32 v73, v0
	v_mov_b32_e32 v74, v0
	v_mov_b32_e32 v75, v0
	v_mov_b32_e32 v76, v0
	v_mov_b32_e32 v77, v0
	v_mov_b32_e32 v78, v0
	v_mov_b32_e32 v79, v0
	v_mov_b32_e32 v80, v0
	v_mov_b32_e32 v81, v0
	v_mov_b32_e32 v82, v0
	v_mov_b32_e32 v83, v0
	v_mov_b32_e32 v84, v0
	v_mov_b32_e32 v85, v0
	v_mov_b32_e32 v86, v0
	v_mov_b32_e32 v87, v0
	v_mov_b32_e32 v88, v0
	v_mov_b32_e32 v89, v0
	v_mov_b32_e32 v90, v0
	v_mov_b32_e32 v91, v0
	v_mov_b32_e32 v92, v0
	v_mov_b32_e32 v93, v0
	v_mov_b32_e32 v94, v0
	v_mov_b32_e32 v95, v0
	v_mov_b32_e32 v96, v0
	v_mov_b32_e32 v97, v0
	v_mov_b32_e32 v98, v0
	v_mov_b32_e32 v99, v0
	v_mov_b32_e32 v100, v0
	v_mov_b32_e32 v101, v0
	v_mov_b32_e32 v102, v0
	v_mov_b32_e32 v103, v0
	v_mov_b32_e32 v104, v0
	v_mov_b32_e32 v105, v0
	v_mov_b32_e32 v106, v0
	v_mov_b32_e32 v107, v0
	v_mov_b32_e32 v108, v0
	v_mov_b32_e32 v109, v0
	v_mov_b32_e32 v110, v0
	v_mov_b32_e32 v111, v0
	v_mov_b32_e32 v112, v0
	v_mov_b32_e32 v113, v0
	v_mov_b32_e32 v114, v0
	v_mov_b32_e32 v115, v0
	v_mov_b32_e32 v116, v0
	v_mov_b32_e32 v117, v0
	v_mov_b32_e32 v118, v0
	v_mov_b32_e32 v119, v0
	v_mov_b32_e32 v120, v0
	v_mov_b32_e32 v121, v0
	v_mov_b32_e32 v122, v0
	v_mov_b32_e32 v123, v0
	v_mov_b32_e32 v124, v0
	v_mov_b32_e32 v125, v0
	v_mov_b32_e32 v126, v0
	v_mov_b32_e32 v127, v0
	s_waitcnt lgkmcnt(0)
	s_barrier
	v_add_u32_e32 v187, v181, v180
	v_add_u32_e32 v190, v181, v179
	v_lshl_add_u32 v191, v185, 1, v186
	v_lshl_add_u32 v196, v184, 1, v186
	v_lshl_add_u32 v197, v183, 1, v186
	v_lshl_add_u32 v249, v182, 1, v186
	v_add_u32_e32 v191, 0x12000, v191
	v_add_u32_e32 v196, 0x12000, v196
	v_add_u32_e32 v197, 0x12000, v197
	v_add_u32_e32 v249, 0x12000, v249
	s_mov_b32 s98, 0x1ff880
	s_mov_b32 s99, 0
	s_mov_b32 s100, 0xffe00780
	s_mov_b32 s101, -1
	s_movk_i32 s78, 7
.Lgt_loop:
	ds_read_b128 v[192:195], v187 offset:0
	ds_read_b128 v[220:223], v187 offset:4608
	ds_read_b128 v[232:235], v190 offset:36864
	ds_read_b128 v[236:239], v190 offset:41472
	ds_read_b128 v[240:243], v190 offset:46080
	ds_read_b128 v[244:247], v190 offset:50688
	ds_read_b128 v[224:227], v187 offset:32
	ds_read_b128 v[228:231], v187 offset:4640
	s_waitcnt lgkmcnt(5)
	v_mfma_f32_32x32x16_bf16 v[112:127], v[192:195], v[232:235], v[112:127]
	v_mfma_f32_32x32x16_bf16 v[48:63], v[220:223], v[232:235], v[48:63]
	ds_read_b128 v[232:235], v190 offset:36896
	s_waitcnt vmcnt(0)
	ds_write_b128 v191, v[144:147]
	s_waitcnt lgkmcnt(6)
	v_mfma_f32_32x32x16_bf16 v[96:111], v[192:195], v[236:239], v[96:111]
	v_mfma_f32_32x32x16_bf16 v[32:47], v[220:223], v[236:239], v[32:47]
	ds_read_b128 v[236:239], v190 offset:41504
	ds_write_b128 v191, v[152:155] offset:36864
	s_waitcnt lgkmcnt(7)
	v_mfma_f32_32x32x16_bf16 v[80:95], v[192:195], v[240:243], v[80:95]
	v_mfma_f32_32x32x16_bf16 v[16:31], v[220:223], v[240:243], v[16:31]
	ds_read_b128 v[240:243], v190 offset:46112
	ds_write_b128 v196, v[136:139]
	s_waitcnt lgkmcnt(8)
	v_mfma_f32_32x32x16_bf16 v[64:79], v[192:195], v[244:247], v[64:79]
	v_mfma_f32_32x32x16_bf16 v[0:15], v[220:223], v[244:247], v[0:15]
	ds_read_b128 v[244:247], v190 offset:50720
	ds_write_b128 v196, v[148:151] offset:36864
	ds_read_b128 v[192:195], v187 offset:64
	ds_read_b128 v[220:223], v187 offset:4672
	s_waitcnt lgkmcnt(9)
	v_mfma_f32_32x32x16_bf16 v[112:127], v[224:227], v[232:235], v[112:127]
	v_mfma_f32_32x32x16_bf16 v[48:63], v[228:231], v[232:235], v[48:63]
	ds_read_b128 v[232:235], v190 offset:36928
	ds_write_b128 v197, v[132:135]
	s_waitcnt lgkmcnt(9)
	v_mfma_f32_32x32x16_bf16 v[96:111], v[224:227], v[236:239], v[96:111]
	v_mfma_f32_32x32x16_bf16 v[32:47], v[228:231], v[236:239], v[32:47]
	ds_read_b128 v[236:239], v190 offset:41536
	ds_write_b128 v197, v[140:143] offset:36864
	s_waitcnt lgkmcnt(9)
	v_mfma_f32_32x32x16_bf16 v[80:95], v[224:227], v[240:243], v[80:95]
	v_mfma_f32_32x32x16_bf16 v[16:31], v[228:231], v[240:243], v[16:31]
	ds_read_b128 v[240:243], v190 offset:46144
	ds_write_b128 v249, v[128:131]
	s_waitcnt lgkmcnt(9)
	v_mfma_f32_32x32x16_bf16 v[64:79], v[224:227], v[244:247], v[64:79]
	v_mfma_f32_32x32x16_bf16 v[0:15], v[228:231], v[244:247], v[0:15]
	ds_read_b128 v[244:247], v190 offset:50752
	ds_write_b128 v249, v[156:159] offset:36864
	ds_read_b128 v[224:227], v187 offset:96
	ds_read_b128 v[228:231], v187 offset:4704
	s_waitcnt lgkmcnt(9)
	v_mfma_f32_32x32x16_bf16 v[112:127], v[192:195], v[232:235], v[112:127]
	v_mfma_f32_32x32x16_bf16 v[48:63], v[220:223], v[232:235], v[48:63]
	ds_read_b128 v[232:235], v190 offset:36960
	v_subrev_u32_e32 v191, 0x12000, v191
	global_load_dwordx4 v[144:147], v[174:175], off
	v_lshl_add_u64 v[174:175], v[174:175], 0, s[58:59]
	s_waitcnt lgkmcnt(8)
	v_mfma_f32_32x32x16_bf16 v[96:111], v[192:195], v[236:239], v[96:111]
	v_mfma_f32_32x32x16_bf16 v[32:47], v[220:223], v[236:239], v[32:47]
	ds_read_b128 v[236:239], v190 offset:41568
	v_subrev_u32_e32 v196, 0x12000, v196
	global_load_dwordx4 v[152:155], v[166:167], off
	v_lshl_add_u64 v[166:167], v[166:167], 0, s[58:59]
	s_waitcnt lgkmcnt(7)
	v_mfma_f32_32x32x16_bf16 v[80:95], v[192:195], v[240:243], v[80:95]
	v_mfma_f32_32x32x16_bf16 v[16:31], v[220:223], v[240:243], v[16:31]
	ds_read_b128 v[240:243], v190 offset:46176
	v_subrev_u32_e32 v197, 0x12000, v197
	global_load_dwordx4 v[136:139], v[172:173], off
	v_lshl_add_u64 v[172:173], v[172:173], 0, s[58:59]
	s_waitcnt lgkmcnt(6)
; template <bool AT>
; DI void gemm_main(f32x16 (&acc)[2][4], const u16* __restrict__ R, int ldr, const u16* __restrict__ Cm, int ldc,
;                   const u16* __restrict__ RT, int ldrt, int K, char* smem, int tid) {
;     ...
;   for (int kt = -1; kt < nk; ++kt) {
;     if (kt + 1 < nk) {
;       const int ks1 = kt + 1;
;       u16* Rs = S0 + (ks1 & 1) * STG;
;       u16* Cs = Rs + 256 * 72;
; #pragma unroll
;       for (int i = 0; i < 4; ++i) {
;         const int cid = tid + NT * i;
;         const int row = cid >> 3, kc = cid & 7;
;         if (AT && ks1 < 8) {
;           const int kr = cid >> 5, tc = cid & 31;
;           *(u32x4*)(Rs + kr * 264 + tc * 8) = rr[i];
;         } else {
;           *(u32x4*)(Rs + row * 72 + kc * 8) = rr[i];
;         }
;         *(u32x4*)(Cs + row * 72 + kc * 8) = cr[i];
;       }
;     }
;     if (kt + 2 < nk) {
;       const int kn = kt + 2;
; #pragma unroll
;       for (int i = 0; i < 4; ++i) {
;         const int cid = tid + NT * i;
;         const int row = cid >> 3, kc = cid & 7;
;         if (AT && kn < 8) {
;           const int kr = cid >> 5, tc = cid & 31;
;           rr[i] = *(const u32x4*)(RT + (size_t)(kn * 64 + kr) * ldrt + tc * 8);
;         } else {
;           rr[i] = *(const u32x4*)(R + (size_t)row * ldr + kn * 64 + kc * 8);
;         }
;         cr[i] = *(const u32x4*)(Cm + (size_t)row * ldc + kn * 64 + kc * 8);
;       }
;     }
;     __builtin_amdgcn_sched_barrier(0x38F);
;     if (kt >= 0) {
;       const u16* Rs = S0 + (kt & 1) * STG;
;       const u16* Cs = Rs + 256 * 72;
;       const u16* RTs = Rs;
; #pragma unroll
;       for (int ks = 0; ks < 4; ++ks) {
;         bf16x8 rf[2];
; #pragma unroll
;         for (int rb = 0; rb < 2; ++rb) {
;           if (AT && kt < 8) {
;             const u16* src = RTs + (16 * ks + 8 * g) * 264 + 64 * wr + 32 * rb + li;
;             bf16x8 t;
; #pragma unroll
;             for (int j = 0; j < 8; ++j) t[j] = (short)src[j * 264];
;             rf[rb] = t;
;           } else {
;             rf[rb] = *(const bf16x8*)(Rs + (64 * wr + 32 * rb + li) * 72 + 16 * ks + 8 * g);
;           }
;         }
; #pragma unroll
;         for (int cb = 0; cb < 4; ++cb) {
;           const bf16x8 cfv = *(const bf16x8*)(Cs + (128 * wc + 32 * cb + li) * 72 + 16 * ks + 8 * g);
; #pragma unroll
;           for (int rb = 0; rb < 2; ++rb) acc[rb][cb] = MFMA(rf[rb], cfv, acc[rb][cb]);
	v_mfma_f32_32x32x16_bf16 v[64:79], v[192:195], v[244:247], v[64:79]
	v_mfma_f32_32x32x16_bf16 v[0:15], v[220:223], v[244:247], v[0:15]
	ds_read_b128 v[244:247], v190 offset:50784
	v_subrev_u32_e32 v249, 0x12000, v249
	global_load_dwordx4 v[148:151], v[164:165], off
	v_lshl_add_u64 v[164:165], v[164:165], 0, s[58:59]
	v_add_u32_e32 v187, 0x12000, v187
	v_add_u32_e32 v190, 0x12000, v190
	s_waitcnt lgkmcnt(3)
	v_mfma_f32_32x32x16_bf16 v[112:127], v[224:227], v[232:235], v[112:127]
	v_mfma_f32_32x32x16_bf16 v[48:63], v[228:231], v[232:235], v[48:63]
	global_load_dwordx4 v[132:135], v[170:171], off
	v_lshl_add_u64 v[170:171], v[170:171], 0, s[58:59]
	s_waitcnt lgkmcnt(2)
	v_mfma_f32_32x32x16_bf16 v[96:111], v[224:227], v[236:239], v[96:111]
	v_mfma_f32_32x32x16_bf16 v[32:47], v[228:231], v[236:239], v[32:47]
	global_load_dwordx4 v[140:143], v[162:163], off
	v_lshl_add_u64 v[162:163], v[162:163], 0, s[58:59]
	s_waitcnt lgkmcnt(1)
	v_mfma_f32_32x32x16_bf16 v[80:95], v[224:227], v[240:243], v[80:95]
	v_mfma_f32_32x32x16_bf16 v[16:31], v[228:231], v[240:243], v[16:31]
	global_load_dwordx4 v[128:131], v[168:169], off
	v_lshl_add_u64 v[168:169], v[168:169], 0, s[58:59]
	s_waitcnt lgkmcnt(0)
	v_mfma_f32_32x32x16_bf16 v[64:79], v[224:227], v[244:247], v[64:79]
	v_mfma_f32_32x32x16_bf16 v[0:15], v[228:231], v[244:247], v[0:15]
	global_load_dwordx4 v[156:159], v[160:161], off
	v_lshl_add_u64 v[160:161], v[160:161], 0, s[58:59]
	s_waitcnt lgkmcnt(0)
	s_barrier
	ds_read_b128 v[192:195], v187 offset:0
	ds_read_b128 v[220:223], v187 offset:4608
	ds_read_b128 v[232:235], v190 offset:36864
	ds_read_b128 v[236:239], v190 offset:41472
	ds_read_b128 v[240:243], v190 offset:46080
	ds_read_b128 v[244:247], v190 offset:50688
	ds_read_b128 v[224:227], v187 offset:32
	ds_read_b128 v[228:231], v187 offset:4640
	s_waitcnt lgkmcnt(5)
	v_mfma_f32_32x32x16_bf16 v[112:127], v[192:195], v[232:235], v[112:127]
	v_mfma_f32_32x32x16_bf16 v[48:63], v[220:223], v[232:235], v[48:63]
	ds_read_b128 v[232:235], v190 offset:36896
	s_waitcnt vmcnt(0)
	ds_write_b128 v191, v[144:147]
	s_waitcnt lgkmcnt(6)
	v_mfma_f32_32x32x16_bf16 v[96:111], v[192:195], v[236:239], v[96:111]
	v_mfma_f32_32x32x16_bf16 v[32:47], v[220:223], v[236:239], v[32:47]
	ds_read_b128 v[236:239], v190 offset:41504
	ds_write_b128 v191, v[152:155] offset:36864
	s_waitcnt lgkmcnt(7)
	v_mfma_f32_32x32x16_bf16 v[80:95], v[192:195], v[240:243], v[80:95]
	v_mfma_f32_32x32x16_bf16 v[16:31], v[220:223], v[240:243], v[16:31]
	ds_read_b128 v[240:243], v190 offset:46112
	ds_write_b128 v196, v[136:139]
	s_waitcnt lgkmcnt(8)
	v_mfma_f32_32x32x16_bf16 v[64:79], v[192:195], v[244:247], v[64:79]
	v_mfma_f32_32x32x16_bf16 v[0:15], v[220:223], v[244:247], v[0:15]
	ds_read_b128 v[244:247], v190 offset:50720
	ds_write_b128 v196, v[148:151] offset:36864
	ds_read_b128 v[192:195], v187 offset:64
	ds_read_b128 v[220:223], v187 offset:4672
	s_waitcnt lgkmcnt(9)
	v_mfma_f32_32x32x16_bf16 v[112:127], v[224:227], v[232:235], v[112:127]
	v_mfma_f32_32x32x16_bf16 v[48:63], v[228:231], v[232:235], v[48:63]
	ds_read_b128 v[232:235], v190 offset:36928
	ds_write_b128 v197, v[132:135]
	s_cmp_eq_u32 s78, 1
	s_cbranch_scc0 .Lgt_nopf
	v_lshl_add_u64 v[166:167], v[166:167], 0, s[98:99]
	global_load_dword v251, v[166:167], off
	global_load_dword v251, v[166:167], off offset:128
	v_lshl_add_u64 v[166:167], v[166:167], 0, s[100:101]
	v_lshl_add_u64 v[164:165], v[164:165], 0, s[98:99]
	global_load_dword v251, v[164:165], off
	global_load_dword v251, v[164:165], off offset:128
	v_lshl_add_u64 v[164:165], v[164:165], 0, s[100:101]
	v_lshl_add_u64 v[162:163], v[162:163], 0, s[98:99]
	global_load_dword v251, v[162:163], off
	global_load_dword v251, v[162:163], off offset:128
	v_lshl_add_u64 v[162:163], v[162:163], 0, s[100:101]
	v_lshl_add_u64 v[160:161], v[160:161], 0, s[98:99]
	global_load_dword v251, v[160:161], off
	global_load_dword v251, v[160:161], off offset:128
	v_lshl_add_u64 v[160:161], v[160:161], 0, s[100:101]
.Lgt_nopf:
	s_waitcnt lgkmcnt(9)
	v_mfma_f32_32x32x16_bf16 v[96:111], v[224:227], v[236:239], v[96:111]
	v_mfma_f32_32x32x16_bf16 v[32:47], v[228:231], v[236:239], v[32:47]
	ds_read_b128 v[236:239], v190 offset:41536
	ds_write_b128 v197, v[140:143] offset:36864
	s_waitcnt lgkmcnt(9)
	v_mfma_f32_32x32x16_bf16 v[80:95], v[224:227], v[240:243], v[80:95]
	v_mfma_f32_32x32x16_bf16 v[16:31], v[228:231], v[240:243], v[16:31]
	ds_read_b128 v[240:243], v190 offset:46144
	ds_write_b128 v249, v[128:131]
	s_waitcnt lgkmcnt(9)
	v_mfma_f32_32x32x16_bf16 v[64:79], v[224:227], v[244:247], v[64:79]
	v_mfma_f32_32x32x16_bf16 v[0:15], v[228:231], v[244:247], v[0:15]
	ds_read_b128 v[244:247], v190 offset:50752
	ds_write_b128 v249, v[156:159] offset:36864
	ds_read_b128 v[224:227], v187 offset:96
	ds_read_b128 v[228:231], v187 offset:4704
	s_waitcnt lgkmcnt(9)
	v_mfma_f32_32x32x16_bf16 v[112:127], v[192:195], v[232:235], v[112:127]
	v_mfma_f32_32x32x16_bf16 v[48:63], v[220:223], v[232:235], v[48:63]
	ds_read_b128 v[232:235], v190 offset:36960
	v_add_u32_e32 v191, 0x12000, v191
	global_load_dwordx4 v[144:147], v[174:175], off
	v_lshl_add_u64 v[174:175], v[174:175], 0, s[58:59]
	s_waitcnt lgkmcnt(8)
	v_mfma_f32_32x32x16_bf16 v[96:111], v[192:195], v[236:239], v[96:111]
	v_mfma_f32_32x32x16_bf16 v[32:47], v[220:223], v[236:239], v[32:47]
	ds_read_b128 v[236:239], v190 offset:41568
	v_add_u32_e32 v196, 0x12000, v196
	global_load_dwordx4 v[152:155], v[166:167], off
	v_lshl_add_u64 v[166:167], v[166:167], 0, s[58:59]
	s_waitcnt lgkmcnt(7)
; template <bool AT>
; DI void gemm_main(f32x16 (&acc)[2][4], const u16* __restrict__ R, int ldr, const u16* __restrict__ Cm, int ldc,
;                   const u16* __restrict__ RT, int ldrt, int K, char* smem, int tid) {
;     ...
;   for (int kt = -1; kt < nk; ++kt) {
;     if (kt + 1 < nk) {
;       const int ks1 = kt + 1;
;       u16* Rs = S0 + (ks1 & 1) * STG;
;       u16* Cs = Rs + 256 * 72;
; #pragma unroll
;       for (int i = 0; i < 4; ++i) {
;         const int cid = tid + NT * i;
;         const int row = cid >> 3, kc = cid & 7;
;         if (AT && ks1 < 8) {
;           const int kr = cid >> 5, tc = cid & 31;
;           *(u32x4*)(Rs + kr * 264 + tc * 8) = rr[i];
;         } else {
;           *(u32x4*)(Rs + row * 72 + kc * 8) = rr[i];
;         }
;         *(u32x4*)(Cs + row * 72 + kc * 8) = cr[i];
;       }
;     }
;     if (kt + 2 < nk) {
;       const int kn = kt + 2;
; #pragma unroll
;       for (int i = 0; i < 4; ++i) {
;         const int cid = tid + NT * i;
;         const int row = cid >> 3, kc = cid & 7;
;         if (AT && kn < 8) {
;           const int kr = cid >> 5, tc = cid & 31;
;           rr[i] = *(const u32x4*)(RT + (size_t)(kn * 64 + kr) * ldrt + tc * 8);
;         } else {
;           rr[i] = *(const u32x4*)(R + (size_t)row * ldr + kn * 64 + kc * 8);
;         }
;         cr[i] = *(const u32x4*)(Cm + (size_t)row * ldc + kn * 64 + kc * 8);
;       }
;     }
;     __builtin_amdgcn_sched_barrier(0x38F);
;     if (kt >= 0) {
;       const u16* Rs = S0 + (kt & 1) * STG;
;       const u16* Cs = Rs + 256 * 72;
;       const u16* RTs = Rs;
; #pragma unroll
;       for (int ks = 0; ks < 4; ++ks) {
;         bf16x8 rf[2];
; #pragma unroll
;         for (int rb = 0; rb < 2; ++rb) {
;           if (AT && kt < 8) {
;             const u16* src = RTs + (16 * ks + 8 * g) * 264 + 64 * wr + 32 * rb + li;
;             bf16x8 t;
; #pragma unroll
;             for (int j = 0; j < 8; ++j) t[j] = (short)src[j * 264];
;             rf[rb] = t;
;           } else {
;             rf[rb] = *(const bf16x8*)(Rs + (64 * wr + 32 * rb + li) * 72 + 16 * ks + 8 * g);
;           }
;         }
; #pragma unroll
;         for (int cb = 0; cb < 4; ++cb) {
;           const bf16x8 cfv = *(const bf16x8*)(Cs + (128 * wc + 32 * cb + li) * 72 + 16 * ks + 8 * g);
; #pragma unroll
;           for (int rb = 0; rb < 2; ++rb) acc[rb][cb] = MFMA(rf[rb], cfv, acc[rb][cb]);
	v_mfma_f32_32x32x16_bf16 v[80:95], v[192:195], v[240:243], v[80:95]
	v_mfma_f32_32x32x16_bf16 v[16:31], v[220:223], v[240:243], v[16:31]
	ds_read_b128 v[240:243], v190 offset:46176
	v_add_u32_e32 v197, 0x12000, v197
	global_load_dwordx4 v[136:139], v[172:173], off
	v_lshl_add_u64 v[172:173], v[172:173], 0, s[58:59]
	s_waitcnt lgkmcnt(6)
	v_mfma_f32_32x32x16_bf16 v[64:79], v[192:195], v[244:247], v[64:79]
	v_mfma_f32_32x32x16_bf16 v[0:15], v[220:223], v[244:247], v[0:15]
	ds_read_b128 v[244:247], v190 offset:50784
	v_add_u32_e32 v249, 0x12000, v249
	global_load_dwordx4 v[148:151], v[164:165], off
	v_lshl_add_u64 v[164:165], v[164:165], 0, s[58:59]
	v_subrev_u32_e32 v187, 0x12000, v187
	v_subrev_u32_e32 v190, 0x12000, v190
	s_waitcnt lgkmcnt(3)
	v_mfma_f32_32x32x16_bf16 v[112:127], v[224:227], v[232:235], v[112:127]
	v_mfma_f32_32x32x16_bf16 v[48:63], v[228:231], v[232:235], v[48:63]
	global_load_dwordx4 v[132:135], v[170:171], off
	v_lshl_add_u64 v[170:171], v[170:171], 0, s[58:59]
	s_waitcnt lgkmcnt(2)
	v_mfma_f32_32x32x16_bf16 v[96:111], v[224:227], v[236:239], v[96:111]
	v_mfma_f32_32x32x16_bf16 v[32:47], v[228:231], v[236:239], v[32:47]
	global_load_dwordx4 v[140:143], v[162:163], off
	v_lshl_add_u64 v[162:163], v[162:163], 0, s[58:59]
	s_waitcnt lgkmcnt(1)
	v_mfma_f32_32x32x16_bf16 v[80:95], v[224:227], v[240:243], v[80:95]
	v_mfma_f32_32x32x16_bf16 v[16:31], v[228:231], v[240:243], v[16:31]
	global_load_dwordx4 v[128:131], v[168:169], off
	v_lshl_add_u64 v[168:169], v[168:169], 0, s[58:59]
	s_waitcnt lgkmcnt(0)
	v_mfma_f32_32x32x16_bf16 v[64:79], v[224:227], v[244:247], v[64:79]
	v_mfma_f32_32x32x16_bf16 v[0:15], v[228:231], v[244:247], v[0:15]
	global_load_dwordx4 v[156:159], v[160:161], off
	v_lshl_add_u64 v[160:161], v[160:161], 0, s[58:59]
	s_waitcnt lgkmcnt(0)
	s_barrier
	s_add_i32 s78, s78, -1
	s_cmp_lg_u32 s78, 0
	s_cbranch_scc1 .Lgt_loop
	s_add_i32 s8, 0, 0x12000
	v_add_u32_e32 v160, s8, v188
	v_lshlrev_b32_e32 v162, 1, v185
	v_add_u32_e32 v161, s90, v188
	v_add_u32_e32 v163, v160, v162
	s_waitcnt vmcnt(7)
	ds_write_b128 v163, v[144:147]
	v_add_u32_e32 v144, v161, v162
	s_waitcnt vmcnt(6)
	ds_write_b128 v144, v[152:155]
	v_lshlrev_b32_e32 v144, 1, v184
	v_add_u32_e32 v145, v160, v144
	s_waitcnt vmcnt(5)
	ds_write_b128 v145, v[136:139]
	v_add_u32_e32 v136, v161, v144
	s_waitcnt vmcnt(4)
	ds_write_b128 v136, v[148:151]
	v_lshlrev_b32_e32 v136, 1, v183
	v_add_u32_e32 v137, v160, v136
	s_waitcnt vmcnt(3)
	ds_write_b128 v137, v[132:135]
	v_add_u32_e32 v132, v161, v136
	s_waitcnt vmcnt(2)
	ds_write_b128 v132, v[140:143]
	v_lshlrev_b32_e32 v132, 1, v182
	v_add_u32_e32 v133, v160, v132
	s_waitcnt vmcnt(1)
	ds_write_b128 v133, v[128:131]
	v_add_u32_e32 v128, v161, v132
	s_waitcnt vmcnt(0)
	ds_write_b128 v128, v[156:159]
	v_add_u32_e32 v140, v181, v180
	ds_read_b128 v[128:131], v140
	ds_read_b128 v[136:139], v140 offset:4608
	v_add_u32_e32 v141, v181, v179
	ds_read_b128 v[132:135], v141 offset:36864
	s_waitcnt lgkmcnt(0)
	v_mfma_f32_32x32x16_bf16 v[112:127], v[128:131], v[132:135], v[112:127]
	v_bfe_u32 v145, v176, 6, 1
	s_cmp_lt_u32 s11, 12
	v_mfma_f32_32x32x16_bf16 v[48:63], v[136:139], v[132:135], v[48:63]
	ds_read_b128 v[132:135], v141 offset:41472
	s_waitcnt lgkmcnt(0)
	v_mfma_f32_32x32x16_bf16 v[96:111], v[128:131], v[132:135], v[96:111]
	v_mfma_f32_32x32x16_bf16 v[32:47], v[136:139], v[132:135], v[32:47]
	ds_read_b128 v[132:135], v141 offset:46080
	s_waitcnt lgkmcnt(0)
	v_mfma_f32_32x32x16_bf16 v[80:95], v[128:131], v[132:135], v[80:95]
	v_mfma_f32_32x32x16_bf16 v[16:31], v[136:139], v[132:135], v[16:31]
	ds_read_b128 v[132:135], v141 offset:50688
	s_waitcnt lgkmcnt(0)
	v_mfma_f32_32x32x16_bf16 v[64:79], v[128:131], v[132:135], v[64:79]
	v_mfma_f32_32x32x16_bf16 v[0:15], v[136:139], v[132:135], v[0:15]
	ds_read_b128 v[128:131], v140 offset:32
	ds_read_b128 v[132:135], v141 offset:36896
	ds_read_b128 v[136:139], v140 offset:4640
	s_waitcnt lgkmcnt(1)
	v_mfma_f32_32x32x16_bf16 v[112:127], v[128:131], v[132:135], v[112:127]
	s_waitcnt lgkmcnt(0)
	v_mfma_f32_32x32x16_bf16 v[48:63], v[136:139], v[132:135], v[48:63]
	ds_read_b128 v[132:135], v141 offset:41504
	s_waitcnt lgkmcnt(0)
	v_mfma_f32_32x32x16_bf16 v[96:111], v[128:131], v[132:135], v[96:111]
	v_mfma_f32_32x32x16_bf16 v[32:47], v[136:139], v[132:135], v[32:47]
	ds_read_b128 v[132:135], v141 offset:46112
	s_waitcnt lgkmcnt(0)
	v_mfma_f32_32x32x16_bf16 v[80:95], v[128:131], v[132:135], v[80:95]
	v_mfma_f32_32x32x16_bf16 v[16:31], v[136:139], v[132:135], v[16:31]
	ds_read_b128 v[132:135], v141 offset:50720
	s_waitcnt lgkmcnt(0)
	v_mfma_f32_32x32x16_bf16 v[64:79], v[128:131], v[132:135], v[64:79]
	v_mfma_f32_32x32x16_bf16 v[0:15], v[136:139], v[132:135], v[0:15]
	ds_read_b128 v[128:131], v140 offset:64
	ds_read_b128 v[132:135], v141 offset:36928
	ds_read_b128 v[136:139], v140 offset:4672
	s_waitcnt lgkmcnt(1)
	v_mfma_f32_32x32x16_bf16 v[112:127], v[128:131], v[132:135], v[112:127]
	s_waitcnt lgkmcnt(0)
	v_mfma_f32_32x32x16_bf16 v[48:63], v[136:139], v[132:135], v[48:63]
	ds_read_b128 v[132:135], v141 offset:41536
	s_waitcnt lgkmcnt(0)
	v_mfma_f32_32x32x16_bf16 v[96:111], v[128:131], v[132:135], v[96:111]
	v_mfma_f32_32x32x16_bf16 v[32:47], v[136:139], v[132:135], v[32:47]
	ds_read_b128 v[132:135], v141 offset:46144
	s_waitcnt lgkmcnt(0)
	v_mfma_f32_32x32x16_bf16 v[80:95], v[128:131], v[132:135], v[80:95]
	v_mfma_f32_32x32x16_bf16 v[16:31], v[136:139], v[132:135], v[16:31]
	ds_read_b128 v[132:135], v141 offset:50752
	s_waitcnt lgkmcnt(0)
	v_mfma_f32_32x32x16_bf16 v[64:79], v[128:131], v[132:135], v[64:79]
	v_mfma_f32_32x32x16_bf16 v[0:15], v[136:139], v[132:135], v[0:15]
	ds_read_b128 v[128:131], v140 offset:96
	ds_read_b128 v[132:135], v141 offset:36960
	ds_read_b128 v[136:139], v140 offset:4704
	v_add3_u32 v140, s8, v178, v180
	s_mov_b64 s[8:9], -1
	s_waitcnt lgkmcnt(1)
	v_mfma_f32_32x32x16_bf16 v[112:127], v[128:131], v[132:135], v[112:127]
	s_waitcnt lgkmcnt(0)
	v_mfma_f32_32x32x16_bf16 v[48:63], v[136:139], v[132:135], v[48:63]
	ds_read_b128 v[132:135], v141 offset:41568
	s_waitcnt lgkmcnt(0)
	v_mfma_f32_32x32x16_bf16 v[96:111], v[128:131], v[132:135], v[96:111]
	v_mfma_f32_32x32x16_bf16 v[32:47], v[136:139], v[132:135], v[32:47]
	ds_read_b128 v[132:135], v141 offset:46176
	s_waitcnt lgkmcnt(0)
	v_mfma_f32_32x32x16_bf16 v[80:95], v[128:131], v[132:135], v[80:95]
	v_mfma_f32_32x32x16_bf16 v[16:31], v[136:139], v[132:135], v[16:31]
	ds_read_b128 v[132:135], v141 offset:50784
	s_waitcnt lgkmcnt(0)
	s_barrier
; #define MFMA(a, b, c) __builtin_amdgcn_mfma_f32_32x32x16_bf16((a), (b), (c), 0, 0, 0)
; DI u16 f2bf(float a) { return (u16)(pack2(a, 0.f) & 0xffffu); }
; DI int crow(int reg, int g) { return (reg & 3) + 8 * (reg >> 2) + 4 * g; }
; DI float siluf(float x) { return x * __builtin_amdgcn_rcpf(1.f + __expf(-x)); }
; template <bool AT>
; DI void gemm_main(f32x16 (&acc)[2][4], const u16* __restrict__ R, int ldr, const u16* __restrict__ Cm, int ldc,
;                   const u16* __restrict__ RT, int ldrt, int K, char* smem, int tid) {
;     ...
;       for (int ks = 0; ks < 4; ++ks) {
;         bf16x8 rf[2];
; #pragma unroll
;         for (int rb = 0; rb < 2; ++rb) {
;           if (AT && kt < 8) {
;             const u16* src = RTs + (16 * ks + 8 * g) * 264 + 64 * wr + 32 * rb + li;
;             bf16x8 t;
; #pragma unroll
;             for (int j = 0; j < 8; ++j) t[j] = (short)src[j * 264];
;             rf[rb] = t;
;           } else {
;             rf[rb] = *(const bf16x8*)(Rs + (64 * wr + 32 * rb + li) * 72 + 16 * ks + 8 * g);
;           }
;         }
; #pragma unroll
;         for (int cb = 0; cb < 4; ++cb) {
;           const bf16x8 cfv = *(const bf16x8*)(Cs + (128 * wc + 32 * cb + li) * 72 + 16 * ks + 8 * g);
; #pragma unroll
;           for (int rb = 0; rb < 2; ++rb) acc[rb][cb] = MFMA(rf[rb], cfv, acc[rb][cb]);
;         }
;       }
;     }
;     __syncthreads();
;   }
; template <bool TR>
; DI void gemm_in_tile(const P& p, int l, int id, char* smem) {
;     ...
;   } else {
; #pragma unroll
;     for (int rb = 0; rb < 2; ++rb) {
; #pragma unroll
;       for (int reg = 0; reg < 16; ++reg) {
;         if ((reg & 7) == 0) asm volatile("" ::: "memory");
;         const int rl = 64 * wr + 32 * rb + crow(reg, g);
;         const int tok = m0 + rl;
;         const float rs = rs_s[rl];
; #pragma unroll
;         for (int cb = 0; cb < 4; ++cb) {
;           const int col = n0 - 3584 + 128 * wc + 32 * cb + li;
;           p.AG[(size_t)tok * 512 + col] = f2bf(siluf(acc[rb][cb][reg] * rs));
	v_add3_u32 v141, s90, v178, v179
	v_mfma_f32_32x32x16_bf16 v[64:79], v[128:131], v[132:135], v[64:79]
	ds_read_b128 v[128:131], v140
	v_mfma_f32_32x32x16_bf16 v[0:15], v[136:139], v[132:135], v[0:15]
	ds_read_b128 v[136:139], v140 offset:4608
	ds_read_b128 v[132:135], v141
	s_waitcnt lgkmcnt(0)
	v_mfma_f32_32x32x16_bf16 v[112:127], v[128:131], v[132:135], v[112:127]
	v_mfma_f32_32x32x16_bf16 v[48:63], v[136:139], v[132:135], v[48:63]
	ds_read_b128 v[132:135], v141 offset:4608
	s_waitcnt lgkmcnt(0)
	v_mfma_f32_32x32x16_bf16 v[96:111], v[128:131], v[132:135], v[96:111]
	v_mfma_f32_32x32x16_bf16 v[32:47], v[136:139], v[132:135], v[32:47]
	ds_read_b128 v[132:135], v141 offset:9216
	s_waitcnt lgkmcnt(0)
	v_mfma_f32_32x32x16_bf16 v[80:95], v[128:131], v[132:135], v[80:95]
	v_mfma_f32_32x32x16_bf16 v[16:31], v[136:139], v[132:135], v[16:31]
	ds_read_b128 v[132:135], v141 offset:13824
	s_waitcnt lgkmcnt(0)
	v_mfma_f32_32x32x16_bf16 v[64:79], v[128:131], v[132:135], v[64:79]
	v_mfma_f32_32x32x16_bf16 v[0:15], v[136:139], v[132:135], v[0:15]
	ds_read_b128 v[128:131], v140 offset:32
	ds_read_b128 v[132:135], v141 offset:32
	ds_read_b128 v[136:139], v140 offset:4640
	s_waitcnt lgkmcnt(1)
	v_mfma_f32_32x32x16_bf16 v[112:127], v[128:131], v[132:135], v[112:127]
	s_waitcnt lgkmcnt(0)
	v_mfma_f32_32x32x16_bf16 v[48:63], v[136:139], v[132:135], v[48:63]
	ds_read_b128 v[132:135], v141 offset:4640
	s_waitcnt lgkmcnt(0)
	v_mfma_f32_32x32x16_bf16 v[96:111], v[128:131], v[132:135], v[96:111]
	v_mfma_f32_32x32x16_bf16 v[32:47], v[136:139], v[132:135], v[32:47]
	ds_read_b128 v[132:135], v141 offset:9248
	s_waitcnt lgkmcnt(0)
	v_mfma_f32_32x32x16_bf16 v[80:95], v[128:131], v[132:135], v[80:95]
	v_mfma_f32_32x32x16_bf16 v[16:31], v[136:139], v[132:135], v[16:31]
	ds_read_b128 v[132:135], v141 offset:13856
	s_waitcnt lgkmcnt(0)
	v_mfma_f32_32x32x16_bf16 v[64:79], v[128:131], v[132:135], v[64:79]
	v_mfma_f32_32x32x16_bf16 v[0:15], v[136:139], v[132:135], v[0:15]
	ds_read_b128 v[128:131], v140 offset:64
	ds_read_b128 v[132:135], v141 offset:64
	ds_read_b128 v[136:139], v140 offset:4672
	s_waitcnt lgkmcnt(1)
	v_mfma_f32_32x32x16_bf16 v[112:127], v[128:131], v[132:135], v[112:127]
	s_waitcnt lgkmcnt(0)
	v_mfma_f32_32x32x16_bf16 v[48:63], v[136:139], v[132:135], v[48:63]
	ds_read_b128 v[132:135], v141 offset:4672
	s_waitcnt lgkmcnt(0)
	v_mfma_f32_32x32x16_bf16 v[96:111], v[128:131], v[132:135], v[96:111]
	v_mfma_f32_32x32x16_bf16 v[32:47], v[136:139], v[132:135], v[32:47]
	ds_read_b128 v[132:135], v141 offset:9280
	s_waitcnt lgkmcnt(0)
	v_mfma_f32_32x32x16_bf16 v[80:95], v[128:131], v[132:135], v[80:95]
	v_mfma_f32_32x32x16_bf16 v[16:31], v[136:139], v[132:135], v[16:31]
	ds_read_b128 v[132:135], v141 offset:13888
	s_waitcnt lgkmcnt(0)
	v_mfma_f32_32x32x16_bf16 v[64:79], v[128:131], v[132:135], v[64:79]
	v_mfma_f32_32x32x16_bf16 v[0:15], v[136:139], v[132:135], v[0:15]
	ds_read_b128 v[128:131], v140 offset:96
	ds_read_b128 v[132:135], v141 offset:96
	ds_read_b128 v[136:139], v140 offset:4704
	v_ashrrev_i32_e32 v140, 7, v176
	s_waitcnt lgkmcnt(1)
	v_mfma_f32_32x32x16_bf16 v[112:127], v[128:131], v[132:135], v[112:127]
	s_waitcnt lgkmcnt(0)
	v_mfma_f32_32x32x16_bf16 v[48:63], v[136:139], v[132:135], v[48:63]
	ds_read_b128 v[132:135], v141 offset:4704
	s_waitcnt lgkmcnt(0)
	v_mfma_f32_32x32x16_bf16 v[96:111], v[128:131], v[132:135], v[96:111]
	v_mfma_f32_32x32x16_bf16 v[32:47], v[136:139], v[132:135], v[32:47]
	ds_read_b128 v[132:135], v141 offset:9312
	s_waitcnt lgkmcnt(0)
	v_mfma_f32_32x32x16_bf16 v[80:95], v[128:131], v[132:135], v[80:95]
	v_mfma_f32_32x32x16_bf16 v[16:31], v[136:139], v[132:135], v[16:31]
	ds_read_b128 v[132:135], v141 offset:13920
	v_bfe_u32 v141, v176, 5, 1
	s_waitcnt lgkmcnt(0)
	s_barrier
	v_mfma_f32_32x32x16_bf16 v[64:79], v[128:131], v[132:135], v[64:79]
	v_lshlrev_b32_e32 v128, 6, v140
	v_lshl_or_b32 v144, v141, 2, v128
	v_mfma_f32_32x32x16_bf16 v[0:15], v[136:139], v[132:135], v[0:15]
	s_cbranch_scc1 .LBB0_332
	s_add_i32 s8, s56, 0xfffff200
	v_lshlrev_b32_e32 v128, 7, v145
	v_or3_b32 v132, v128, s8, v177
	s_add_i32 s8, 0, 0x24000
	v_lshl_add_u32 v128, v144, 2, s8
	ds_read_b128 v[128:131], v128
	v_add_u32_e32 v140, s76, v144
	v_ashrrev_i32_e32 v141, 31, v140
	v_lshlrev_b64 v[134:135], 10, v[140:141]
	v_lshl_add_u64 v[142:143], s[30:31], 0, v[134:135]
	s_waitcnt lgkmcnt(0)
; DI u16 f2bf(float a) { return (u16)(pack2(a, 0.f) & 0xffffu); }
; DI int crow(int reg, int g) { return (reg & 3) + 8 * (reg >> 2) + 4 * g; }
; DI float siluf(float x) { return x * __builtin_amdgcn_rcpf(1.f + __expf(-x)); }
; template <bool TR>
; DI void gemm_in_tile(const P& p, int l, int id, char* smem) {
;     ...
; #pragma unroll
;     for (int rb = 0; rb < 2; ++rb) {
; #pragma unroll
;       for (int reg = 0; reg < 16; ++reg) {
;         if ((reg & 7) == 0) asm volatile("" ::: "memory");
;         const int rl = 64 * wr + 32 * rb + crow(reg, g);
;         const int tok = m0 + rl;
;         const float rs = rs_s[rl];
; #pragma unroll
;         for (int cb = 0; cb < 4; ++cb) {
;           const int col = n0 - 3584 + 128 * wc + 32 * cb + li;
;           p.AG[(size_t)tok * 512 + col] = f2bf(siluf(acc[rb][cb][reg] * rs));
	v_mul_f32_e32 v133, v112, v128
	v_mul_f32_e32 v134, 0xbfb8aa3b, v133
	v_exp_f32_e32 v134, v134
	s_nop 0
	v_add_f32_e32 v134, 1.0, v134
	v_rcp_f32_e32 v134, v134
	s_nop 0
	v_mul_f32_e32 v133, v133, v134
	v_cvt_pk_bf16_f32 v136, v133, s0
	v_ashrrev_i32_e32 v133, 31, v132
	v_lshlrev_b64 v[138:139], 1, v[132:133]
	v_lshl_add_u64 v[134:135], v[142:143], 0, v[138:139]
	v_mul_f32_e32 v133, v96, v128
	global_store_short v[134:135], v136, off
	v_mul_f32_e32 v135, 0xbfb8aa3b, v133
	v_exp_f32_e32 v135, v135
	v_or_b32_e32 v134, 32, v132
	v_add_f32_e32 v135, 1.0, v135
	v_rcp_f32_e32 v135, v135
	s_nop 0
	v_mul_f32_e32 v133, v133, v135
	v_ashrrev_i32_e32 v135, 31, v134
	v_lshlrev_b64 v[136:137], 1, v[134:135]
	v_cvt_pk_bf16_f32 v133, v133, s0
	v_lshl_add_u64 v[134:135], v[142:143], 0, v[136:137]
	global_store_short v[134:135], v133, off
	v_mul_f32_e32 v133, v80, v128
	v_mul_f32_e32 v135, 0xbfb8aa3b, v133
	v_exp_f32_e32 v135, v135
	v_or_b32_e32 v134, 64, v132
	v_mul_f32_e32 v128, v64, v128
	v_or_b32_e32 v132, 0x60, v132
	v_add_f32_e32 v135, 1.0, v135
	v_rcp_f32_e32 v135, v135
	s_nop 0
	v_mul_f32_e32 v133, v133, v135
	v_ashrrev_i32_e32 v135, 31, v134
	v_lshlrev_b64 v[134:135], 1, v[134:135]
	v_cvt_pk_bf16_f32 v133, v133, s0
	v_lshl_add_u64 v[146:147], v[142:143], 0, v[134:135]
	global_store_short v[146:147], v133, off
	v_mul_f32_e32 v133, 0xbfb8aa3b, v128
	v_exp_f32_e32 v133, v133
	s_nop 0
	v_add_f32_e32 v133, 1.0, v133
	v_rcp_f32_e32 v133, v133
	s_nop 0
	v_mul_f32_e32 v128, v128, v133
	v_ashrrev_i32_e32 v133, 31, v132
	v_lshlrev_b64 v[132:133], 1, v[132:133]
	v_cvt_pk_bf16_f32 v128, v128, s0
	v_lshl_add_u64 v[142:143], v[142:143], 0, v[132:133]
	global_store_short v[142:143], v128, off
	v_mul_f32_e32 v128, v113, v129
	v_mul_f32_e32 v141, 0xbfb8aa3b, v128
	v_exp_f32_e32 v141, v141
	v_add_u32_e32 v142, 1, v140
	v_ashrrev_i32_e32 v143, 31, v142
	v_lshlrev_b64 v[142:143], 10, v[142:143]
	v_add_f32_e32 v141, 1.0, v141
	v_rcp_f32_e32 v141, v141
	v_lshl_add_u64 v[142:143], s[30:31], 0, v[142:143]
	v_lshl_add_u64 v[146:147], v[142:143], 0, v[138:139]
	v_mul_f32_e32 v128, v128, v141
	v_cvt_pk_bf16_f32 v128, v128, s0
	global_store_short v[146:147], v128, off
	v_mul_f32_e32 v128, v97, v129
	v_mul_f32_e32 v141, 0xbfb8aa3b, v128
	v_exp_f32_e32 v141, v141
	v_lshl_add_u64 v[146:147], v[142:143], 0, v[136:137]
	v_add_f32_e32 v141, 1.0, v141
	v_rcp_f32_e32 v141, v141
	s_nop 0
	v_mul_f32_e32 v128, v128, v141
	v_cvt_pk_bf16_f32 v128, v128, s0
	global_store_short v[146:147], v128, off
	v_mul_f32_e32 v128, v81, v129
	v_mul_f32_e32 v141, 0xbfb8aa3b, v128
	v_exp_f32_e32 v141, v141
	v_lshl_add_u64 v[146:147], v[142:143], 0, v[134:135]
	v_add_f32_e32 v141, 1.0, v141
	v_rcp_f32_e32 v141, v141
	s_nop 0
	v_mul_f32_e32 v128, v128, v141
	v_cvt_pk_bf16_f32 v128, v128, s0
	global_store_short v[146:147], v128, off
	v_mul_f32_e32 v128, v65, v129
	v_mul_f32_e32 v129, 0xbfb8aa3b, v128
	v_exp_f32_e32 v129, v129
	s_nop 0
	v_add_f32_e32 v129, 1.0, v129
	v_rcp_f32_e32 v129, v129
	s_nop 0
	v_mul_f32_e32 v128, v128, v129
	v_cvt_pk_bf16_f32 v141, v128, s0
	v_lshl_add_u64 v[128:129], v[142:143], 0, v[132:133]
	global_store_short v[128:129], v141, off
	v_mul_f32_e32 v141, v114, v130
	v_mul_f32_e32 v142, 0xbfb8aa3b, v141
	v_exp_f32_e32 v142, v142
	v_add_u32_e32 v128, 2, v140
	v_ashrrev_i32_e32 v129, 31, v128
	v_lshlrev_b64 v[128:129], 10, v[128:129]
	v_add_f32_e32 v142, 1.0, v142
	v_rcp_f32_e32 v142, v142
	v_lshl_add_u64 v[128:129], s[30:31], 0, v[128:129]
	v_mul_f32_e32 v141, v141, v142
	v_cvt_pk_bf16_f32 v141, v141, s0
	v_lshl_add_u64 v[142:143], v[128:129], 0, v[138:139]
	global_store_short v[142:143], v141, off
	v_mul_f32_e32 v141, v98, v130
	v_mul_f32_e32 v142, 0xbfb8aa3b, v141
	v_exp_f32_e32 v142, v142
	s_nop 0
	v_add_f32_e32 v142, 1.0, v142
	v_rcp_f32_e32 v142, v142
	s_nop 0
	v_mul_f32_e32 v141, v141, v142
	v_cvt_pk_bf16_f32 v141, v141, s0
	v_lshl_add_u64 v[142:143], v[128:129], 0, v[136:137]
	global_store_short v[142:143], v141, off
	v_mul_f32_e32 v141, v82, v130
	v_mul_f32_e32 v142, 0xbfb8aa3b, v141
	v_exp_f32_e32 v142, v142
	v_mul_f32_e32 v130, v66, v130
	v_add_f32_e32 v142, 1.0, v142
	v_rcp_f32_e32 v142, v142
	s_nop 0
	v_mul_f32_e32 v141, v141, v142
	v_cvt_pk_bf16_f32 v141, v141, s0
	v_lshl_add_u64 v[142:143], v[128:129], 0, v[134:135]
	global_store_short v[142:143], v141, off
	v_mul_f32_e32 v141, 0xbfb8aa3b, v130
	v_exp_f32_e32 v141, v141
	v_lshl_add_u64 v[128:129], v[128:129], 0, v[132:133]
	v_add_f32_e32 v141, 1.0, v141
	v_rcp_f32_e32 v141, v141
	s_nop 0
	v_mul_f32_e32 v130, v130, v141
	v_cvt_pk_bf16_f32 v130, v130, s0
	global_store_short v[128:129], v130, off
	v_mul_f32_e32 v130, v115, v131
	v_mul_f32_e32 v141, 0xbfb8aa3b, v130
	v_exp_f32_e32 v141, v141
	v_add_u32_e32 v128, 3, v140
	v_ashrrev_i32_e32 v129, 31, v128
	v_lshlrev_b64 v[128:129], 10, v[128:129]
	v_add_f32_e32 v141, 1.0, v141
	v_rcp_f32_e32 v141, v141
	v_lshl_add_u64 v[128:129], s[30:31], 0, v[128:129]
	v_lshl_add_u64 v[142:143], v[128:129], 0, v[138:139]
	v_mul_f32_e32 v130, v130, v141
	v_cvt_pk_bf16_f32 v130, v130, s0
	global_store_short v[142:143], v130, off
	v_mul_f32_e32 v130, v99, v131
	v_mul_f32_e32 v141, 0xbfb8aa3b, v130
	v_exp_f32_e32 v141, v141
	v_lshl_add_u64 v[142:143], v[128:129], 0, v[136:137]
	v_add_f32_e32 v141, 1.0, v141
	v_rcp_f32_e32 v141, v141
	s_nop 0
	v_mul_f32_e32 v130, v130, v141
	v_cvt_pk_bf16_f32 v130, v130, s0
	global_store_short v[142:143], v130, off
	v_mul_f32_e32 v130, v83, v131
	v_mul_f32_e32 v141, 0xbfb8aa3b, v130
	v_exp_f32_e32 v141, v141
	v_lshl_add_u64 v[142:143], v[128:129], 0, v[134:135]
	v_lshl_add_u64 v[128:129], v[128:129], 0, v[132:133]
	v_add_f32_e32 v141, 1.0, v141
	v_rcp_f32_e32 v141, v141
	s_nop 0
	v_mul_f32_e32 v130, v130, v141
	v_cvt_pk_bf16_f32 v130, v130, s0
	global_store_short v[142:143], v130, off
	v_mul_f32_e32 v130, v67, v131
	v_mul_f32_e32 v131, 0xbfb8aa3b, v130
	v_exp_f32_e32 v131, v131
	s_nop 0
	v_add_f32_e32 v131, 1.0, v131
	v_rcp_f32_e32 v131, v131
	s_nop 0
	v_mul_f32_e32 v130, v130, v131
	v_cvt_pk_bf16_f32 v130, v130, s0
	global_store_short v[128:129], v130, off
	v_or_b32_e32 v128, 8, v144
	v_add_u32_e32 v142, s76, v128
	v_lshl_add_u32 v128, v128, 2, s8
	ds_read_b128 v[128:131], v128
	v_ashrrev_i32_e32 v143, 31, v142
	v_lshlrev_b64 v[142:143], 10, v[142:143]
	v_lshl_add_u64 v[142:143], s[30:31], 0, v[142:143]
	s_waitcnt lgkmcnt(0)
; DI u16 f2bf(float a) { return (u16)(pack2(a, 0.f) & 0xffffu); }
; DI int crow(int reg, int g) { return (reg & 3) + 8 * (reg >> 2) + 4 * g; }
; DI float siluf(float x) { return x * __builtin_amdgcn_rcpf(1.f + __expf(-x)); }
; template <bool TR>
; DI void gemm_in_tile(const P& p, int l, int id, char* smem) {
;     ...
; #pragma unroll
;     for (int rb = 0; rb < 2; ++rb) {
; #pragma unroll
;       for (int reg = 0; reg < 16; ++reg) {
;         if ((reg & 7) == 0) asm volatile("" ::: "memory");
;         const int rl = 64 * wr + 32 * rb + crow(reg, g);
;         const int tok = m0 + rl;
;         const float rs = rs_s[rl];
; #pragma unroll
;         for (int cb = 0; cb < 4; ++cb) {
;           const int col = n0 - 3584 + 128 * wc + 32 * cb + li;
;           p.AG[(size_t)tok * 512 + col] = f2bf(siluf(acc[rb][cb][reg] * rs));
	v_mul_f32_e32 v141, v116, v128
	v_mul_f32_e32 v146, 0xbfb8aa3b, v141
	v_exp_f32_e32 v146, v146
	s_nop 0
	v_add_f32_e32 v146, 1.0, v146
	v_rcp_f32_e32 v146, v146
	s_nop 0
	v_mul_f32_e32 v141, v141, v146
	v_cvt_pk_bf16_f32 v141, v141, s0
	v_lshl_add_u64 v[146:147], v[142:143], 0, v[138:139]
	global_store_short v[146:147], v141, off
	v_mul_f32_e32 v141, v100, v128
	v_mul_f32_e32 v146, 0xbfb8aa3b, v141
	v_exp_f32_e32 v146, v146
	s_nop 0
	v_add_f32_e32 v146, 1.0, v146
	v_rcp_f32_e32 v146, v146
	s_nop 0
	v_mul_f32_e32 v141, v141, v146
	v_cvt_pk_bf16_f32 v141, v141, s0
	v_lshl_add_u64 v[146:147], v[142:143], 0, v[136:137]
	global_store_short v[146:147], v141, off
	v_mul_f32_e32 v141, v84, v128
	v_mul_f32_e32 v146, 0xbfb8aa3b, v141
	v_exp_f32_e32 v146, v146
	v_mul_f32_e32 v128, v68, v128
	v_add_f32_e32 v146, 1.0, v146
	v_rcp_f32_e32 v146, v146
	s_nop 0
	v_mul_f32_e32 v141, v141, v146
	v_cvt_pk_bf16_f32 v141, v141, s0
	v_lshl_add_u64 v[146:147], v[142:143], 0, v[134:135]
	global_store_short v[146:147], v141, off
	v_mul_f32_e32 v141, 0xbfb8aa3b, v128
	v_exp_f32_e32 v141, v141
	v_lshl_add_u64 v[142:143], v[142:143], 0, v[132:133]
	v_add_f32_e32 v141, 1.0, v141
	v_rcp_f32_e32 v141, v141
	s_nop 0
	v_mul_f32_e32 v128, v128, v141
	v_cvt_pk_bf16_f32 v128, v128, s0
	global_store_short v[142:143], v128, off
	v_mul_f32_e32 v128, v117, v129
	v_mul_f32_e32 v141, 0xbfb8aa3b, v128
	v_exp_f32_e32 v141, v141
	v_add_u32_e32 v142, 9, v140
	v_ashrrev_i32_e32 v143, 31, v142
	v_lshlrev_b64 v[142:143], 10, v[142:143]
	v_add_f32_e32 v141, 1.0, v141
	v_rcp_f32_e32 v141, v141
	v_lshl_add_u64 v[142:143], s[30:31], 0, v[142:143]
	v_lshl_add_u64 v[146:147], v[142:143], 0, v[138:139]
	v_mul_f32_e32 v128, v128, v141
	v_cvt_pk_bf16_f32 v128, v128, s0
	global_store_short v[146:147], v128, off
	v_mul_f32_e32 v128, v101, v129
	v_mul_f32_e32 v141, 0xbfb8aa3b, v128
	v_exp_f32_e32 v141, v141
	v_lshl_add_u64 v[146:147], v[142:143], 0, v[136:137]
	v_add_f32_e32 v141, 1.0, v141
	v_rcp_f32_e32 v141, v141
	s_nop 0
	v_mul_f32_e32 v128, v128, v141
	v_cvt_pk_bf16_f32 v128, v128, s0
	global_store_short v[146:147], v128, off
	v_mul_f32_e32 v128, v85, v129
	v_mul_f32_e32 v141, 0xbfb8aa3b, v128
	v_exp_f32_e32 v141, v141
	v_lshl_add_u64 v[146:147], v[142:143], 0, v[134:135]
	v_add_f32_e32 v141, 1.0, v141
	v_rcp_f32_e32 v141, v141
	s_nop 0
	v_mul_f32_e32 v128, v128, v141
	v_cvt_pk_bf16_f32 v128, v128, s0
	global_store_short v[146:147], v128, off
	v_mul_f32_e32 v128, v69, v129
	v_mul_f32_e32 v129, 0xbfb8aa3b, v128
	v_exp_f32_e32 v129, v129
	s_nop 0
	v_add_f32_e32 v129, 1.0, v129
	v_rcp_f32_e32 v129, v129
	s_nop 0
	v_mul_f32_e32 v128, v128, v129
	v_cvt_pk_bf16_f32 v141, v128, s0
	v_lshl_add_u64 v[128:129], v[142:143], 0, v[132:133]
	global_store_short v[128:129], v141, off
	v_mul_f32_e32 v141, v118, v130
	v_mul_f32_e32 v142, 0xbfb8aa3b, v141
	v_exp_f32_e32 v142, v142
	v_add_u32_e32 v128, 10, v140
	v_ashrrev_i32_e32 v129, 31, v128
	v_lshlrev_b64 v[128:129], 10, v[128:129]
	v_add_f32_e32 v142, 1.0, v142
	v_rcp_f32_e32 v142, v142
	v_lshl_add_u64 v[128:129], s[30:31], 0, v[128:129]
	v_mul_f32_e32 v141, v141, v142
	v_cvt_pk_bf16_f32 v141, v141, s0
	v_lshl_add_u64 v[142:143], v[128:129], 0, v[138:139]
	global_store_short v[142:143], v141, off
	v_mul_f32_e32 v141, v102, v130
	v_mul_f32_e32 v142, 0xbfb8aa3b, v141
	v_exp_f32_e32 v142, v142
	s_nop 0
	v_add_f32_e32 v142, 1.0, v142
	v_rcp_f32_e32 v142, v142
	s_nop 0
	v_mul_f32_e32 v141, v141, v142
	v_cvt_pk_bf16_f32 v141, v141, s0
	v_lshl_add_u64 v[142:143], v[128:129], 0, v[136:137]
	global_store_short v[142:143], v141, off
	v_mul_f32_e32 v141, v86, v130
	v_mul_f32_e32 v142, 0xbfb8aa3b, v141
	v_exp_f32_e32 v142, v142
	v_mul_f32_e32 v130, v70, v130
	v_add_f32_e32 v142, 1.0, v142
	v_rcp_f32_e32 v142, v142
	s_nop 0
	v_mul_f32_e32 v141, v141, v142
	v_cvt_pk_bf16_f32 v141, v141, s0
	v_lshl_add_u64 v[142:143], v[128:129], 0, v[134:135]
	global_store_short v[142:143], v141, off
	v_mul_f32_e32 v141, 0xbfb8aa3b, v130
	v_exp_f32_e32 v141, v141
	v_lshl_add_u64 v[128:129], v[128:129], 0, v[132:133]
	v_add_f32_e32 v141, 1.0, v141
	v_rcp_f32_e32 v141, v141
	s_nop 0
	v_mul_f32_e32 v130, v130, v141
	v_cvt_pk_bf16_f32 v130, v130, s0
	global_store_short v[128:129], v130, off
	v_mul_f32_e32 v130, v119, v131
	v_mul_f32_e32 v141, 0xbfb8aa3b, v130
	v_exp_f32_e32 v141, v141
	v_add_u32_e32 v128, 11, v140
	v_ashrrev_i32_e32 v129, 31, v128
	v_lshlrev_b64 v[128:129], 10, v[128:129]
	v_add_f32_e32 v141, 1.0, v141
	v_rcp_f32_e32 v141, v141
	v_lshl_add_u64 v[128:129], s[30:31], 0, v[128:129]
	v_lshl_add_u64 v[142:143], v[128:129], 0, v[138:139]
	v_mul_f32_e32 v130, v130, v141
	v_cvt_pk_bf16_f32 v130, v130, s0
	global_store_short v[142:143], v130, off
	v_mul_f32_e32 v130, v103, v131
	v_mul_f32_e32 v141, 0xbfb8aa3b, v130
	v_exp_f32_e32 v141, v141
	v_lshl_add_u64 v[142:143], v[128:129], 0, v[136:137]
	v_add_f32_e32 v141, 1.0, v141
	v_rcp_f32_e32 v141, v141
	s_nop 0
	v_mul_f32_e32 v130, v130, v141
	v_cvt_pk_bf16_f32 v130, v130, s0
	global_store_short v[142:143], v130, off
	v_mul_f32_e32 v130, v87, v131
	v_mul_f32_e32 v141, 0xbfb8aa3b, v130
	v_exp_f32_e32 v141, v141
	v_lshl_add_u64 v[142:143], v[128:129], 0, v[134:135]
	v_lshl_add_u64 v[128:129], v[128:129], 0, v[132:133]
	v_add_f32_e32 v141, 1.0, v141
	v_rcp_f32_e32 v141, v141
	s_nop 0
	v_mul_f32_e32 v130, v130, v141
	v_cvt_pk_bf16_f32 v130, v130, s0
	global_store_short v[142:143], v130, off
	v_mul_f32_e32 v130, v71, v131
	v_mul_f32_e32 v131, 0xbfb8aa3b, v130
	v_exp_f32_e32 v131, v131
	s_nop 0
	v_add_f32_e32 v131, 1.0, v131
	v_rcp_f32_e32 v131, v131
	s_nop 0
	v_mul_f32_e32 v130, v130, v131
	v_cvt_pk_bf16_f32 v130, v130, s0
	global_store_short v[128:129], v130, off
	v_or_b32_e32 v128, 16, v144
	v_add_u32_e32 v142, s76, v128
	v_lshl_add_u32 v128, v128, 2, s8
	ds_read_b128 v[128:131], v128
	v_ashrrev_i32_e32 v143, 31, v142
	v_lshlrev_b64 v[142:143], 10, v[142:143]
	v_lshl_add_u64 v[142:143], s[30:31], 0, v[142:143]
	s_waitcnt lgkmcnt(0)
; DI u16 f2bf(float a) { return (u16)(pack2(a, 0.f) & 0xffffu); }
; DI int crow(int reg, int g) { return (reg & 3) + 8 * (reg >> 2) + 4 * g; }
; DI float siluf(float x) { return x * __builtin_amdgcn_rcpf(1.f + __expf(-x)); }
; template <bool TR>
; DI void gemm_in_tile(const P& p, int l, int id, char* smem) {
;     ...
; #pragma unroll
;     for (int rb = 0; rb < 2; ++rb) {
; #pragma unroll
;       for (int reg = 0; reg < 16; ++reg) {
;         if ((reg & 7) == 0) asm volatile("" ::: "memory");
;         const int rl = 64 * wr + 32 * rb + crow(reg, g);
;         const int tok = m0 + rl;
;         const float rs = rs_s[rl];
; #pragma unroll
;         for (int cb = 0; cb < 4; ++cb) {
;           const int col = n0 - 3584 + 128 * wc + 32 * cb + li;
;           p.AG[(size_t)tok * 512 + col] = f2bf(siluf(acc[rb][cb][reg] * rs));
	v_mul_f32_e32 v141, v120, v128
	v_mul_f32_e32 v146, 0xbfb8aa3b, v141
	v_exp_f32_e32 v146, v146
	s_nop 0
	v_add_f32_e32 v146, 1.0, v146
	v_rcp_f32_e32 v146, v146
	s_nop 0
	v_mul_f32_e32 v141, v141, v146
	v_cvt_pk_bf16_f32 v141, v141, s0
	v_lshl_add_u64 v[146:147], v[142:143], 0, v[138:139]
	global_store_short v[146:147], v141, off
	v_mul_f32_e32 v141, v104, v128
	v_mul_f32_e32 v146, 0xbfb8aa3b, v141
	v_exp_f32_e32 v146, v146
	s_nop 0
	v_add_f32_e32 v146, 1.0, v146
	v_rcp_f32_e32 v146, v146
	s_nop 0
	v_mul_f32_e32 v141, v141, v146
	v_cvt_pk_bf16_f32 v141, v141, s0
	v_lshl_add_u64 v[146:147], v[142:143], 0, v[136:137]
	global_store_short v[146:147], v141, off
	v_mul_f32_e32 v141, v88, v128
	v_mul_f32_e32 v146, 0xbfb8aa3b, v141
	v_exp_f32_e32 v146, v146
	v_mul_f32_e32 v128, v72, v128
	v_add_f32_e32 v146, 1.0, v146
	v_rcp_f32_e32 v146, v146
	s_nop 0
	v_mul_f32_e32 v141, v141, v146
	v_cvt_pk_bf16_f32 v141, v141, s0
	v_lshl_add_u64 v[146:147], v[142:143], 0, v[134:135]
	global_store_short v[146:147], v141, off
	v_mul_f32_e32 v141, 0xbfb8aa3b, v128
	v_exp_f32_e32 v141, v141
	v_lshl_add_u64 v[142:143], v[142:143], 0, v[132:133]
	v_add_f32_e32 v141, 1.0, v141
	v_rcp_f32_e32 v141, v141
	s_nop 0
	v_mul_f32_e32 v128, v128, v141
	v_cvt_pk_bf16_f32 v128, v128, s0
	global_store_short v[142:143], v128, off
	v_mul_f32_e32 v128, v121, v129
	v_mul_f32_e32 v141, 0xbfb8aa3b, v128
	v_exp_f32_e32 v141, v141
	v_add_u32_e32 v142, 17, v140
	v_ashrrev_i32_e32 v143, 31, v142
	v_lshlrev_b64 v[142:143], 10, v[142:143]
	v_add_f32_e32 v141, 1.0, v141
	v_rcp_f32_e32 v141, v141
	v_lshl_add_u64 v[142:143], s[30:31], 0, v[142:143]
	v_lshl_add_u64 v[146:147], v[142:143], 0, v[138:139]
	v_mul_f32_e32 v128, v128, v141
	v_cvt_pk_bf16_f32 v128, v128, s0
	global_store_short v[146:147], v128, off
	v_mul_f32_e32 v128, v105, v129
	v_mul_f32_e32 v141, 0xbfb8aa3b, v128
	v_exp_f32_e32 v141, v141
	v_lshl_add_u64 v[146:147], v[142:143], 0, v[136:137]
	v_add_f32_e32 v141, 1.0, v141
	v_rcp_f32_e32 v141, v141
	s_nop 0
	v_mul_f32_e32 v128, v128, v141
	v_cvt_pk_bf16_f32 v128, v128, s0
	global_store_short v[146:147], v128, off
	v_mul_f32_e32 v128, v89, v129
	v_mul_f32_e32 v141, 0xbfb8aa3b, v128
	v_exp_f32_e32 v141, v141
	v_lshl_add_u64 v[146:147], v[142:143], 0, v[134:135]
	v_add_f32_e32 v141, 1.0, v141
	v_rcp_f32_e32 v141, v141
	s_nop 0
	v_mul_f32_e32 v128, v128, v141
	v_cvt_pk_bf16_f32 v128, v128, s0
	global_store_short v[146:147], v128, off
	v_mul_f32_e32 v128, v73, v129
	v_mul_f32_e32 v129, 0xbfb8aa3b, v128
	v_exp_f32_e32 v129, v129
	s_nop 0
	v_add_f32_e32 v129, 1.0, v129
	v_rcp_f32_e32 v129, v129
	s_nop 0
	v_mul_f32_e32 v128, v128, v129
	v_cvt_pk_bf16_f32 v141, v128, s0
	v_lshl_add_u64 v[128:129], v[142:143], 0, v[132:133]
	global_store_short v[128:129], v141, off
	v_mul_f32_e32 v141, v122, v130
	v_mul_f32_e32 v142, 0xbfb8aa3b, v141
	v_exp_f32_e32 v142, v142
	v_add_u32_e32 v128, 18, v140
	v_ashrrev_i32_e32 v129, 31, v128
	v_lshlrev_b64 v[128:129], 10, v[128:129]
	v_add_f32_e32 v142, 1.0, v142
	v_rcp_f32_e32 v142, v142
	v_lshl_add_u64 v[128:129], s[30:31], 0, v[128:129]
	v_mul_f32_e32 v141, v141, v142
	v_cvt_pk_bf16_f32 v141, v141, s0
	v_lshl_add_u64 v[142:143], v[128:129], 0, v[138:139]
	global_store_short v[142:143], v141, off
	v_mul_f32_e32 v141, v106, v130
	v_mul_f32_e32 v142, 0xbfb8aa3b, v141
	v_exp_f32_e32 v142, v142
	s_nop 0
	v_add_f32_e32 v142, 1.0, v142
	v_rcp_f32_e32 v142, v142
	s_nop 0
	v_mul_f32_e32 v141, v141, v142
	v_cvt_pk_bf16_f32 v141, v141, s0
	v_lshl_add_u64 v[142:143], v[128:129], 0, v[136:137]
	global_store_short v[142:143], v141, off
	v_mul_f32_e32 v141, v90, v130
	v_mul_f32_e32 v142, 0xbfb8aa3b, v141
	v_exp_f32_e32 v142, v142
	v_mul_f32_e32 v130, v74, v130
	v_add_f32_e32 v142, 1.0, v142
	v_rcp_f32_e32 v142, v142
	s_nop 0
	v_mul_f32_e32 v141, v141, v142
	v_cvt_pk_bf16_f32 v141, v141, s0
	v_lshl_add_u64 v[142:143], v[128:129], 0, v[134:135]
	global_store_short v[142:143], v141, off
	v_mul_f32_e32 v141, 0xbfb8aa3b, v130
	v_exp_f32_e32 v141, v141
	v_lshl_add_u64 v[128:129], v[128:129], 0, v[132:133]
	v_add_f32_e32 v141, 1.0, v141
	v_rcp_f32_e32 v141, v141
	s_nop 0
	v_mul_f32_e32 v130, v130, v141
	v_cvt_pk_bf16_f32 v130, v130, s0
	global_store_short v[128:129], v130, off
	v_mul_f32_e32 v130, v123, v131
	v_mul_f32_e32 v141, 0xbfb8aa3b, v130
	v_exp_f32_e32 v141, v141
	v_add_u32_e32 v128, 19, v140
	v_ashrrev_i32_e32 v129, 31, v128
	v_lshlrev_b64 v[128:129], 10, v[128:129]
	v_add_f32_e32 v141, 1.0, v141
	v_rcp_f32_e32 v141, v141
	v_lshl_add_u64 v[128:129], s[30:31], 0, v[128:129]
	v_lshl_add_u64 v[142:143], v[128:129], 0, v[138:139]
	v_mul_f32_e32 v130, v130, v141
	v_cvt_pk_bf16_f32 v130, v130, s0
	global_store_short v[142:143], v130, off
	v_mul_f32_e32 v130, v107, v131
	v_mul_f32_e32 v141, 0xbfb8aa3b, v130
	v_exp_f32_e32 v141, v141
	v_lshl_add_u64 v[142:143], v[128:129], 0, v[136:137]
	v_add_f32_e32 v141, 1.0, v141
	v_rcp_f32_e32 v141, v141
	s_nop 0
	v_mul_f32_e32 v130, v130, v141
	v_cvt_pk_bf16_f32 v130, v130, s0
	global_store_short v[142:143], v130, off
	v_mul_f32_e32 v130, v91, v131
	v_mul_f32_e32 v141, 0xbfb8aa3b, v130
	v_exp_f32_e32 v141, v141
	v_lshl_add_u64 v[142:143], v[128:129], 0, v[134:135]
	v_lshl_add_u64 v[128:129], v[128:129], 0, v[132:133]
	v_add_f32_e32 v141, 1.0, v141
	v_rcp_f32_e32 v141, v141
	s_nop 0
	v_mul_f32_e32 v130, v130, v141
	v_cvt_pk_bf16_f32 v130, v130, s0
	global_store_short v[142:143], v130, off
	v_mul_f32_e32 v130, v75, v131
	v_mul_f32_e32 v131, 0xbfb8aa3b, v130
	v_exp_f32_e32 v131, v131
	s_nop 0
	v_add_f32_e32 v131, 1.0, v131
	v_rcp_f32_e32 v131, v131
	s_nop 0
	v_mul_f32_e32 v130, v130, v131
	v_cvt_pk_bf16_f32 v130, v130, s0
	global_store_short v[128:129], v130, off
	v_or_b32_e32 v128, 24, v144
	v_add_u32_e32 v142, s76, v128
	v_lshl_add_u32 v128, v128, 2, s8
	ds_read_b128 v[128:131], v128
	v_ashrrev_i32_e32 v143, 31, v142
	v_lshlrev_b64 v[142:143], 10, v[142:143]
	v_lshl_add_u64 v[142:143], s[30:31], 0, v[142:143]
	s_waitcnt lgkmcnt(0)
; DI u16 f2bf(float a) { return (u16)(pack2(a, 0.f) & 0xffffu); }
; DI int crow(int reg, int g) { return (reg & 3) + 8 * (reg >> 2) + 4 * g; }
; DI float siluf(float x) { return x * __builtin_amdgcn_rcpf(1.f + __expf(-x)); }
; template <bool TR>
; DI void gemm_in_tile(const P& p, int l, int id, char* smem) {
;     ...
; #pragma unroll
;     for (int rb = 0; rb < 2; ++rb) {
; #pragma unroll
;       for (int reg = 0; reg < 16; ++reg) {
;         if ((reg & 7) == 0) asm volatile("" ::: "memory");
;         const int rl = 64 * wr + 32 * rb + crow(reg, g);
;         const int tok = m0 + rl;
;         const float rs = rs_s[rl];
; #pragma unroll
;         for (int cb = 0; cb < 4; ++cb) {
;           const int col = n0 - 3584 + 128 * wc + 32 * cb + li;
;           p.AG[(size_t)tok * 512 + col] = f2bf(siluf(acc[rb][cb][reg] * rs));
	v_mul_f32_e32 v141, v124, v128
	v_mul_f32_e32 v146, 0xbfb8aa3b, v141
	v_exp_f32_e32 v146, v146
	s_nop 0
	v_add_f32_e32 v146, 1.0, v146
	v_rcp_f32_e32 v146, v146
	s_nop 0
	v_mul_f32_e32 v141, v141, v146
	v_cvt_pk_bf16_f32 v141, v141, s0
	v_lshl_add_u64 v[146:147], v[142:143], 0, v[138:139]
	global_store_short v[146:147], v141, off
	v_mul_f32_e32 v141, v108, v128
	v_mul_f32_e32 v146, 0xbfb8aa3b, v141
	v_exp_f32_e32 v146, v146
	s_nop 0
	v_add_f32_e32 v146, 1.0, v146
	v_rcp_f32_e32 v146, v146
	s_nop 0
	v_mul_f32_e32 v141, v141, v146
	v_cvt_pk_bf16_f32 v141, v141, s0
	v_lshl_add_u64 v[146:147], v[142:143], 0, v[136:137]
	global_store_short v[146:147], v141, off
	v_mul_f32_e32 v141, v92, v128
	v_mul_f32_e32 v146, 0xbfb8aa3b, v141
	v_exp_f32_e32 v146, v146
	v_mul_f32_e32 v128, v76, v128
	v_add_f32_e32 v146, 1.0, v146
	v_rcp_f32_e32 v146, v146
	s_nop 0
	v_mul_f32_e32 v141, v141, v146
	v_cvt_pk_bf16_f32 v141, v141, s0
	v_lshl_add_u64 v[146:147], v[142:143], 0, v[134:135]
	global_store_short v[146:147], v141, off
	v_mul_f32_e32 v141, 0xbfb8aa3b, v128
	v_exp_f32_e32 v141, v141
	v_lshl_add_u64 v[142:143], v[142:143], 0, v[132:133]
	v_add_f32_e32 v141, 1.0, v141
	v_rcp_f32_e32 v141, v141
	s_nop 0
	v_mul_f32_e32 v128, v128, v141
	v_cvt_pk_bf16_f32 v128, v128, s0
	global_store_short v[142:143], v128, off
	v_mul_f32_e32 v128, v125, v129
	v_mul_f32_e32 v141, 0xbfb8aa3b, v128
	v_exp_f32_e32 v141, v141
	v_add_u32_e32 v142, 25, v140
	v_ashrrev_i32_e32 v143, 31, v142
	v_lshlrev_b64 v[142:143], 10, v[142:143]
	v_add_f32_e32 v141, 1.0, v141
	v_rcp_f32_e32 v141, v141
	v_lshl_add_u64 v[142:143], s[30:31], 0, v[142:143]
	v_lshl_add_u64 v[146:147], v[142:143], 0, v[138:139]
	v_mul_f32_e32 v128, v128, v141
	v_cvt_pk_bf16_f32 v128, v128, s0
	global_store_short v[146:147], v128, off
	v_mul_f32_e32 v128, v109, v129
	v_mul_f32_e32 v141, 0xbfb8aa3b, v128
	v_exp_f32_e32 v141, v141
	v_lshl_add_u64 v[146:147], v[142:143], 0, v[136:137]
	v_add_f32_e32 v141, 1.0, v141
	v_rcp_f32_e32 v141, v141
	s_nop 0
	v_mul_f32_e32 v128, v128, v141
	v_cvt_pk_bf16_f32 v128, v128, s0
	global_store_short v[146:147], v128, off
	v_mul_f32_e32 v128, v93, v129
	v_mul_f32_e32 v141, 0xbfb8aa3b, v128
	v_exp_f32_e32 v141, v141
	v_lshl_add_u64 v[146:147], v[142:143], 0, v[134:135]
	v_add_f32_e32 v141, 1.0, v141
	v_rcp_f32_e32 v141, v141
	s_nop 0
	v_mul_f32_e32 v128, v128, v141
	v_cvt_pk_bf16_f32 v128, v128, s0
	global_store_short v[146:147], v128, off
	v_mul_f32_e32 v128, v77, v129
	v_mul_f32_e32 v129, 0xbfb8aa3b, v128
	v_exp_f32_e32 v129, v129
	s_nop 0
	v_add_f32_e32 v129, 1.0, v129
	v_rcp_f32_e32 v129, v129
	s_nop 0
	v_mul_f32_e32 v128, v128, v129
	v_cvt_pk_bf16_f32 v141, v128, s0
	v_lshl_add_u64 v[128:129], v[142:143], 0, v[132:133]
	global_store_short v[128:129], v141, off
	v_mul_f32_e32 v141, v126, v130
	v_mul_f32_e32 v142, 0xbfb8aa3b, v141
	v_exp_f32_e32 v142, v142
	v_add_u32_e32 v128, 26, v140
	v_ashrrev_i32_e32 v129, 31, v128
	v_lshlrev_b64 v[128:129], 10, v[128:129]
	v_add_f32_e32 v142, 1.0, v142
	v_rcp_f32_e32 v142, v142
	v_lshl_add_u64 v[128:129], s[30:31], 0, v[128:129]
	v_mul_f32_e32 v141, v141, v142
	v_cvt_pk_bf16_f32 v141, v141, s0
	v_lshl_add_u64 v[142:143], v[128:129], 0, v[138:139]
	global_store_short v[142:143], v141, off
	v_mul_f32_e32 v141, v110, v130
	v_mul_f32_e32 v142, 0xbfb8aa3b, v141
	v_exp_f32_e32 v142, v142
	s_nop 0
	v_add_f32_e32 v142, 1.0, v142
	v_rcp_f32_e32 v142, v142
	s_nop 0
	v_mul_f32_e32 v141, v141, v142
	v_cvt_pk_bf16_f32 v141, v141, s0
	v_lshl_add_u64 v[142:143], v[128:129], 0, v[136:137]
	global_store_short v[142:143], v141, off
	v_mul_f32_e32 v141, v94, v130
	v_mul_f32_e32 v142, 0xbfb8aa3b, v141
	v_exp_f32_e32 v142, v142
	v_mul_f32_e32 v130, v78, v130
	v_add_f32_e32 v142, 1.0, v142
	v_rcp_f32_e32 v142, v142
	s_nop 0
	v_mul_f32_e32 v141, v141, v142
	v_cvt_pk_bf16_f32 v141, v141, s0
	v_lshl_add_u64 v[142:143], v[128:129], 0, v[134:135]
	global_store_short v[142:143], v141, off
	v_mul_f32_e32 v141, 0xbfb8aa3b, v130
	v_exp_f32_e32 v141, v141
	v_lshl_add_u64 v[128:129], v[128:129], 0, v[132:133]
	v_add_f32_e32 v141, 1.0, v141
	v_rcp_f32_e32 v141, v141
	s_nop 0
	v_mul_f32_e32 v130, v130, v141
	v_cvt_pk_bf16_f32 v130, v130, s0
	global_store_short v[128:129], v130, off
	v_mul_f32_e32 v130, v127, v131
	v_mul_f32_e32 v141, 0xbfb8aa3b, v130
	v_exp_f32_e32 v141, v141
	v_add_u32_e32 v128, 27, v140
	v_ashrrev_i32_e32 v129, 31, v128
	v_lshlrev_b64 v[128:129], 10, v[128:129]
	v_add_f32_e32 v141, 1.0, v141
	v_rcp_f32_e32 v141, v141
	v_lshl_add_u64 v[128:129], s[30:31], 0, v[128:129]
	v_lshl_add_u64 v[142:143], v[128:129], 0, v[138:139]
	v_mul_f32_e32 v130, v130, v141
	v_cvt_pk_bf16_f32 v130, v130, s0
	global_store_short v[142:143], v130, off
	v_mul_f32_e32 v130, v111, v131
	v_mul_f32_e32 v141, 0xbfb8aa3b, v130
	v_exp_f32_e32 v141, v141
	v_lshl_add_u64 v[142:143], v[128:129], 0, v[136:137]
	v_add_f32_e32 v141, 1.0, v141
	v_rcp_f32_e32 v141, v141
	s_nop 0
	v_mul_f32_e32 v130, v130, v141
	v_cvt_pk_bf16_f32 v130, v130, s0
	global_store_short v[142:143], v130, off
	v_mul_f32_e32 v130, v95, v131
	v_mul_f32_e32 v141, 0xbfb8aa3b, v130
	v_exp_f32_e32 v141, v141
	v_lshl_add_u64 v[142:143], v[128:129], 0, v[134:135]
	v_lshl_add_u64 v[128:129], v[128:129], 0, v[132:133]
	v_add_f32_e32 v141, 1.0, v141
	v_rcp_f32_e32 v141, v141
	s_nop 0
	v_mul_f32_e32 v130, v130, v141
	v_cvt_pk_bf16_f32 v130, v130, s0
	global_store_short v[142:143], v130, off
	v_mul_f32_e32 v130, v79, v131
	v_mul_f32_e32 v131, 0xbfb8aa3b, v130
	v_exp_f32_e32 v131, v131
	s_nop 0
	v_add_f32_e32 v131, 1.0, v131
	v_rcp_f32_e32 v131, v131
	s_nop 0
	v_mul_f32_e32 v130, v130, v131
	v_cvt_pk_bf16_f32 v130, v130, s0
	global_store_short v[128:129], v130, off
	v_or_b32_e32 v128, 32, v144
	v_add_u32_e32 v142, s76, v128
	v_lshl_add_u32 v128, v128, 2, s8
	ds_read_b128 v[128:131], v128
	v_ashrrev_i32_e32 v143, 31, v142
	v_lshlrev_b64 v[142:143], 10, v[142:143]
	v_lshl_add_u64 v[142:143], s[30:31], 0, v[142:143]
	s_waitcnt lgkmcnt(0)
; DI u16 f2bf(float a) { return (u16)(pack2(a, 0.f) & 0xffffu); }
; DI int crow(int reg, int g) { return (reg & 3) + 8 * (reg >> 2) + 4 * g; }
; DI float siluf(float x) { return x * __builtin_amdgcn_rcpf(1.f + __expf(-x)); }
; template <bool TR>
; DI void gemm_in_tile(const P& p, int l, int id, char* smem) {
;     ...
; #pragma unroll
;     for (int rb = 0; rb < 2; ++rb) {
; #pragma unroll
;       for (int reg = 0; reg < 16; ++reg) {
;         if ((reg & 7) == 0) asm volatile("" ::: "memory");
;         const int rl = 64 * wr + 32 * rb + crow(reg, g);
;         const int tok = m0 + rl;
;         const float rs = rs_s[rl];
; #pragma unroll
;         for (int cb = 0; cb < 4; ++cb) {
;           const int col = n0 - 3584 + 128 * wc + 32 * cb + li;
;           p.AG[(size_t)tok * 512 + col] = f2bf(siluf(acc[rb][cb][reg] * rs));
	v_mul_f32_e32 v141, v48, v128
	v_mul_f32_e32 v146, 0xbfb8aa3b, v141
	v_exp_f32_e32 v146, v146
	s_nop 0
	v_add_f32_e32 v146, 1.0, v146
	v_rcp_f32_e32 v146, v146
	s_nop 0
	v_mul_f32_e32 v141, v141, v146
	v_cvt_pk_bf16_f32 v141, v141, s0
	v_lshl_add_u64 v[146:147], v[142:143], 0, v[138:139]
	global_store_short v[146:147], v141, off
	v_mul_f32_e32 v141, v32, v128
	v_mul_f32_e32 v146, 0xbfb8aa3b, v141
	v_exp_f32_e32 v146, v146
	s_nop 0
	v_add_f32_e32 v146, 1.0, v146
	v_rcp_f32_e32 v146, v146
	s_nop 0
	v_mul_f32_e32 v141, v141, v146
	v_cvt_pk_bf16_f32 v141, v141, s0
	v_lshl_add_u64 v[146:147], v[142:143], 0, v[136:137]
	global_store_short v[146:147], v141, off
	v_mul_f32_e32 v141, v16, v128
	v_mul_f32_e32 v146, 0xbfb8aa3b, v141
	v_exp_f32_e32 v146, v146
	v_mul_f32_e32 v128, v0, v128
	v_add_f32_e32 v146, 1.0, v146
	v_rcp_f32_e32 v146, v146
	s_nop 0
	v_mul_f32_e32 v141, v141, v146
	v_cvt_pk_bf16_f32 v141, v141, s0
	v_lshl_add_u64 v[146:147], v[142:143], 0, v[134:135]
	global_store_short v[146:147], v141, off
	v_mul_f32_e32 v141, 0xbfb8aa3b, v128
	v_exp_f32_e32 v141, v141
	v_lshl_add_u64 v[142:143], v[142:143], 0, v[132:133]
	v_add_f32_e32 v141, 1.0, v141
	v_rcp_f32_e32 v141, v141
	s_nop 0
	v_mul_f32_e32 v128, v128, v141
	v_cvt_pk_bf16_f32 v128, v128, s0
	global_store_short v[142:143], v128, off
	v_mul_f32_e32 v128, v49, v129
	v_mul_f32_e32 v141, 0xbfb8aa3b, v128
	v_exp_f32_e32 v141, v141
	v_add_u32_e32 v142, 33, v140
	v_ashrrev_i32_e32 v143, 31, v142
	v_lshlrev_b64 v[142:143], 10, v[142:143]
	v_add_f32_e32 v141, 1.0, v141
	v_rcp_f32_e32 v141, v141
	v_lshl_add_u64 v[142:143], s[30:31], 0, v[142:143]
	v_lshl_add_u64 v[146:147], v[142:143], 0, v[138:139]
	v_mul_f32_e32 v128, v128, v141
	v_cvt_pk_bf16_f32 v128, v128, s0
	global_store_short v[146:147], v128, off
	v_mul_f32_e32 v128, v33, v129
	v_mul_f32_e32 v141, 0xbfb8aa3b, v128
	v_exp_f32_e32 v141, v141
	v_lshl_add_u64 v[146:147], v[142:143], 0, v[136:137]
	v_add_f32_e32 v141, 1.0, v141
	v_rcp_f32_e32 v141, v141
	s_nop 0
	v_mul_f32_e32 v128, v128, v141
	v_cvt_pk_bf16_f32 v128, v128, s0
	global_store_short v[146:147], v128, off
	v_mul_f32_e32 v128, v17, v129
	v_mul_f32_e32 v141, 0xbfb8aa3b, v128
	v_exp_f32_e32 v141, v141
	v_lshl_add_u64 v[146:147], v[142:143], 0, v[134:135]
	v_add_f32_e32 v141, 1.0, v141
	v_rcp_f32_e32 v141, v141
	s_nop 0
	v_mul_f32_e32 v128, v128, v141
	v_cvt_pk_bf16_f32 v128, v128, s0
	global_store_short v[146:147], v128, off
	v_mul_f32_e32 v128, v1, v129
	v_mul_f32_e32 v129, 0xbfb8aa3b, v128
	v_exp_f32_e32 v129, v129
	s_nop 0
	v_add_f32_e32 v129, 1.0, v129
	v_rcp_f32_e32 v129, v129
	s_nop 0
	v_mul_f32_e32 v128, v128, v129
	v_cvt_pk_bf16_f32 v141, v128, s0
	v_lshl_add_u64 v[128:129], v[142:143], 0, v[132:133]
	global_store_short v[128:129], v141, off
	v_mul_f32_e32 v141, v50, v130
	v_mul_f32_e32 v142, 0xbfb8aa3b, v141
	v_exp_f32_e32 v142, v142
	v_add_u32_e32 v128, 34, v140
	v_ashrrev_i32_e32 v129, 31, v128
	v_lshlrev_b64 v[128:129], 10, v[128:129]
	v_add_f32_e32 v142, 1.0, v142
	v_rcp_f32_e32 v142, v142
	v_lshl_add_u64 v[128:129], s[30:31], 0, v[128:129]
	v_mul_f32_e32 v141, v141, v142
	v_cvt_pk_bf16_f32 v141, v141, s0
	v_lshl_add_u64 v[142:143], v[128:129], 0, v[138:139]
	global_store_short v[142:143], v141, off
	v_mul_f32_e32 v141, v34, v130
	v_mul_f32_e32 v142, 0xbfb8aa3b, v141
	v_exp_f32_e32 v142, v142
	s_nop 0
	v_add_f32_e32 v142, 1.0, v142
	v_rcp_f32_e32 v142, v142
	s_nop 0
	v_mul_f32_e32 v141, v141, v142
	v_cvt_pk_bf16_f32 v141, v141, s0
	v_lshl_add_u64 v[142:143], v[128:129], 0, v[136:137]
	global_store_short v[142:143], v141, off
	v_mul_f32_e32 v141, v18, v130
	v_mul_f32_e32 v142, 0xbfb8aa3b, v141
	v_exp_f32_e32 v142, v142
	v_mul_f32_e32 v130, v2, v130
	v_add_f32_e32 v142, 1.0, v142
	v_rcp_f32_e32 v142, v142
	s_nop 0
	v_mul_f32_e32 v141, v141, v142
	v_cvt_pk_bf16_f32 v141, v141, s0
	v_lshl_add_u64 v[142:143], v[128:129], 0, v[134:135]
	global_store_short v[142:143], v141, off
	v_mul_f32_e32 v141, 0xbfb8aa3b, v130
	v_exp_f32_e32 v141, v141
	v_lshl_add_u64 v[128:129], v[128:129], 0, v[132:133]
	v_add_f32_e32 v141, 1.0, v141
	v_rcp_f32_e32 v141, v141
	s_nop 0
	v_mul_f32_e32 v130, v130, v141
	v_cvt_pk_bf16_f32 v130, v130, s0
	global_store_short v[128:129], v130, off
	v_mul_f32_e32 v130, v51, v131
	v_mul_f32_e32 v141, 0xbfb8aa3b, v130
	v_exp_f32_e32 v141, v141
	v_add_u32_e32 v128, 35, v140
	v_ashrrev_i32_e32 v129, 31, v128
	v_lshlrev_b64 v[128:129], 10, v[128:129]
	v_add_f32_e32 v141, 1.0, v141
	v_rcp_f32_e32 v141, v141
	v_lshl_add_u64 v[128:129], s[30:31], 0, v[128:129]
	v_lshl_add_u64 v[142:143], v[128:129], 0, v[138:139]
	v_mul_f32_e32 v130, v130, v141
	v_cvt_pk_bf16_f32 v130, v130, s0
	global_store_short v[142:143], v130, off
	v_mul_f32_e32 v130, v35, v131
	v_mul_f32_e32 v141, 0xbfb8aa3b, v130
	v_exp_f32_e32 v141, v141
	v_lshl_add_u64 v[142:143], v[128:129], 0, v[136:137]
	v_add_f32_e32 v141, 1.0, v141
	v_rcp_f32_e32 v141, v141
	s_nop 0
	v_mul_f32_e32 v130, v130, v141
	v_cvt_pk_bf16_f32 v130, v130, s0
	global_store_short v[142:143], v130, off
	v_mul_f32_e32 v130, v19, v131
	v_mul_f32_e32 v141, 0xbfb8aa3b, v130
	v_exp_f32_e32 v141, v141
	v_lshl_add_u64 v[142:143], v[128:129], 0, v[134:135]
	v_lshl_add_u64 v[128:129], v[128:129], 0, v[132:133]
	v_add_f32_e32 v141, 1.0, v141
	v_rcp_f32_e32 v141, v141
	s_nop 0
	v_mul_f32_e32 v130, v130, v141
	v_cvt_pk_bf16_f32 v130, v130, s0
	global_store_short v[142:143], v130, off
	v_mul_f32_e32 v130, v3, v131
	v_mul_f32_e32 v131, 0xbfb8aa3b, v130
	v_exp_f32_e32 v131, v131
	s_nop 0
	v_add_f32_e32 v131, 1.0, v131
	v_rcp_f32_e32 v131, v131
	s_nop 0
	v_mul_f32_e32 v130, v130, v131
	v_cvt_pk_bf16_f32 v130, v130, s0
	global_store_short v[128:129], v130, off
	v_or_b32_e32 v128, 40, v144
	v_add_u32_e32 v142, s76, v128
	v_lshl_add_u32 v128, v128, 2, s8
	ds_read_b128 v[128:131], v128
	v_ashrrev_i32_e32 v143, 31, v142
	v_lshlrev_b64 v[142:143], 10, v[142:143]
	v_lshl_add_u64 v[142:143], s[30:31], 0, v[142:143]
	s_waitcnt lgkmcnt(0)
; DI u16 f2bf(float a) { return (u16)(pack2(a, 0.f) & 0xffffu); }
; DI int crow(int reg, int g) { return (reg & 3) + 8 * (reg >> 2) + 4 * g; }
; DI float siluf(float x) { return x * __builtin_amdgcn_rcpf(1.f + __expf(-x)); }
; template <bool TR>
; DI void gemm_in_tile(const P& p, int l, int id, char* smem) {
;     ...
; #pragma unroll
;     for (int rb = 0; rb < 2; ++rb) {
; #pragma unroll
;       for (int reg = 0; reg < 16; ++reg) {
;         if ((reg & 7) == 0) asm volatile("" ::: "memory");
;         const int rl = 64 * wr + 32 * rb + crow(reg, g);
;         const int tok = m0 + rl;
;         const float rs = rs_s[rl];
; #pragma unroll
;         for (int cb = 0; cb < 4; ++cb) {
;           const int col = n0 - 3584 + 128 * wc + 32 * cb + li;
;           p.AG[(size_t)tok * 512 + col] = f2bf(siluf(acc[rb][cb][reg] * rs));
	v_mul_f32_e32 v141, v52, v128
	v_mul_f32_e32 v146, 0xbfb8aa3b, v141
	v_exp_f32_e32 v146, v146
	s_nop 0
	v_add_f32_e32 v146, 1.0, v146
	v_rcp_f32_e32 v146, v146
	s_nop 0
	v_mul_f32_e32 v141, v141, v146
	v_cvt_pk_bf16_f32 v141, v141, s0
	v_lshl_add_u64 v[146:147], v[142:143], 0, v[138:139]
	global_store_short v[146:147], v141, off
	v_mul_f32_e32 v141, v36, v128
	v_mul_f32_e32 v146, 0xbfb8aa3b, v141
	v_exp_f32_e32 v146, v146
	s_nop 0
	v_add_f32_e32 v146, 1.0, v146
	v_rcp_f32_e32 v146, v146
	s_nop 0
	v_mul_f32_e32 v141, v141, v146
	v_cvt_pk_bf16_f32 v141, v141, s0
	v_lshl_add_u64 v[146:147], v[142:143], 0, v[136:137]
	global_store_short v[146:147], v141, off
	v_mul_f32_e32 v141, v20, v128
	v_mul_f32_e32 v146, 0xbfb8aa3b, v141
	v_exp_f32_e32 v146, v146
	v_mul_f32_e32 v128, v4, v128
	v_add_f32_e32 v146, 1.0, v146
	v_rcp_f32_e32 v146, v146
	s_nop 0
	v_mul_f32_e32 v141, v141, v146
	v_cvt_pk_bf16_f32 v141, v141, s0
	v_lshl_add_u64 v[146:147], v[142:143], 0, v[134:135]
	global_store_short v[146:147], v141, off
	v_mul_f32_e32 v141, 0xbfb8aa3b, v128
	v_exp_f32_e32 v141, v141
	v_lshl_add_u64 v[142:143], v[142:143], 0, v[132:133]
	v_add_f32_e32 v141, 1.0, v141
	v_rcp_f32_e32 v141, v141
	s_nop 0
	v_mul_f32_e32 v128, v128, v141
	v_cvt_pk_bf16_f32 v128, v128, s0
	global_store_short v[142:143], v128, off
	v_mul_f32_e32 v128, v53, v129
	v_mul_f32_e32 v141, 0xbfb8aa3b, v128
	v_exp_f32_e32 v141, v141
	v_add_u32_e32 v142, 41, v140
	v_ashrrev_i32_e32 v143, 31, v142
	v_lshlrev_b64 v[142:143], 10, v[142:143]
	v_add_f32_e32 v141, 1.0, v141
	v_rcp_f32_e32 v141, v141
	v_lshl_add_u64 v[142:143], s[30:31], 0, v[142:143]
	v_lshl_add_u64 v[146:147], v[142:143], 0, v[138:139]
	v_mul_f32_e32 v128, v128, v141
	v_cvt_pk_bf16_f32 v128, v128, s0
	global_store_short v[146:147], v128, off
	v_mul_f32_e32 v128, v37, v129
	v_mul_f32_e32 v141, 0xbfb8aa3b, v128
	v_exp_f32_e32 v141, v141
	v_lshl_add_u64 v[146:147], v[142:143], 0, v[136:137]
	v_add_f32_e32 v141, 1.0, v141
	v_rcp_f32_e32 v141, v141
	s_nop 0
	v_mul_f32_e32 v128, v128, v141
	v_cvt_pk_bf16_f32 v128, v128, s0
	global_store_short v[146:147], v128, off
	v_mul_f32_e32 v128, v21, v129
	v_mul_f32_e32 v141, 0xbfb8aa3b, v128
	v_exp_f32_e32 v141, v141
	v_lshl_add_u64 v[146:147], v[142:143], 0, v[134:135]
	v_add_f32_e32 v141, 1.0, v141
	v_rcp_f32_e32 v141, v141
	s_nop 0
	v_mul_f32_e32 v128, v128, v141
	v_cvt_pk_bf16_f32 v128, v128, s0
	global_store_short v[146:147], v128, off
	v_mul_f32_e32 v128, v5, v129
	v_mul_f32_e32 v129, 0xbfb8aa3b, v128
	v_exp_f32_e32 v129, v129
	s_nop 0
	v_add_f32_e32 v129, 1.0, v129
	v_rcp_f32_e32 v129, v129
	s_nop 0
	v_mul_f32_e32 v128, v128, v129
	v_cvt_pk_bf16_f32 v141, v128, s0
	v_lshl_add_u64 v[128:129], v[142:143], 0, v[132:133]
	global_store_short v[128:129], v141, off
	v_mul_f32_e32 v141, v54, v130
	v_mul_f32_e32 v142, 0xbfb8aa3b, v141
	v_exp_f32_e32 v142, v142
	v_add_u32_e32 v128, 42, v140
	v_ashrrev_i32_e32 v129, 31, v128
	v_lshlrev_b64 v[128:129], 10, v[128:129]
	v_add_f32_e32 v142, 1.0, v142
	v_rcp_f32_e32 v142, v142
	v_lshl_add_u64 v[128:129], s[30:31], 0, v[128:129]
	v_mul_f32_e32 v141, v141, v142
	v_cvt_pk_bf16_f32 v141, v141, s0
	v_lshl_add_u64 v[142:143], v[128:129], 0, v[138:139]
	global_store_short v[142:143], v141, off
	v_mul_f32_e32 v141, v38, v130
	v_mul_f32_e32 v142, 0xbfb8aa3b, v141
	v_exp_f32_e32 v142, v142
	s_nop 0
	v_add_f32_e32 v142, 1.0, v142
	v_rcp_f32_e32 v142, v142
	s_nop 0
	v_mul_f32_e32 v141, v141, v142
	v_cvt_pk_bf16_f32 v141, v141, s0
	v_lshl_add_u64 v[142:143], v[128:129], 0, v[136:137]
	global_store_short v[142:143], v141, off
	v_mul_f32_e32 v141, v22, v130
	v_mul_f32_e32 v142, 0xbfb8aa3b, v141
	v_exp_f32_e32 v142, v142
	v_mul_f32_e32 v130, v6, v130
	v_add_f32_e32 v142, 1.0, v142
	v_rcp_f32_e32 v142, v142
	s_nop 0
	v_mul_f32_e32 v141, v141, v142
	v_cvt_pk_bf16_f32 v141, v141, s0
	v_lshl_add_u64 v[142:143], v[128:129], 0, v[134:135]
	global_store_short v[142:143], v141, off
	v_mul_f32_e32 v141, 0xbfb8aa3b, v130
	v_exp_f32_e32 v141, v141
	v_lshl_add_u64 v[128:129], v[128:129], 0, v[132:133]
	v_add_f32_e32 v141, 1.0, v141
	v_rcp_f32_e32 v141, v141
	s_nop 0
	v_mul_f32_e32 v130, v130, v141
	v_cvt_pk_bf16_f32 v130, v130, s0
	global_store_short v[128:129], v130, off
	v_mul_f32_e32 v130, v55, v131
	v_mul_f32_e32 v141, 0xbfb8aa3b, v130
	v_exp_f32_e32 v141, v141
	v_add_u32_e32 v128, 43, v140
	v_ashrrev_i32_e32 v129, 31, v128
	v_lshlrev_b64 v[128:129], 10, v[128:129]
	v_add_f32_e32 v141, 1.0, v141
	v_rcp_f32_e32 v141, v141
	v_lshl_add_u64 v[128:129], s[30:31], 0, v[128:129]
	v_lshl_add_u64 v[142:143], v[128:129], 0, v[138:139]
	v_mul_f32_e32 v130, v130, v141
	v_cvt_pk_bf16_f32 v130, v130, s0
	global_store_short v[142:143], v130, off
	v_mul_f32_e32 v130, v39, v131
	v_mul_f32_e32 v141, 0xbfb8aa3b, v130
	v_exp_f32_e32 v141, v141
	v_lshl_add_u64 v[142:143], v[128:129], 0, v[136:137]
	v_add_f32_e32 v141, 1.0, v141
	v_rcp_f32_e32 v141, v141
	s_nop 0
	v_mul_f32_e32 v130, v130, v141
	v_cvt_pk_bf16_f32 v130, v130, s0
	global_store_short v[142:143], v130, off
	v_mul_f32_e32 v130, v23, v131
	v_mul_f32_e32 v141, 0xbfb8aa3b, v130
	v_exp_f32_e32 v141, v141
	v_lshl_add_u64 v[142:143], v[128:129], 0, v[134:135]
	v_lshl_add_u64 v[128:129], v[128:129], 0, v[132:133]
	v_add_f32_e32 v141, 1.0, v141
	v_rcp_f32_e32 v141, v141
	s_nop 0
	v_mul_f32_e32 v130, v130, v141
	v_cvt_pk_bf16_f32 v130, v130, s0
	global_store_short v[142:143], v130, off
	v_mul_f32_e32 v130, v7, v131
	v_mul_f32_e32 v131, 0xbfb8aa3b, v130
	v_exp_f32_e32 v131, v131
	s_nop 0
	v_add_f32_e32 v131, 1.0, v131
	v_rcp_f32_e32 v131, v131
	s_nop 0
	v_mul_f32_e32 v130, v130, v131
	v_cvt_pk_bf16_f32 v130, v130, s0
	global_store_short v[128:129], v130, off
	v_or_b32_e32 v128, 48, v144
	v_add_u32_e32 v142, s76, v128
	v_lshl_add_u32 v128, v128, 2, s8
	ds_read_b128 v[128:131], v128
	v_ashrrev_i32_e32 v143, 31, v142
	v_lshlrev_b64 v[142:143], 10, v[142:143]
	v_lshl_add_u64 v[142:143], s[30:31], 0, v[142:143]
	s_waitcnt lgkmcnt(0)
; DI u16 f2bf(float a) { return (u16)(pack2(a, 0.f) & 0xffffu); }
; DI int crow(int reg, int g) { return (reg & 3) + 8 * (reg >> 2) + 4 * g; }
; DI float siluf(float x) { return x * __builtin_amdgcn_rcpf(1.f + __expf(-x)); }
; template <bool TR>
; DI void gemm_in_tile(const P& p, int l, int id, char* smem) {
;     ...
; #pragma unroll
;     for (int rb = 0; rb < 2; ++rb) {
; #pragma unroll
;       for (int reg = 0; reg < 16; ++reg) {
;         if ((reg & 7) == 0) asm volatile("" ::: "memory");
;         const int rl = 64 * wr + 32 * rb + crow(reg, g);
;         const int tok = m0 + rl;
;         const float rs = rs_s[rl];
; #pragma unroll
;         for (int cb = 0; cb < 4; ++cb) {
;           const int col = n0 - 3584 + 128 * wc + 32 * cb + li;
;           p.AG[(size_t)tok * 512 + col] = f2bf(siluf(acc[rb][cb][reg] * rs));
	v_mul_f32_e32 v141, v56, v128
	v_mul_f32_e32 v146, 0xbfb8aa3b, v141
	v_exp_f32_e32 v146, v146
	s_nop 0
	v_add_f32_e32 v146, 1.0, v146
	v_rcp_f32_e32 v146, v146
	s_nop 0
	v_mul_f32_e32 v141, v141, v146
	v_cvt_pk_bf16_f32 v141, v141, s0
	v_lshl_add_u64 v[146:147], v[142:143], 0, v[138:139]
	global_store_short v[146:147], v141, off
	v_mul_f32_e32 v141, v40, v128
	v_mul_f32_e32 v146, 0xbfb8aa3b, v141
	v_exp_f32_e32 v146, v146
	s_nop 0
	v_add_f32_e32 v146, 1.0, v146
	v_rcp_f32_e32 v146, v146
	s_nop 0
	v_mul_f32_e32 v141, v141, v146
	v_cvt_pk_bf16_f32 v141, v141, s0
	v_lshl_add_u64 v[146:147], v[142:143], 0, v[136:137]
	global_store_short v[146:147], v141, off
	v_mul_f32_e32 v141, v24, v128
	v_mul_f32_e32 v146, 0xbfb8aa3b, v141
	v_exp_f32_e32 v146, v146
	v_mul_f32_e32 v128, v8, v128
	v_add_f32_e32 v146, 1.0, v146
	v_rcp_f32_e32 v146, v146
	s_nop 0
	v_mul_f32_e32 v141, v141, v146
	v_cvt_pk_bf16_f32 v141, v141, s0
	v_lshl_add_u64 v[146:147], v[142:143], 0, v[134:135]
	global_store_short v[146:147], v141, off
	v_mul_f32_e32 v141, 0xbfb8aa3b, v128
	v_exp_f32_e32 v141, v141
	v_lshl_add_u64 v[142:143], v[142:143], 0, v[132:133]
	v_add_f32_e32 v141, 1.0, v141
	v_rcp_f32_e32 v141, v141
	s_nop 0
	v_mul_f32_e32 v128, v128, v141
	v_cvt_pk_bf16_f32 v128, v128, s0
	global_store_short v[142:143], v128, off
	v_mul_f32_e32 v128, v57, v129
	v_mul_f32_e32 v141, 0xbfb8aa3b, v128
	v_exp_f32_e32 v141, v141
	v_add_u32_e32 v142, 49, v140
	v_ashrrev_i32_e32 v143, 31, v142
	v_lshlrev_b64 v[142:143], 10, v[142:143]
	v_add_f32_e32 v141, 1.0, v141
	v_rcp_f32_e32 v141, v141
	v_lshl_add_u64 v[142:143], s[30:31], 0, v[142:143]
	v_lshl_add_u64 v[146:147], v[142:143], 0, v[138:139]
	v_mul_f32_e32 v128, v128, v141
	v_cvt_pk_bf16_f32 v128, v128, s0
	global_store_short v[146:147], v128, off
	v_mul_f32_e32 v128, v41, v129
	v_mul_f32_e32 v141, 0xbfb8aa3b, v128
	v_exp_f32_e32 v141, v141
	v_lshl_add_u64 v[146:147], v[142:143], 0, v[136:137]
	v_add_f32_e32 v141, 1.0, v141
	v_rcp_f32_e32 v141, v141
	s_nop 0
	v_mul_f32_e32 v128, v128, v141
	v_cvt_pk_bf16_f32 v128, v128, s0
	global_store_short v[146:147], v128, off
	v_mul_f32_e32 v128, v25, v129
	v_mul_f32_e32 v141, 0xbfb8aa3b, v128
	v_exp_f32_e32 v141, v141
	v_lshl_add_u64 v[146:147], v[142:143], 0, v[134:135]
	v_add_f32_e32 v141, 1.0, v141
	v_rcp_f32_e32 v141, v141
	s_nop 0
	v_mul_f32_e32 v128, v128, v141
	v_cvt_pk_bf16_f32 v128, v128, s0
	global_store_short v[146:147], v128, off
	v_mul_f32_e32 v128, v9, v129
	v_mul_f32_e32 v129, 0xbfb8aa3b, v128
	v_exp_f32_e32 v129, v129
	s_nop 0
	v_add_f32_e32 v129, 1.0, v129
	v_rcp_f32_e32 v129, v129
	s_nop 0
	v_mul_f32_e32 v128, v128, v129
	v_cvt_pk_bf16_f32 v141, v128, s0
	v_lshl_add_u64 v[128:129], v[142:143], 0, v[132:133]
	global_store_short v[128:129], v141, off
	v_mul_f32_e32 v141, v58, v130
	v_mul_f32_e32 v142, 0xbfb8aa3b, v141
	v_exp_f32_e32 v142, v142
	v_add_u32_e32 v128, 50, v140
	v_ashrrev_i32_e32 v129, 31, v128
	v_lshlrev_b64 v[128:129], 10, v[128:129]
	v_add_f32_e32 v142, 1.0, v142
	v_rcp_f32_e32 v142, v142
	v_lshl_add_u64 v[128:129], s[30:31], 0, v[128:129]
	v_mul_f32_e32 v141, v141, v142
	v_cvt_pk_bf16_f32 v141, v141, s0
	v_lshl_add_u64 v[142:143], v[128:129], 0, v[138:139]
	global_store_short v[142:143], v141, off
	v_mul_f32_e32 v141, v42, v130
	v_mul_f32_e32 v142, 0xbfb8aa3b, v141
	v_exp_f32_e32 v142, v142
	s_nop 0
	v_add_f32_e32 v142, 1.0, v142
	v_rcp_f32_e32 v142, v142
	s_nop 0
	v_mul_f32_e32 v141, v141, v142
	v_cvt_pk_bf16_f32 v141, v141, s0
	v_lshl_add_u64 v[142:143], v[128:129], 0, v[136:137]
	global_store_short v[142:143], v141, off
	v_mul_f32_e32 v141, v26, v130
	v_mul_f32_e32 v142, 0xbfb8aa3b, v141
	v_exp_f32_e32 v142, v142
	v_mul_f32_e32 v130, v10, v130
	v_add_f32_e32 v142, 1.0, v142
	v_rcp_f32_e32 v142, v142
	s_nop 0
	v_mul_f32_e32 v141, v141, v142
	v_cvt_pk_bf16_f32 v141, v141, s0
	v_lshl_add_u64 v[142:143], v[128:129], 0, v[134:135]
	global_store_short v[142:143], v141, off
	v_mul_f32_e32 v141, 0xbfb8aa3b, v130
	v_exp_f32_e32 v141, v141
	v_lshl_add_u64 v[128:129], v[128:129], 0, v[132:133]
	v_add_f32_e32 v141, 1.0, v141
	v_rcp_f32_e32 v141, v141
	s_nop 0
	v_mul_f32_e32 v130, v130, v141
	v_cvt_pk_bf16_f32 v130, v130, s0
	global_store_short v[128:129], v130, off
	v_mul_f32_e32 v130, v59, v131
	v_mul_f32_e32 v141, 0xbfb8aa3b, v130
	v_exp_f32_e32 v141, v141
	v_add_u32_e32 v128, 51, v140
	v_ashrrev_i32_e32 v129, 31, v128
	v_lshlrev_b64 v[128:129], 10, v[128:129]
	v_add_f32_e32 v141, 1.0, v141
	v_rcp_f32_e32 v141, v141
	v_lshl_add_u64 v[128:129], s[30:31], 0, v[128:129]
	v_lshl_add_u64 v[142:143], v[128:129], 0, v[138:139]
	v_mul_f32_e32 v130, v130, v141
	v_cvt_pk_bf16_f32 v130, v130, s0
	global_store_short v[142:143], v130, off
	v_mul_f32_e32 v130, v43, v131
	v_mul_f32_e32 v141, 0xbfb8aa3b, v130
	v_exp_f32_e32 v141, v141
	v_lshl_add_u64 v[142:143], v[128:129], 0, v[136:137]
	v_add_f32_e32 v141, 1.0, v141
	v_rcp_f32_e32 v141, v141
	s_nop 0
	v_mul_f32_e32 v130, v130, v141
	v_cvt_pk_bf16_f32 v130, v130, s0
	global_store_short v[142:143], v130, off
	v_mul_f32_e32 v130, v27, v131
	v_mul_f32_e32 v141, 0xbfb8aa3b, v130
	v_exp_f32_e32 v141, v141
	v_lshl_add_u64 v[142:143], v[128:129], 0, v[134:135]
	v_lshl_add_u64 v[128:129], v[128:129], 0, v[132:133]
	v_add_f32_e32 v141, 1.0, v141
	v_rcp_f32_e32 v141, v141
	s_nop 0
	v_mul_f32_e32 v130, v130, v141
	v_cvt_pk_bf16_f32 v130, v130, s0
	global_store_short v[142:143], v130, off
	v_mul_f32_e32 v130, v11, v131
	v_mul_f32_e32 v131, 0xbfb8aa3b, v130
	v_exp_f32_e32 v131, v131
	s_nop 0
	v_add_f32_e32 v131, 1.0, v131
	v_rcp_f32_e32 v131, v131
	s_nop 0
	v_mul_f32_e32 v130, v130, v131
	v_cvt_pk_bf16_f32 v130, v130, s0
	global_store_short v[128:129], v130, off
	v_or_b32_e32 v128, 56, v144
	v_add_u32_e32 v142, s76, v128
	v_lshl_add_u32 v128, v128, 2, s8
	ds_read_b128 v[128:131], v128
	v_ashrrev_i32_e32 v143, 31, v142
	v_lshlrev_b64 v[142:143], 10, v[142:143]
	v_lshl_add_u64 v[142:143], s[30:31], 0, v[142:143]
	s_mov_b64 s[8:9], 0
	s_waitcnt lgkmcnt(0)
; DI u16 f2bf(float a) { return (u16)(pack2(a, 0.f) & 0xffffu); }
; DI int crow(int reg, int g) { return (reg & 3) + 8 * (reg >> 2) + 4 * g; }
; DI float siluf(float x) { return x * __builtin_amdgcn_rcpf(1.f + __expf(-x)); }
; template <bool TR>
; DI void gemm_in_tile(const P& p, int l, int id, char* smem) {
;     ...
; #pragma unroll
;     for (int rb = 0; rb < 2; ++rb) {
; #pragma unroll
;       for (int reg = 0; reg < 16; ++reg) {
;         if ((reg & 7) == 0) asm volatile("" ::: "memory");
;         const int rl = 64 * wr + 32 * rb + crow(reg, g);
;         const int tok = m0 + rl;
;         const float rs = rs_s[rl];
; #pragma unroll
;         for (int cb = 0; cb < 4; ++cb) {
;           const int col = n0 - 3584 + 128 * wc + 32 * cb + li;
;           p.AG[(size_t)tok * 512 + col] = f2bf(siluf(acc[rb][cb][reg] * rs));
	v_mul_f32_e32 v141, v60, v128
	v_mul_f32_e32 v146, 0xbfb8aa3b, v141
	v_exp_f32_e32 v146, v146
	s_nop 0
	v_add_f32_e32 v146, 1.0, v146
	v_rcp_f32_e32 v146, v146
	s_nop 0
	v_mul_f32_e32 v141, v141, v146
	v_cvt_pk_bf16_f32 v141, v141, s0
	v_lshl_add_u64 v[146:147], v[142:143], 0, v[138:139]
	global_store_short v[146:147], v141, off
	v_mul_f32_e32 v141, v44, v128
	v_mul_f32_e32 v146, 0xbfb8aa3b, v141
	v_exp_f32_e32 v146, v146
	s_nop 0
	v_add_f32_e32 v146, 1.0, v146
	v_rcp_f32_e32 v146, v146
	s_nop 0
	v_mul_f32_e32 v141, v141, v146
	v_cvt_pk_bf16_f32 v141, v141, s0
	v_lshl_add_u64 v[146:147], v[142:143], 0, v[136:137]
	global_store_short v[146:147], v141, off
	v_mul_f32_e32 v141, v28, v128
	v_mul_f32_e32 v146, 0xbfb8aa3b, v141
	v_exp_f32_e32 v146, v146
	v_mul_f32_e32 v128, v12, v128
	v_add_f32_e32 v146, 1.0, v146
	v_rcp_f32_e32 v146, v146
	s_nop 0
	v_mul_f32_e32 v141, v141, v146
	v_cvt_pk_bf16_f32 v141, v141, s0
	v_lshl_add_u64 v[146:147], v[142:143], 0, v[134:135]
	global_store_short v[146:147], v141, off
	v_mul_f32_e32 v141, 0xbfb8aa3b, v128
	v_exp_f32_e32 v141, v141
	v_lshl_add_u64 v[142:143], v[142:143], 0, v[132:133]
	v_add_f32_e32 v141, 1.0, v141
	v_rcp_f32_e32 v141, v141
	s_nop 0
	v_mul_f32_e32 v128, v128, v141
	v_cvt_pk_bf16_f32 v128, v128, s0
	global_store_short v[142:143], v128, off
	v_mul_f32_e32 v128, v61, v129
	v_mul_f32_e32 v141, 0xbfb8aa3b, v128
	v_exp_f32_e32 v141, v141
	v_add_u32_e32 v142, 57, v140
	v_ashrrev_i32_e32 v143, 31, v142
	v_lshlrev_b64 v[142:143], 10, v[142:143]
	v_add_f32_e32 v141, 1.0, v141
	v_rcp_f32_e32 v141, v141
	v_lshl_add_u64 v[142:143], s[30:31], 0, v[142:143]
	v_lshl_add_u64 v[146:147], v[142:143], 0, v[138:139]
	v_mul_f32_e32 v128, v128, v141
	v_cvt_pk_bf16_f32 v128, v128, s0
	global_store_short v[146:147], v128, off
	v_mul_f32_e32 v128, v45, v129
	v_mul_f32_e32 v141, 0xbfb8aa3b, v128
	v_exp_f32_e32 v141, v141
	v_lshl_add_u64 v[146:147], v[142:143], 0, v[136:137]
	v_add_f32_e32 v141, 1.0, v141
	v_rcp_f32_e32 v141, v141
	s_nop 0
	v_mul_f32_e32 v128, v128, v141
	v_cvt_pk_bf16_f32 v128, v128, s0
	global_store_short v[146:147], v128, off
	v_mul_f32_e32 v128, v29, v129
	v_mul_f32_e32 v141, 0xbfb8aa3b, v128
	v_exp_f32_e32 v141, v141
	v_lshl_add_u64 v[146:147], v[142:143], 0, v[134:135]
	v_add_f32_e32 v141, 1.0, v141
	v_rcp_f32_e32 v141, v141
	s_nop 0
	v_mul_f32_e32 v128, v128, v141
	v_cvt_pk_bf16_f32 v128, v128, s0
	global_store_short v[146:147], v128, off
	v_mul_f32_e32 v128, v13, v129
	v_mul_f32_e32 v129, 0xbfb8aa3b, v128
	v_exp_f32_e32 v129, v129
	s_nop 0
	v_add_f32_e32 v129, 1.0, v129
	v_rcp_f32_e32 v129, v129
	s_nop 0
	v_mul_f32_e32 v128, v128, v129
	v_cvt_pk_bf16_f32 v141, v128, s0
	v_lshl_add_u64 v[128:129], v[142:143], 0, v[132:133]
	global_store_short v[128:129], v141, off
	v_mul_f32_e32 v141, v62, v130
	v_mul_f32_e32 v142, 0xbfb8aa3b, v141
	v_exp_f32_e32 v142, v142
	v_add_u32_e32 v128, 58, v140
	v_ashrrev_i32_e32 v129, 31, v128
	v_lshlrev_b64 v[128:129], 10, v[128:129]
	v_add_f32_e32 v142, 1.0, v142
	v_rcp_f32_e32 v142, v142
	v_lshl_add_u64 v[128:129], s[30:31], 0, v[128:129]
	v_mul_f32_e32 v141, v141, v142
	v_cvt_pk_bf16_f32 v141, v141, s0
	v_lshl_add_u64 v[142:143], v[128:129], 0, v[138:139]
	global_store_short v[142:143], v141, off
	v_mul_f32_e32 v141, v46, v130
	v_mul_f32_e32 v142, 0xbfb8aa3b, v141
	v_exp_f32_e32 v142, v142
	s_nop 0
	v_add_f32_e32 v142, 1.0, v142
	v_rcp_f32_e32 v142, v142
	s_nop 0
	v_mul_f32_e32 v141, v141, v142
	v_cvt_pk_bf16_f32 v141, v141, s0
	v_lshl_add_u64 v[142:143], v[128:129], 0, v[136:137]
	global_store_short v[142:143], v141, off
	v_mul_f32_e32 v141, v30, v130
	v_mul_f32_e32 v142, 0xbfb8aa3b, v141
	v_exp_f32_e32 v142, v142
	v_mul_f32_e32 v130, v14, v130
	v_add_f32_e32 v142, 1.0, v142
	v_rcp_f32_e32 v142, v142
	s_nop 0
	v_mul_f32_e32 v141, v141, v142
	v_cvt_pk_bf16_f32 v141, v141, s0
	v_lshl_add_u64 v[142:143], v[128:129], 0, v[134:135]
	global_store_short v[142:143], v141, off
	v_mul_f32_e32 v141, 0xbfb8aa3b, v130
	v_exp_f32_e32 v141, v141
	v_lshl_add_u64 v[128:129], v[128:129], 0, v[132:133]
	v_add_f32_e32 v141, 1.0, v141
	v_rcp_f32_e32 v141, v141
	s_nop 0
	v_mul_f32_e32 v130, v130, v141
	v_cvt_pk_bf16_f32 v130, v130, s0
	global_store_short v[128:129], v130, off
	v_mul_f32_e32 v130, v63, v131
	v_add_u32_e32 v128, 59, v140
	v_mul_f32_e32 v140, 0xbfb8aa3b, v130
	v_exp_f32_e32 v140, v140
	v_ashrrev_i32_e32 v129, 31, v128
	v_lshlrev_b64 v[128:129], 10, v[128:129]
	v_lshl_add_u64 v[128:129], s[30:31], 0, v[128:129]
	v_add_f32_e32 v140, 1.0, v140
	v_rcp_f32_e32 v140, v140
	v_lshl_add_u64 v[138:139], v[128:129], 0, v[138:139]
	v_lshl_add_u64 v[136:137], v[128:129], 0, v[136:137]
	v_lshl_add_u64 v[134:135], v[128:129], 0, v[134:135]
	v_mul_f32_e32 v130, v130, v140
	v_cvt_pk_bf16_f32 v130, v130, s0
	global_store_short v[138:139], v130, off
	v_mul_f32_e32 v130, v47, v131
	v_mul_f32_e32 v138, 0xbfb8aa3b, v130
	v_exp_f32_e32 v138, v138
	v_lshl_add_u64 v[128:129], v[128:129], 0, v[132:133]
	v_add_f32_e32 v138, 1.0, v138
	v_rcp_f32_e32 v138, v138
	s_nop 0
	v_mul_f32_e32 v130, v130, v138
	v_cvt_pk_bf16_f32 v130, v130, s0
	global_store_short v[136:137], v130, off
	v_mul_f32_e32 v130, v31, v131
	v_mul_f32_e32 v136, 0xbfb8aa3b, v130
	v_exp_f32_e32 v136, v136
	s_nop 0
	v_add_f32_e32 v136, 1.0, v136
	v_rcp_f32_e32 v136, v136
	s_nop 0
	v_mul_f32_e32 v130, v130, v136
	v_cvt_pk_bf16_f32 v130, v130, s0
	global_store_short v[134:135], v130, off
	v_mul_f32_e32 v130, v15, v131
	v_mul_f32_e32 v131, 0xbfb8aa3b, v130
	v_exp_f32_e32 v131, v131
	s_nop 0
	v_add_f32_e32 v131, 1.0, v131
	v_rcp_f32_e32 v131, v131
	s_nop 0
	v_mul_f32_e32 v130, v130, v131
	v_cvt_pk_bf16_f32 v130, v130, s0
	global_store_short v[128:129], v130, off

; DI f32x16 zero16() { f32x16 z; for (int i = 0; i < 16; ++i) z[i] = 0.f; return z; }
; template <bool AT>
; DI void gemm_main(f32x16 (&acc)[2][4], const u16* __restrict__ R, int ldr, const u16* __restrict__ Cm, int ldc,
;                   const u16* __restrict__ RT, int ldrt, int K, char* smem, int tid) {
;   constexpr int STG = 2 * 256 * 72;
;   u16* S0 = (u16*)smem;
;   const int lane = tid & 63, wave = tid >> 6, wr = wave >> 1, wc = wave & 1;
;   const int li = lane & 31, g = lane >> 5;
;   u32x4 rr[4], cr[4];
; #pragma unroll
;   for (int a = 0; a < 2; ++a)
; #pragma unroll
;     for (int b = 0; b < 4; ++b) acc[a][b] = zero16();
;   const int nk = K / 64;
; #pragma unroll
;   for (int i = 0; i < 4; ++i) {
;     const int cid = tid + NT * i;
;     const int row = cid >> 3, kc = cid & 7;
;     if (AT) {
;       const int kr = cid >> 5, tc = cid & 31;
;       rr[i] = *(const u32x4*)(RT + (size_t)kr * ldrt + tc * 8);
;     } else {
;       rr[i] = *(const u32x4*)(R + (size_t)row * ldr + kc * 8);
;     }
;     cr[i] = *(const u32x4*)(Cm + (size_t)row * ldc + kc * 8);
;   }
;   for (int kt = -1; kt < nk; ++kt) {
;     if (kt + 1 < nk) {
;       const int ks1 = kt + 1;
;       u16* Rs = S0 + (ks1 & 1) * STG;
;       u16* Cs = Rs + 256 * 72;
; #pragma unroll
;       for (int i = 0; i < 4; ++i) {
;         const int cid = tid + NT * i;
;         const int row = cid >> 3, kc = cid & 7;
;         if (AT && ks1 < 8) {
;           const int kr = cid >> 5, tc = cid & 31;
;           *(u32x4*)(Rs + kr * 264 + tc * 8) = rr[i];
;         } else {
;           *(u32x4*)(Rs + row * 72 + kc * 8) = rr[i];
;         }
;         *(u32x4*)(Cs + row * 72 + kc * 8) = cr[i];
;       }
.LBB0_341:
	s_or_b64 exec, exec, s[8:9]
	s_lshl_b32 s8, s74, 8
	s_lshl_b32 s9, s76, 19
	v_lshlrev_b32_e32 v0, 3, v177
	s_add_u32 s76, s36, s9
	v_and_b32_e32 v0, 56, v0
	s_addc_u32 s77, s37, 0
	v_lshlrev_b32_e32 v188, 1, v0
	s_ashr_i32 s9, s8, 31
	v_lshl_add_u64 v[20:21], s[76:77], 0, v[188:189]
	s_lshl_b64 s[76:77], s[8:9], 11
	v_readlane_b32 s9, v248, 29
	v_add_u32_e32 v8, 0x200, v177
	v_add_u32_e32 v9, 0x400, v177
	v_add_u32_e32 v10, 0x600, v177
	v_ashrrev_i32_e32 v32, 3, v177
	s_add_u32 s76, s9, s76
	v_readlane_b32 s9, v248, 30
	v_ashrrev_i32_e32 v40, 3, v8
	v_ashrrev_i32_e32 v42, 3, v9
	v_ashrrev_i32_e32 v44, 3, v10
	v_ashrrev_i32_e32 v33, 31, v32
	s_addc_u32 s77, s9, s77
	v_ashrrev_i32_e32 v41, 31, v40
	v_ashrrev_i32_e32 v43, 31, v42
	v_ashrrev_i32_e32 v45, 31, v44
	v_lshlrev_b64 v[34:35], 11, v[32:33]
	v_lshl_add_u64 v[24:25], s[76:77], 0, v[188:189]
	v_lshlrev_b64 v[46:47], 11, v[40:41]
	v_lshlrev_b64 v[52:53], 11, v[42:43]
	v_lshlrev_b64 v[56:57], 11, v[44:45]
	v_lshl_add_u64 v[36:37], v[20:21], 0, v[34:35]
	v_lshl_add_u64 v[38:39], v[24:25], 0, v[34:35]
	v_lshl_add_u64 v[48:49], v[24:25], 0, v[46:47]
	v_lshl_add_u64 v[50:51], v[20:21], 0, v[46:47]
	v_lshl_add_u64 v[54:55], v[24:25], 0, v[52:53]
	v_lshl_add_u64 v[60:61], v[20:21], 0, v[52:53]
	v_lshl_add_u64 v[62:63], v[24:25], 0, v[56:57]
	s_waitcnt lgkmcnt(0)
	global_load_dwordx4 v[0:3], v[36:37], off
	global_load_dwordx4 v[4:7], v[38:39], off
	global_load_dwordx4 v[8:11], v[48:49], off
	global_load_dwordx4 v[12:15], v[50:51], off
	global_load_dwordx4 v[16:19], v[54:55], off
	v_lshl_add_u64 v[58:59], v[20:21], 0, v[56:57]
	global_load_dwordx4 v[20:23], v[60:61], off
	global_load_dwordx4 v[24:27], v[62:63], off
	global_load_dwordx4 v[28:31], v[58:59], off
	global_load_dwordx4 v[136:139], v[36:37], off offset:128
	global_load_dwordx4 v[132:135], v[50:51], off offset:128
	global_load_dwordx4 v[128:131], v[60:61], off offset:128
	global_load_dwordx4 v[156:159], v[58:59], off offset:128
	global_load_dwordx4 v[152:155], v[38:39], off offset:128
	global_load_dwordx4 v[148:151], v[48:49], off offset:128
	global_load_dwordx4 v[144:147], v[54:55], off offset:128
	global_load_dwordx4 v[140:143], v[62:63], off offset:128
	s_movk_i32 s9, 0x48
	v_mul_lo_u32 v184, v32, s9
	v_mul_lo_u32 v185, v40, s9
	v_mul_lo_u32 v183, v42, s9
	v_mul_lo_u32 v182, v44, s9
	v_readlane_b32 s9, v248, 36
	s_add_u32 s76, s9, s64
	v_readlane_b32 s9, v248, 38
	s_addc_u32 s77, s9, 0
	s_lshl_b32 s9, s11, 8
	s_and_b32 s9, s9, 0xfffffc00
	v_ashrrev_i32_e32 v41, 1, v177
	s_or_b32 s10, s9, s10
	v_and_b32_e32 v33, 31, v177
	v_lshlrev_b32_e32 v45, 1, v177
	v_and_b32_e32 v178, 0xffffffc0, v41
	s_ashr_i32 s11, s10, 31
	v_lshlrev_b32_e32 v64, 4, v177
	v_and_or_b32 v176, v45, s95, v33
	v_or_b32_e32 v33, v178, v33
	v_add_u32_e32 v186, 0, v188
	s_lshl_b64 s[10:11], s[10:11], 11
	v_lshrrev_b32_e32 v43, 1, v177
	v_and_b32_e32 v32, 0x70, v64
	v_mul_lo_u32 v180, v33, s94
	v_lshl_add_u32 v33, v184, 1, v186
	s_add_u32 s10, s72, s10
	v_and_b32_e32 v179, 16, v43
	v_lshl_add_u32 v40, v185, 1, v186
	v_lshl_add_u32 v41, v183, 1, v186
	v_lshl_add_u32 v42, v182, 1, v186
	v_or_b32_e32 v56, v56, v32
	v_or_b32_e32 v52, v52, v32
	v_or_b32_e32 v46, v46, v32
	v_or_b32_e32 v34, v34, v32
	s_addc_u32 s11, s73, s11
	v_lshl_add_u64 v[160:161], s[76:77], 0, v[56:57]
	v_lshl_add_u64 v[162:163], s[76:77], 0, v[52:53]
	v_lshl_add_u64 v[164:165], s[76:77], 0, v[46:47]
	v_lshl_add_u64 v[166:167], s[76:77], 0, v[34:35]
	v_lshl_add_u64 v[168:169], s[10:11], 0, v[56:57]
	s_waitcnt vmcnt(15)
	ds_write_b128 v33, v[0:3] offset:36864
	s_waitcnt vmcnt(14)
	ds_write_b128 v33, v[4:7]
	s_waitcnt vmcnt(13)
	ds_write_b128 v40, v[8:11]
	s_waitcnt vmcnt(12)
	ds_write_b128 v40, v[12:15] offset:36864
	s_waitcnt vmcnt(11)
	ds_write_b128 v41, v[16:19]
	s_waitcnt vmcnt(10)
	ds_write_b128 v41, v[20:23] offset:36864
	s_waitcnt vmcnt(9)
	ds_write_b128 v42, v[24:27]
	s_waitcnt vmcnt(8)
	ds_write_b128 v42, v[28:31] offset:36864
	v_mov_b32_e32 v0, 0
	v_lshl_add_u64 v[170:171], s[10:11], 0, v[52:53]
	v_lshl_add_u64 v[172:173], s[10:11], 0, v[46:47]
	v_lshl_add_u64 v[174:175], s[10:11], 0, v[34:35]
	s_mov_b32 s9, 0
	s_mov_b64 s[10:11], 0
	v_mov_b32_e32 v1, v0
	v_mov_b32_e32 v2, v0
	v_mov_b32_e32 v3, v0
	v_mov_b32_e32 v4, v0
	v_mov_b32_e32 v5, v0
	v_mov_b32_e32 v6, v0
	v_mov_b32_e32 v7, v0
	v_mov_b32_e32 v8, v0
	v_mov_b32_e32 v9, v0
	v_mov_b32_e32 v10, v0
	v_mov_b32_e32 v11, v0
	v_mov_b32_e32 v12, v0
	v_mov_b32_e32 v13, v0
	v_mov_b32_e32 v14, v0
	v_mov_b32_e32 v15, v0
	v_mov_b32_e32 v32, v0
	v_mov_b32_e32 v33, v0
	v_mov_b32_e32 v34, v0
	v_mov_b32_e32 v35, v0
	v_mov_b32_e32 v36, v0
	v_mov_b32_e32 v37, v0
	v_mov_b32_e32 v38, v0
	v_mov_b32_e32 v39, v0
	v_mov_b32_e32 v40, v0
	v_mov_b32_e32 v41, v0
	v_mov_b32_e32 v42, v0
	v_mov_b32_e32 v43, v0
	v_mov_b32_e32 v44, v0
	v_mov_b32_e32 v45, v0
	v_mov_b32_e32 v46, v0
	v_mov_b32_e32 v47, v0
	v_mov_b32_e32 v64, v0
	v_mov_b32_e32 v65, v0
	v_mov_b32_e32 v66, v0
	v_mov_b32_e32 v67, v0
	v_mov_b32_e32 v68, v0
	v_mov_b32_e32 v69, v0
	v_mov_b32_e32 v70, v0
	v_mov_b32_e32 v71, v0
	v_mov_b32_e32 v72, v0
	v_mov_b32_e32 v73, v0
	v_mov_b32_e32 v74, v0
	v_mov_b32_e32 v75, v0
	v_mov_b32_e32 v76, v0
	v_mov_b32_e32 v77, v0
	v_mov_b32_e32 v78, v0
	v_mov_b32_e32 v79, v0
	v_mov_b32_e32 v96, v0
	v_mov_b32_e32 v97, v0
	v_mov_b32_e32 v98, v0
	v_mov_b32_e32 v99, v0
	v_mov_b32_e32 v100, v0
	v_mov_b32_e32 v101, v0
	v_mov_b32_e32 v102, v0
	v_mov_b32_e32 v103, v0
	v_mov_b32_e32 v104, v0
	v_mov_b32_e32 v105, v0
	v_mov_b32_e32 v106, v0
	v_mov_b32_e32 v107, v0
	v_mov_b32_e32 v108, v0
	v_mov_b32_e32 v109, v0
	v_mov_b32_e32 v110, v0
	v_mov_b32_e32 v111, v0
	v_mov_b32_e32 v16, v0
; template <bool AT>
; DI void gemm_main(f32x16 (&acc)[2][4], const u16* __restrict__ R, int ldr, const u16* __restrict__ Cm, int ldc,
;                   const u16* __restrict__ RT, int ldrt, int K, char* smem, int tid) {
;     ...
;   for (int kt = -1; kt < nk; ++kt) {
;     if (kt + 1 < nk) {
;       const int ks1 = kt + 1;
;       u16* Rs = S0 + (ks1 & 1) * STG;
;       u16* Cs = Rs + 256 * 72;
; #pragma unroll
;       for (int i = 0; i < 4; ++i) {
;         const int cid = tid + NT * i;
;         const int row = cid >> 3, kc = cid & 7;
;         if (AT && ks1 < 8) {
;           const int kr = cid >> 5, tc = cid & 31;
;           *(u32x4*)(Rs + kr * 264 + tc * 8) = rr[i];
;         } else {
;           *(u32x4*)(Rs + row * 72 + kc * 8) = rr[i];
;         }
;         *(u32x4*)(Cs + row * 72 + kc * 8) = cr[i];
;       }
;     }
;     if (kt + 2 < nk) {
;       const int kn = kt + 2;
; #pragma unroll
;       for (int i = 0; i < 4; ++i) {
;         const int cid = tid + NT * i;
;         const int row = cid >> 3, kc = cid & 7;
;         if (AT && kn < 8) {
;           const int kr = cid >> 5, tc = cid & 31;
;           rr[i] = *(const u32x4*)(RT + (size_t)(kn * 64 + kr) * ldrt + tc * 8);
;         } else {
;           rr[i] = *(const u32x4*)(R + (size_t)row * ldr + kn * 64 + kc * 8);
;         }
;         cr[i] = *(const u32x4*)(Cm + (size_t)row * ldc + kn * 64 + kc * 8);
;       }
;     }
;     __builtin_amdgcn_sched_barrier(0x38F);
;     if (kt >= 0) {
;       const u16* Rs = S0 + (kt & 1) * STG;
;       const u16* Cs = Rs + 256 * 72;
;       const u16* RTs = Rs;
; #pragma unroll
;       for (int ks = 0; ks < 4; ++ks) {
;         bf16x8 rf[2];
; #pragma unroll
;         for (int rb = 0; rb < 2; ++rb) {
;           if (AT && kt < 8) {
;             const u16* src = RTs + (16 * ks + 8 * g) * 264 + 64 * wr + 32 * rb + li;
;             bf16x8 t;
; #pragma unroll
;             for (int j = 0; j < 8; ++j) t[j] = (short)src[j * 264];
;             rf[rb] = t;
;           } else {
;             rf[rb] = *(const bf16x8*)(Rs + (64 * wr + 32 * rb + li) * 72 + 16 * ks + 8 * g);
;           }
;         }
; #pragma unroll
;         for (int cb = 0; cb < 4; ++cb) {
;           const bf16x8 cfv = *(const bf16x8*)(Cs + (128 * wc + 32 * cb + li) * 72 + 16 * ks + 8 * g);
; #pragma unroll
;           for (int rb = 0; rb < 2; ++rb) acc[rb][cb] = MFMA(rf[rb], cfv, acc[rb][cb]);
	v_mov_b32_e32 v17, v0
	v_mov_b32_e32 v18, v0
	v_mov_b32_e32 v19, v0
	v_mov_b32_e32 v20, v0
	v_mov_b32_e32 v21, v0
	v_mov_b32_e32 v22, v0
	v_mov_b32_e32 v23, v0
	v_mov_b32_e32 v24, v0
	v_mov_b32_e32 v25, v0
	v_mov_b32_e32 v26, v0
	v_mov_b32_e32 v27, v0
	v_mov_b32_e32 v28, v0
	v_mov_b32_e32 v29, v0
	v_mov_b32_e32 v30, v0
	v_mov_b32_e32 v31, v0
	v_mov_b32_e32 v48, v0
	v_mov_b32_e32 v49, v0
	v_mov_b32_e32 v50, v0
	v_mov_b32_e32 v51, v0
	v_mov_b32_e32 v52, v0
	v_mov_b32_e32 v53, v0
	v_mov_b32_e32 v54, v0
	v_mov_b32_e32 v55, v0
	v_mov_b32_e32 v56, v0
	v_mov_b32_e32 v57, v0
	v_mov_b32_e32 v58, v0
	v_mov_b32_e32 v59, v0
	v_mov_b32_e32 v60, v0
	v_mov_b32_e32 v61, v0
	v_mov_b32_e32 v62, v0
	v_mov_b32_e32 v63, v0
	v_mov_b32_e32 v80, v0
	v_mov_b32_e32 v81, v0
	v_mov_b32_e32 v82, v0
	v_mov_b32_e32 v83, v0
	v_mov_b32_e32 v84, v0
	v_mov_b32_e32 v85, v0
	v_mov_b32_e32 v86, v0
	v_mov_b32_e32 v87, v0
	v_mov_b32_e32 v88, v0
	v_mov_b32_e32 v89, v0
	v_mov_b32_e32 v90, v0
	v_mov_b32_e32 v91, v0
	v_mov_b32_e32 v92, v0
	v_mov_b32_e32 v93, v0
	v_mov_b32_e32 v94, v0
	v_mov_b32_e32 v95, v0
	v_mov_b32_e32 v112, v0
	v_mov_b32_e32 v113, v0
	v_mov_b32_e32 v114, v0
	v_mov_b32_e32 v115, v0
	v_mov_b32_e32 v116, v0
	v_mov_b32_e32 v117, v0
	v_mov_b32_e32 v118, v0
	v_mov_b32_e32 v119, v0
	v_mov_b32_e32 v120, v0
	v_mov_b32_e32 v121, v0
	v_mov_b32_e32 v122, v0
	v_mov_b32_e32 v123, v0
	v_mov_b32_e32 v124, v0
	v_mov_b32_e32 v125, v0
	v_mov_b32_e32 v126, v0
	v_mov_b32_e32 v127, v0
	v_mul_u32_u24_e32 v181, 0x90, v176
	v_add_u32_e32 v187, 0, v179
	s_waitcnt lgkmcnt(0)
	s_barrier
	v_add_u32_e32 v190, v187, v180
	v_add_u32_e32 v191, v187, v181
	v_lshl_add_u32 v196, v184, 1, v186
	v_lshl_add_u32 v197, v185, 1, v186
	v_lshl_add_u32 v249, v183, 1, v186
	v_lshl_add_u32 v250, v182, 1, v186
	v_add_u32_e32 v196, 0x12000, v196
	v_add_u32_e32 v197, 0x12000, v197
	v_add_u32_e32 v249, 0x12000, v249
	v_add_u32_e32 v250, 0x12000, v250
	s_mov_b32 s98, 0x1ff880
	s_mov_b32 s99, 0
	s_mov_b32 s100, 0xffe00780
	s_mov_b32 s101, -1
	s_movk_i32 s64, 7
.Lgn_loop:
	ds_read_b128 v[192:195], v190 offset:0
	ds_read_b128 v[220:223], v190 offset:4608
	ds_read_b128 v[232:235], v191 offset:36864
	ds_read_b128 v[236:239], v191 offset:41472
	ds_read_b128 v[240:243], v191 offset:46080
	ds_read_b128 v[244:247], v191 offset:50688
	ds_read_b128 v[224:227], v190 offset:32
	ds_read_b128 v[228:231], v190 offset:4640
	s_waitcnt lgkmcnt(5)
	v_mfma_f32_32x32x16_bf16 v[112:127], v[192:195], v[232:235], v[112:127]
	v_mfma_f32_32x32x16_bf16 v[96:111], v[220:223], v[232:235], v[96:111]
	ds_read_b128 v[232:235], v191 offset:36896
	s_waitcnt vmcnt(0)
	ds_write_b128 v196, v[152:155]
	s_waitcnt lgkmcnt(6)
	v_mfma_f32_32x32x16_bf16 v[80:95], v[192:195], v[236:239], v[80:95]
	v_mfma_f32_32x32x16_bf16 v[64:79], v[220:223], v[236:239], v[64:79]
	ds_read_b128 v[236:239], v191 offset:41504
	ds_write_b128 v196, v[136:139] offset:36864
	s_waitcnt lgkmcnt(7)
	v_mfma_f32_32x32x16_bf16 v[48:63], v[192:195], v[240:243], v[48:63]
	v_mfma_f32_32x32x16_bf16 v[32:47], v[220:223], v[240:243], v[32:47]
	ds_read_b128 v[240:243], v191 offset:46112
	ds_write_b128 v197, v[148:151]
	s_waitcnt lgkmcnt(8)
	v_mfma_f32_32x32x16_bf16 v[16:31], v[192:195], v[244:247], v[16:31]
	v_mfma_f32_32x32x16_bf16 v[0:15], v[220:223], v[244:247], v[0:15]
	ds_read_b128 v[244:247], v191 offset:50720
	ds_write_b128 v197, v[132:135] offset:36864
	ds_read_b128 v[192:195], v190 offset:64
	ds_read_b128 v[220:223], v190 offset:4672
	s_waitcnt lgkmcnt(9)
	v_mfma_f32_32x32x16_bf16 v[112:127], v[224:227], v[232:235], v[112:127]
	v_mfma_f32_32x32x16_bf16 v[96:111], v[228:231], v[232:235], v[96:111]
	ds_read_b128 v[232:235], v191 offset:36928
	ds_write_b128 v249, v[144:147]
	s_waitcnt lgkmcnt(9)
	v_mfma_f32_32x32x16_bf16 v[80:95], v[224:227], v[236:239], v[80:95]
	v_mfma_f32_32x32x16_bf16 v[64:79], v[228:231], v[236:239], v[64:79]
	ds_read_b128 v[236:239], v191 offset:41536
	ds_write_b128 v249, v[128:131] offset:36864
	s_waitcnt lgkmcnt(9)
	v_mfma_f32_32x32x16_bf16 v[48:63], v[224:227], v[240:243], v[48:63]
	v_mfma_f32_32x32x16_bf16 v[32:47], v[228:231], v[240:243], v[32:47]
	ds_read_b128 v[240:243], v191 offset:46144
	ds_write_b128 v250, v[140:143]
	s_waitcnt lgkmcnt(9)
	v_mfma_f32_32x32x16_bf16 v[16:31], v[224:227], v[244:247], v[16:31]
	v_mfma_f32_32x32x16_bf16 v[0:15], v[228:231], v[244:247], v[0:15]
	ds_read_b128 v[244:247], v191 offset:50752
	ds_write_b128 v250, v[156:159] offset:36864
	ds_read_b128 v[224:227], v190 offset:96
	ds_read_b128 v[228:231], v190 offset:4704
	s_waitcnt lgkmcnt(9)
	v_mfma_f32_32x32x16_bf16 v[112:127], v[192:195], v[232:235], v[112:127]
	v_mfma_f32_32x32x16_bf16 v[96:111], v[220:223], v[232:235], v[96:111]
	ds_read_b128 v[232:235], v191 offset:36960
	v_subrev_u32_e32 v196, 0x12000, v196
	global_load_dwordx4 v[152:155], v[174:175], off
	v_lshl_add_u64 v[174:175], v[174:175], 0, s[58:59]
	s_waitcnt lgkmcnt(8)
	v_mfma_f32_32x32x16_bf16 v[80:95], v[192:195], v[236:239], v[80:95]
	v_mfma_f32_32x32x16_bf16 v[64:79], v[220:223], v[236:239], v[64:79]
	ds_read_b128 v[236:239], v191 offset:41568
	v_subrev_u32_e32 v197, 0x12000, v197
	global_load_dwordx4 v[136:139], v[166:167], off
	v_lshl_add_u64 v[166:167], v[166:167], 0, s[58:59]
	s_waitcnt lgkmcnt(7)
	v_mfma_f32_32x32x16_bf16 v[48:63], v[192:195], v[240:243], v[48:63]
	v_mfma_f32_32x32x16_bf16 v[32:47], v[220:223], v[240:243], v[32:47]
	ds_read_b128 v[240:243], v191 offset:46176
	v_subrev_u32_e32 v249, 0x12000, v249
	global_load_dwordx4 v[148:151], v[172:173], off
	v_lshl_add_u64 v[172:173], v[172:173], 0, s[58:59]
	s_waitcnt lgkmcnt(6)
	v_mfma_f32_32x32x16_bf16 v[16:31], v[192:195], v[244:247], v[16:31]
	v_mfma_f32_32x32x16_bf16 v[0:15], v[220:223], v[244:247], v[0:15]
	ds_read_b128 v[244:247], v191 offset:50784
	v_subrev_u32_e32 v250, 0x12000, v250
	global_load_dwordx4 v[132:135], v[164:165], off
	v_lshl_add_u64 v[164:165], v[164:165], 0, s[58:59]
	v_add_u32_e32 v190, 0x12000, v190
	v_add_u32_e32 v191, 0x12000, v191
	s_waitcnt lgkmcnt(3)
	v_mfma_f32_32x32x16_bf16 v[112:127], v[224:227], v[232:235], v[112:127]
	v_mfma_f32_32x32x16_bf16 v[96:111], v[228:231], v[232:235], v[96:111]
	global_load_dwordx4 v[144:147], v[170:171], off
	v_lshl_add_u64 v[170:171], v[170:171], 0, s[58:59]
	s_waitcnt lgkmcnt(2)
	v_mfma_f32_32x32x16_bf16 v[80:95], v[224:227], v[236:239], v[80:95]
	v_mfma_f32_32x32x16_bf16 v[64:79], v[228:231], v[236:239], v[64:79]
	global_load_dwordx4 v[128:131], v[162:163], off
	v_lshl_add_u64 v[162:163], v[162:163], 0, s[58:59]
	s_waitcnt lgkmcnt(1)
	v_mfma_f32_32x32x16_bf16 v[48:63], v[224:227], v[240:243], v[48:63]
	v_mfma_f32_32x32x16_bf16 v[32:47], v[228:231], v[240:243], v[32:47]
	global_load_dwordx4 v[140:143], v[168:169], off
	v_lshl_add_u64 v[168:169], v[168:169], 0, s[58:59]
	s_waitcnt lgkmcnt(0)
	v_mfma_f32_32x32x16_bf16 v[16:31], v[224:227], v[244:247], v[16:31]
	v_mfma_f32_32x32x16_bf16 v[0:15], v[228:231], v[244:247], v[0:15]
	global_load_dwordx4 v[156:159], v[160:161], off
	v_lshl_add_u64 v[160:161], v[160:161], 0, s[58:59]
	s_waitcnt lgkmcnt(0)
	s_barrier
; template <bool AT>
; DI void gemm_main(f32x16 (&acc)[2][4], const u16* __restrict__ R, int ldr, const u16* __restrict__ Cm, int ldc,
;                   const u16* __restrict__ RT, int ldrt, int K, char* smem, int tid) {
;     ...
;   for (int kt = -1; kt < nk; ++kt) {
;     if (kt + 1 < nk) {
;       const int ks1 = kt + 1;
;       u16* Rs = S0 + (ks1 & 1) * STG;
;       u16* Cs = Rs + 256 * 72;
; #pragma unroll
;       for (int i = 0; i < 4; ++i) {
;         const int cid = tid + NT * i;
;         const int row = cid >> 3, kc = cid & 7;
;         if (AT && ks1 < 8) {
;           const int kr = cid >> 5, tc = cid & 31;
;           *(u32x4*)(Rs + kr * 264 + tc * 8) = rr[i];
;         } else {
;           *(u32x4*)(Rs + row * 72 + kc * 8) = rr[i];
;         }
;         *(u32x4*)(Cs + row * 72 + kc * 8) = cr[i];
;       }
;     }
;     if (kt + 2 < nk) {
;       const int kn = kt + 2;
; #pragma unroll
;       for (int i = 0; i < 4; ++i) {
;         const int cid = tid + NT * i;
;         const int row = cid >> 3, kc = cid & 7;
;         if (AT && kn < 8) {
;           const int kr = cid >> 5, tc = cid & 31;
;           rr[i] = *(const u32x4*)(RT + (size_t)(kn * 64 + kr) * ldrt + tc * 8);
;         } else {
;           rr[i] = *(const u32x4*)(R + (size_t)row * ldr + kn * 64 + kc * 8);
;         }
;         cr[i] = *(const u32x4*)(Cm + (size_t)row * ldc + kn * 64 + kc * 8);
;       }
;     }
;     __builtin_amdgcn_sched_barrier(0x38F);
;     if (kt >= 0) {
;       const u16* Rs = S0 + (kt & 1) * STG;
;       const u16* Cs = Rs + 256 * 72;
;       const u16* RTs = Rs;
; #pragma unroll
;       for (int ks = 0; ks < 4; ++ks) {
;         bf16x8 rf[2];
; #pragma unroll
;         for (int rb = 0; rb < 2; ++rb) {
;           if (AT && kt < 8) {
;             const u16* src = RTs + (16 * ks + 8 * g) * 264 + 64 * wr + 32 * rb + li;
;             bf16x8 t;
; #pragma unroll
;             for (int j = 0; j < 8; ++j) t[j] = (short)src[j * 264];
;             rf[rb] = t;
;           } else {
;             rf[rb] = *(const bf16x8*)(Rs + (64 * wr + 32 * rb + li) * 72 + 16 * ks + 8 * g);
;           }
;         }
; #pragma unroll
;         for (int cb = 0; cb < 4; ++cb) {
;           const bf16x8 cfv = *(const bf16x8*)(Cs + (128 * wc + 32 * cb + li) * 72 + 16 * ks + 8 * g);
; #pragma unroll
;           for (int rb = 0; rb < 2; ++rb) acc[rb][cb] = MFMA(rf[rb], cfv, acc[rb][cb]);
	ds_read_b128 v[192:195], v190 offset:0
	ds_read_b128 v[220:223], v190 offset:4608
	ds_read_b128 v[232:235], v191 offset:36864
	ds_read_b128 v[236:239], v191 offset:41472
	ds_read_b128 v[240:243], v191 offset:46080
	ds_read_b128 v[244:247], v191 offset:50688
	ds_read_b128 v[224:227], v190 offset:32
	ds_read_b128 v[228:231], v190 offset:4640
	s_waitcnt lgkmcnt(5)
	v_mfma_f32_32x32x16_bf16 v[112:127], v[192:195], v[232:235], v[112:127]
	v_mfma_f32_32x32x16_bf16 v[96:111], v[220:223], v[232:235], v[96:111]
	ds_read_b128 v[232:235], v191 offset:36896
	s_waitcnt vmcnt(0)
	ds_write_b128 v196, v[152:155]
	s_waitcnt lgkmcnt(6)
	v_mfma_f32_32x32x16_bf16 v[80:95], v[192:195], v[236:239], v[80:95]
	v_mfma_f32_32x32x16_bf16 v[64:79], v[220:223], v[236:239], v[64:79]
	ds_read_b128 v[236:239], v191 offset:41504
	ds_write_b128 v196, v[136:139] offset:36864
	s_waitcnt lgkmcnt(7)
	v_mfma_f32_32x32x16_bf16 v[48:63], v[192:195], v[240:243], v[48:63]
	v_mfma_f32_32x32x16_bf16 v[32:47], v[220:223], v[240:243], v[32:47]
	ds_read_b128 v[240:243], v191 offset:46112
	ds_write_b128 v197, v[148:151]
	s_waitcnt lgkmcnt(8)
	v_mfma_f32_32x32x16_bf16 v[16:31], v[192:195], v[244:247], v[16:31]
	v_mfma_f32_32x32x16_bf16 v[0:15], v[220:223], v[244:247], v[0:15]
	ds_read_b128 v[244:247], v191 offset:50720
	ds_write_b128 v197, v[132:135] offset:36864
	ds_read_b128 v[192:195], v190 offset:64
	ds_read_b128 v[220:223], v190 offset:4672
	s_waitcnt lgkmcnt(9)
	v_mfma_f32_32x32x16_bf16 v[112:127], v[224:227], v[232:235], v[112:127]
	v_mfma_f32_32x32x16_bf16 v[96:111], v[228:231], v[232:235], v[96:111]
	ds_read_b128 v[232:235], v191 offset:36928
	ds_write_b128 v249, v[144:147]
	s_cmp_eq_u32 s64, 1
	s_cbranch_scc0 .Lgn_nopf
	v_lshl_add_u64 v[174:175], v[174:175], 0, s[98:99]
	global_load_dword v251, v[174:175], off
	global_load_dword v251, v[174:175], off offset:128
	v_lshl_add_u64 v[174:175], v[174:175], 0, s[100:101]
	v_lshl_add_u64 v[172:173], v[172:173], 0, s[98:99]
	global_load_dword v251, v[172:173], off
	global_load_dword v251, v[172:173], off offset:128
	v_lshl_add_u64 v[172:173], v[172:173], 0, s[100:101]
	v_lshl_add_u64 v[170:171], v[170:171], 0, s[98:99]
	global_load_dword v251, v[170:171], off
	global_load_dword v251, v[170:171], off offset:128
	v_lshl_add_u64 v[170:171], v[170:171], 0, s[100:101]
	v_lshl_add_u64 v[168:169], v[168:169], 0, s[98:99]
	global_load_dword v251, v[168:169], off
	global_load_dword v251, v[168:169], off offset:128
	v_lshl_add_u64 v[168:169], v[168:169], 0, s[100:101]
.Lgn_nopf:
	s_waitcnt lgkmcnt(9)
	v_mfma_f32_32x32x16_bf16 v[80:95], v[224:227], v[236:239], v[80:95]
	v_mfma_f32_32x32x16_bf16 v[64:79], v[228:231], v[236:239], v[64:79]
	ds_read_b128 v[236:239], v191 offset:41536
	ds_write_b128 v249, v[128:131] offset:36864
	s_waitcnt lgkmcnt(9)
	v_mfma_f32_32x32x16_bf16 v[48:63], v[224:227], v[240:243], v[48:63]
	v_mfma_f32_32x32x16_bf16 v[32:47], v[228:231], v[240:243], v[32:47]
	ds_read_b128 v[240:243], v191 offset:46144
	ds_write_b128 v250, v[140:143]
	s_waitcnt lgkmcnt(9)
	v_mfma_f32_32x32x16_bf16 v[16:31], v[224:227], v[244:247], v[16:31]
	v_mfma_f32_32x32x16_bf16 v[0:15], v[228:231], v[244:247], v[0:15]
	ds_read_b128 v[244:247], v191 offset:50752
	ds_write_b128 v250, v[156:159] offset:36864
	ds_read_b128 v[224:227], v190 offset:96
	ds_read_b128 v[228:231], v190 offset:4704
	s_waitcnt lgkmcnt(9)
	v_mfma_f32_32x32x16_bf16 v[112:127], v[192:195], v[232:235], v[112:127]
	v_mfma_f32_32x32x16_bf16 v[96:111], v[220:223], v[232:235], v[96:111]
	ds_read_b128 v[232:235], v191 offset:36960
	v_add_u32_e32 v196, 0x12000, v196
	global_load_dwordx4 v[152:155], v[174:175], off
	v_lshl_add_u64 v[174:175], v[174:175], 0, s[58:59]
	s_waitcnt lgkmcnt(8)
	v_mfma_f32_32x32x16_bf16 v[80:95], v[192:195], v[236:239], v[80:95]
	v_mfma_f32_32x32x16_bf16 v[64:79], v[220:223], v[236:239], v[64:79]
	ds_read_b128 v[236:239], v191 offset:41568
	v_add_u32_e32 v197, 0x12000, v197
	global_load_dwordx4 v[136:139], v[166:167], off
	v_lshl_add_u64 v[166:167], v[166:167], 0, s[58:59]
	s_waitcnt lgkmcnt(7)
	v_mfma_f32_32x32x16_bf16 v[48:63], v[192:195], v[240:243], v[48:63]
	v_mfma_f32_32x32x16_bf16 v[32:47], v[220:223], v[240:243], v[32:47]
	ds_read_b128 v[240:243], v191 offset:46176
	v_add_u32_e32 v249, 0x12000, v249
	global_load_dwordx4 v[148:151], v[172:173], off
	v_lshl_add_u64 v[172:173], v[172:173], 0, s[58:59]
	s_waitcnt lgkmcnt(6)
	v_mfma_f32_32x32x16_bf16 v[16:31], v[192:195], v[244:247], v[16:31]
	v_mfma_f32_32x32x16_bf16 v[0:15], v[220:223], v[244:247], v[0:15]
	ds_read_b128 v[244:247], v191 offset:50784
	v_add_u32_e32 v250, 0x12000, v250
	global_load_dwordx4 v[132:135], v[164:165], off
	v_lshl_add_u64 v[164:165], v[164:165], 0, s[58:59]
	v_subrev_u32_e32 v190, 0x12000, v190
	v_subrev_u32_e32 v191, 0x12000, v191
	s_waitcnt lgkmcnt(3)
	v_mfma_f32_32x32x16_bf16 v[112:127], v[224:227], v[232:235], v[112:127]
	v_mfma_f32_32x32x16_bf16 v[96:111], v[228:231], v[232:235], v[96:111]
	global_load_dwordx4 v[144:147], v[170:171], off
	v_lshl_add_u64 v[170:171], v[170:171], 0, s[58:59]
	s_waitcnt lgkmcnt(2)
	v_mfma_f32_32x32x16_bf16 v[80:95], v[224:227], v[236:239], v[80:95]
	v_mfma_f32_32x32x16_bf16 v[64:79], v[228:231], v[236:239], v[64:79]
	global_load_dwordx4 v[128:131], v[162:163], off
	v_lshl_add_u64 v[162:163], v[162:163], 0, s[58:59]
	s_waitcnt lgkmcnt(1)
	v_mfma_f32_32x32x16_bf16 v[48:63], v[224:227], v[240:243], v[48:63]
	v_mfma_f32_32x32x16_bf16 v[32:47], v[228:231], v[240:243], v[32:47]
	global_load_dwordx4 v[140:143], v[168:169], off
	v_lshl_add_u64 v[168:169], v[168:169], 0, s[58:59]
	s_waitcnt lgkmcnt(0)
	v_mfma_f32_32x32x16_bf16 v[16:31], v[224:227], v[244:247], v[16:31]
	v_mfma_f32_32x32x16_bf16 v[0:15], v[228:231], v[244:247], v[0:15]
	global_load_dwordx4 v[156:159], v[160:161], off
	v_lshl_add_u64 v[160:161], v[160:161], 0, s[58:59]
	s_waitcnt lgkmcnt(0)
	s_barrier
; template <bool AT>
; DI void gemm_main(f32x16 (&acc)[2][4], const u16* __restrict__ R, int ldr, const u16* __restrict__ Cm, int ldc,
;                   const u16* __restrict__ RT, int ldrt, int K, char* smem, int tid) {
;     ...
;   for (int kt = -1; kt < nk; ++kt) {
;     if (kt + 1 < nk) {
;       const int ks1 = kt + 1;
;       u16* Rs = S0 + (ks1 & 1) * STG;
;       u16* Cs = Rs + 256 * 72;
; #pragma unroll
;       for (int i = 0; i < 4; ++i) {
;         const int cid = tid + NT * i;
;         const int row = cid >> 3, kc = cid & 7;
;         if (AT && ks1 < 8) {
;           const int kr = cid >> 5, tc = cid & 31;
;           *(u32x4*)(Rs + kr * 264 + tc * 8) = rr[i];
;         } else {
;           *(u32x4*)(Rs + row * 72 + kc * 8) = rr[i];
;         }
;         *(u32x4*)(Cs + row * 72 + kc * 8) = cr[i];
;       }
;     }
;     if (kt + 2 < nk) {
;       const int kn = kt + 2;
; #pragma unroll
;       for (int i = 0; i < 4; ++i) {
;         const int cid = tid + NT * i;
;         const int row = cid >> 3, kc = cid & 7;
;         if (AT && kn < 8) {
;           const int kr = cid >> 5, tc = cid & 31;
;           rr[i] = *(const u32x4*)(RT + (size_t)(kn * 64 + kr) * ldrt + tc * 8);
;         } else {
;           rr[i] = *(const u32x4*)(R + (size_t)row * ldr + kn * 64 + kc * 8);
;         }
;         cr[i] = *(const u32x4*)(Cm + (size_t)row * ldc + kn * 64 + kc * 8);
;       }
;     }
;     __builtin_amdgcn_sched_barrier(0x38F);
;     if (kt >= 0) {
;       const u16* Rs = S0 + (kt & 1) * STG;
;       const u16* Cs = Rs + 256 * 72;
;       const u16* RTs = Rs;
; #pragma unroll
;       for (int ks = 0; ks < 4; ++ks) {
;         bf16x8 rf[2];
; #pragma unroll
;         for (int rb = 0; rb < 2; ++rb) {
;           if (AT && kt < 8) {
;             const u16* src = RTs + (16 * ks + 8 * g) * 264 + 64 * wr + 32 * rb + li;
;             bf16x8 t;
; #pragma unroll
;             for (int j = 0; j < 8; ++j) t[j] = (short)src[j * 264];
;             rf[rb] = t;
;           } else {
;             rf[rb] = *(const bf16x8*)(Rs + (64 * wr + 32 * rb + li) * 72 + 16 * ks + 8 * g);
;           }
;         }
; #pragma unroll
;         for (int cb = 0; cb < 4; ++cb) {
;           const bf16x8 cfv = *(const bf16x8*)(Cs + (128 * wc + 32 * cb + li) * 72 + 16 * ks + 8 * g);
; #pragma unroll
;           for (int rb = 0; rb < 2; ++rb) acc[rb][cb] = MFMA(rf[rb], cfv, acc[rb][cb]);
	s_add_i32 s64, s64, -1
	s_cmp_lg_u32 s64, 0
	s_cbranch_scc1 .Lgn_loop
	s_add_i32 s9, 0, 0x12000
	v_add_u32_e32 v160, s9, v188
	v_lshlrev_b32_e32 v162, 1, v184
	v_add_u32_e32 v161, s90, v188
	v_add_u32_e32 v163, v160, v162
	s_waitcnt vmcnt(7)
	ds_write_b128 v163, v[152:155]
	v_add_u32_e32 v152, v161, v162
	s_waitcnt vmcnt(6)
	ds_write_b128 v152, v[136:139]
	v_lshlrev_b32_e32 v136, 1, v185
	v_add_u32_e32 v137, v160, v136
	v_add_u32_e32 v136, v161, v136
	s_waitcnt vmcnt(4)
	ds_write_b128 v136, v[132:135]
	v_lshlrev_b32_e32 v132, 1, v183
	v_add_u32_e32 v133, v160, v132
	v_add_u32_e32 v132, v161, v132
	ds_write_b128 v137, v[148:151]
	s_waitcnt vmcnt(2)
	ds_write_b128 v132, v[128:131]
	v_lshlrev_b32_e32 v128, 1, v182
	v_add_u32_e32 v129, v160, v128
	v_add_u32_e32 v128, v161, v128
	ds_write_b128 v133, v[144:147]
	s_waitcnt vmcnt(1)
	ds_write_b128 v129, v[140:143]
	s_waitcnt vmcnt(0)
	ds_write_b128 v128, v[156:159]
	v_add_u32_e32 v148, v187, v180
	ds_read_b128 v[128:131], v148 offset:4608
	v_add_u32_e32 v149, v187, v181
	ds_read_b128 v[132:135], v148
	ds_read_b128 v[136:139], v148 offset:32
	ds_read_b128 v[140:143], v149 offset:36864
	ds_read_b128 v[144:147], v149 offset:36896
	s_waitcnt lgkmcnt(1)
	v_mfma_f32_32x32x16_bf16 v[112:127], v[132:135], v[140:143], v[112:127]
	v_mov_b32_e32 v162, s56
	v_mfma_f32_32x32x16_bf16 v[96:111], v[128:131], v[140:143], v[96:111]
	ds_read_b128 v[140:143], v149 offset:41472
	s_waitcnt lgkmcnt(0)
	v_mfma_f32_32x32x16_bf16 v[80:95], v[132:135], v[140:143], v[80:95]
	v_mfma_f32_32x32x16_bf16 v[64:79], v[128:131], v[140:143], v[64:79]
	ds_read_b128 v[140:143], v149 offset:46080
	s_waitcnt lgkmcnt(0)
	v_mfma_f32_32x32x16_bf16 v[48:63], v[132:135], v[140:143], v[48:63]
	v_mfma_f32_32x32x16_bf16 v[32:47], v[128:131], v[140:143], v[32:47]
	ds_read_b128 v[140:143], v149 offset:50688
	s_waitcnt lgkmcnt(0)
	v_mfma_f32_32x32x16_bf16 v[0:15], v[128:131], v[140:143], v[0:15]
	ds_read_b128 v[128:131], v148 offset:4640
	v_mfma_f32_32x32x16_bf16 v[16:31], v[132:135], v[140:143], v[16:31]
	ds_read_b128 v[132:135], v149 offset:41504
	s_waitcnt lgkmcnt(0)
	v_mfma_f32_32x32x16_bf16 v[80:95], v[136:139], v[132:135], v[80:95]
	v_mfma_f32_32x32x16_bf16 v[64:79], v[128:131], v[132:135], v[64:79]
	ds_read_b128 v[132:135], v149 offset:46112
	s_waitcnt lgkmcnt(0)
	v_mfma_f32_32x32x16_bf16 v[48:63], v[136:139], v[132:135], v[48:63]
	v_mfma_f32_32x32x16_bf16 v[32:47], v[128:131], v[132:135], v[32:47]
	ds_read_b128 v[132:135], v149 offset:50720
	v_mfma_f32_32x32x16_bf16 v[112:127], v[136:139], v[144:147], v[112:127]
	v_mfma_f32_32x32x16_bf16 v[96:111], v[128:131], v[144:147], v[96:111]
	s_waitcnt lgkmcnt(0)
	v_mfma_f32_32x32x16_bf16 v[16:31], v[136:139], v[132:135], v[16:31]
	v_mfma_f32_32x32x16_bf16 v[0:15], v[128:131], v[132:135], v[0:15]
	ds_read_b128 v[128:131], v148 offset:64
	ds_read_b128 v[132:135], v148 offset:4672
	ds_read_b128 v[136:139], v149 offset:36928
	s_waitcnt lgkmcnt(0)
	v_mfma_f32_32x32x16_bf16 v[112:127], v[128:131], v[136:139], v[112:127]
	v_mfma_f32_32x32x16_bf16 v[96:111], v[132:135], v[136:139], v[96:111]
	ds_read_b128 v[136:139], v149 offset:41536
	s_waitcnt lgkmcnt(0)
	v_mfma_f32_32x32x16_bf16 v[80:95], v[128:131], v[136:139], v[80:95]
	v_mfma_f32_32x32x16_bf16 v[64:79], v[132:135], v[136:139], v[64:79]
	ds_read_b128 v[136:139], v149 offset:46144
	s_waitcnt lgkmcnt(0)
	v_mfma_f32_32x32x16_bf16 v[48:63], v[128:131], v[136:139], v[48:63]
	v_mfma_f32_32x32x16_bf16 v[32:47], v[132:135], v[136:139], v[32:47]
	ds_read_b128 v[136:139], v149 offset:50752
	s_waitcnt lgkmcnt(0)
	v_mfma_f32_32x32x16_bf16 v[16:31], v[128:131], v[136:139], v[16:31]
	v_mfma_f32_32x32x16_bf16 v[0:15], v[132:135], v[136:139], v[0:15]
	ds_read_b128 v[128:131], v148 offset:96
	ds_read_b128 v[132:135], v148 offset:4704
	ds_read_b128 v[136:139], v149 offset:36960
	v_add3_u32 v148, s9, v179, v180
	s_lshl_b32 s9, s75, 4
	s_and_b32 s9, s9, 0x200
	s_add_i32 s9, s8, s9
	s_addk_i32 s9, 0xf400
	s_waitcnt lgkmcnt(0)
	v_mfma_f32_32x32x16_bf16 v[112:127], v[128:131], v[136:139], v[112:127]
	v_mfma_f32_32x32x16_bf16 v[96:111], v[132:135], v[136:139], v[96:111]
	ds_read_b128 v[136:139], v149 offset:41568
	s_waitcnt lgkmcnt(0)
	v_mfma_f32_32x32x16_bf16 v[80:95], v[128:131], v[136:139], v[80:95]
	v_mfma_f32_32x32x16_bf16 v[64:79], v[132:135], v[136:139], v[64:79]
	ds_read_b128 v[136:139], v149 offset:46176
	s_waitcnt lgkmcnt(0)
	v_mfma_f32_32x32x16_bf16 v[48:63], v[128:131], v[136:139], v[48:63]
	v_mfma_f32_32x32x16_bf16 v[32:47], v[132:135], v[136:139], v[32:47]
	ds_read_b128 v[136:139], v149 offset:50784
	s_waitcnt lgkmcnt(0)
	s_barrier
; #define MFMA(a, b, c) __builtin_amdgcn_mfma_f32_32x32x16_bf16((a), (b), (c), 0, 0, 0)
; template <bool AT>
; DI void gemm_main(f32x16 (&acc)[2][4], const u16* __restrict__ R, int ldr, const u16* __restrict__ Cm, int ldc,
;                   const u16* __restrict__ RT, int ldrt, int K, char* smem, int tid) {
;     ...
;       for (int ks = 0; ks < 4; ++ks) {
;         bf16x8 rf[2];
; #pragma unroll
;         for (int rb = 0; rb < 2; ++rb) {
;           if (AT && kt < 8) {
;             const u16* src = RTs + (16 * ks + 8 * g) * 264 + 64 * wr + 32 * rb + li;
;             bf16x8 t;
; #pragma unroll
;             for (int j = 0; j < 8; ++j) t[j] = (short)src[j * 264];
;             rf[rb] = t;
;           } else {
;             rf[rb] = *(const bf16x8*)(Rs + (64 * wr + 32 * rb + li) * 72 + 16 * ks + 8 * g);
;           }
;         }
; #pragma unroll
;         for (int cb = 0; cb < 4; ++cb) {
;           const bf16x8 cfv = *(const bf16x8*)(Cs + (128 * wc + 32 * cb + li) * 72 + 16 * ks + 8 * g);
; #pragma unroll
;           for (int rb = 0; rb < 2; ++rb) acc[rb][cb] = MFMA(rf[rb], cfv, acc[rb][cb]);
;         }
; template <bool TR>
; DI void gemm_in_tile(const P& p, int l, int id, char* smem) {
;     ...
;   if (tr) {
;     const bool hy = nt < 8;
; #pragma unroll
;     for (int cb = 0; cb < 4; ++cb) {
;       asm volatile("" ::: "memory");
;       const int tl = 128 * wc + 32 * cb + li;
;       const int tok = m0 + tl;
;       const float rs = rs_s[tl];
;       u16* dst = hy ? (p.hyT + (size_t)(n0 + 64 * wr) * HYP + tok)
;                     : (p.VT + (size_t)((tok >> 13) * 512 + (n0 - 3072) + 64 * wr) * VTP + (tok & 8191));
;       const size_t cstride = hy ? (size_t)HYP : (size_t)VTP;
	v_add3_u32 v149, s90, v179, v181
	v_mfma_f32_32x32x16_bf16 v[16:31], v[128:131], v[136:139], v[16:31]
	ds_read_b128 v[128:131], v148 offset:4608
	v_mfma_f32_32x32x16_bf16 v[0:15], v[132:135], v[136:139], v[0:15]
	ds_read_b128 v[132:135], v148
	ds_read_b128 v[136:139], v148 offset:32
	ds_read_b128 v[140:143], v149
	ds_read_b128 v[144:147], v149 offset:32
	s_waitcnt lgkmcnt(1)
	v_mfma_f32_32x32x16_bf16 v[112:127], v[132:135], v[140:143], v[112:127]
	v_mfma_f32_32x32x16_bf16 v[96:111], v[128:131], v[140:143], v[96:111]
	ds_read_b128 v[140:143], v149 offset:4608
	s_waitcnt lgkmcnt(0)
	v_mfma_f32_32x32x16_bf16 v[80:95], v[132:135], v[140:143], v[80:95]
	v_mfma_f32_32x32x16_bf16 v[64:79], v[128:131], v[140:143], v[64:79]
	ds_read_b128 v[140:143], v149 offset:9216
	s_waitcnt lgkmcnt(0)
	v_mfma_f32_32x32x16_bf16 v[48:63], v[132:135], v[140:143], v[48:63]
	v_mfma_f32_32x32x16_bf16 v[32:47], v[128:131], v[140:143], v[32:47]
	ds_read_b128 v[140:143], v149 offset:13824
	s_waitcnt lgkmcnt(0)
	v_mfma_f32_32x32x16_bf16 v[0:15], v[128:131], v[140:143], v[0:15]
	ds_read_b128 v[128:131], v148 offset:4640
	v_mfma_f32_32x32x16_bf16 v[16:31], v[132:135], v[140:143], v[16:31]
	ds_read_b128 v[132:135], v149 offset:4640
	s_waitcnt lgkmcnt(0)
	v_mfma_f32_32x32x16_bf16 v[80:95], v[136:139], v[132:135], v[80:95]
	v_mfma_f32_32x32x16_bf16 v[64:79], v[128:131], v[132:135], v[64:79]
	ds_read_b128 v[132:135], v149 offset:9248
	s_waitcnt lgkmcnt(0)
	v_mfma_f32_32x32x16_bf16 v[48:63], v[136:139], v[132:135], v[48:63]
	v_mfma_f32_32x32x16_bf16 v[32:47], v[128:131], v[132:135], v[32:47]
	ds_read_b128 v[132:135], v149 offset:13856
	v_mfma_f32_32x32x16_bf16 v[112:127], v[136:139], v[144:147], v[112:127]
	v_mfma_f32_32x32x16_bf16 v[96:111], v[128:131], v[144:147], v[96:111]
	s_waitcnt lgkmcnt(0)
	v_mfma_f32_32x32x16_bf16 v[16:31], v[136:139], v[132:135], v[16:31]
	v_mfma_f32_32x32x16_bf16 v[0:15], v[128:131], v[132:135], v[0:15]
	ds_read_b128 v[128:131], v148 offset:64
	ds_read_b128 v[132:135], v148 offset:4672
	ds_read_b128 v[136:139], v149 offset:64
	s_waitcnt lgkmcnt(0)
	v_mfma_f32_32x32x16_bf16 v[112:127], v[128:131], v[136:139], v[112:127]
	v_mfma_f32_32x32x16_bf16 v[96:111], v[132:135], v[136:139], v[96:111]
	ds_read_b128 v[136:139], v149 offset:4672
	s_waitcnt lgkmcnt(0)
	v_mfma_f32_32x32x16_bf16 v[80:95], v[128:131], v[136:139], v[80:95]
	v_mfma_f32_32x32x16_bf16 v[64:79], v[132:135], v[136:139], v[64:79]
	ds_read_b128 v[136:139], v149 offset:9280
	s_waitcnt lgkmcnt(0)
	v_mfma_f32_32x32x16_bf16 v[48:63], v[128:131], v[136:139], v[48:63]
	v_mfma_f32_32x32x16_bf16 v[32:47], v[132:135], v[136:139], v[32:47]
	ds_read_b128 v[136:139], v149 offset:13888
	s_waitcnt lgkmcnt(0)
	v_mfma_f32_32x32x16_bf16 v[16:31], v[128:131], v[136:139], v[16:31]
	v_mfma_f32_32x32x16_bf16 v[0:15], v[132:135], v[136:139], v[0:15]
	ds_read_b128 v[128:131], v148 offset:96
	ds_read_b128 v[132:135], v148 offset:4704
	ds_read_b128 v[136:139], v149 offset:96
	s_waitcnt lgkmcnt(0)
	v_mfma_f32_32x32x16_bf16 v[112:127], v[128:131], v[136:139], v[112:127]
	v_mfma_f32_32x32x16_bf16 v[96:111], v[132:135], v[136:139], v[96:111]
	ds_read_b128 v[136:139], v149 offset:4704
	s_waitcnt lgkmcnt(0)
	v_mfma_f32_32x32x16_bf16 v[80:95], v[128:131], v[136:139], v[80:95]
	v_mfma_f32_32x32x16_bf16 v[64:79], v[132:135], v[136:139], v[64:79]
	ds_read_b128 v[136:139], v149 offset:9312
	s_waitcnt lgkmcnt(0)
	v_mfma_f32_32x32x16_bf16 v[48:63], v[128:131], v[136:139], v[48:63]
	v_mfma_f32_32x32x16_bf16 v[32:47], v[132:135], v[136:139], v[32:47]
	ds_read_b128 v[136:139], v149 offset:13920
	s_waitcnt lgkmcnt(0)
	s_barrier
	v_mfma_f32_32x32x16_bf16 v[16:31], v[128:131], v[136:139], v[16:31]
	v_lshrrev_b32_e32 v128, 3, v177
	v_and_b32_e32 v163, 4, v128
	v_add_u32_e32 v130, s9, v178
	s_movk_i32 s9, 0x4080
	v_mfma_f32_32x32x16_bf16 v[0:15], v[132:135], v[136:139], v[0:15]
	v_add_u32_e32 v132, s8, v178
	s_add_i32 s8, 0, 0x24000
	v_lshl_add_u32 v128, v176, 2, s8
	ds_read_b32 v164, v128
	v_mov_b64_e32 v[128:129], s[28:29]
	v_mad_i64_i32 v[128:129], s[10:11], v130, s9, v[128:129]
	s_movk_i32 s9, 0x1f9f
	v_or_b32_e32 v133, s56, v176
	v_bitop3_b32 v134, v176, s9, v162 bitop3:0xc8
	v_mov_b64_e32 v[130:131], s[38:39]
	s_and_b64 s[10:11], s[6:7], exec
	s_movk_i32 s9, 0x4040
	v_mad_i64_i32 v[130:131], s[10:11], v132, s67, v[130:131]
	v_cndmask_b32_e64 v132, v134, v133, s[6:7]
	s_cselect_b32 s9, s9, 0x2040
	v_cndmask_b32_e64 v129, v129, v131, s[6:7]
	v_cndmask_b32_e64 v128, v128, v130, s[6:7]
	v_lshlrev_b32_e32 v188, 1, v132
	v_mul_u32_u24_e32 v130, s9, v163
	v_lshl_add_u64 v[138:139], v[128:129], 0, v[188:189]
	s_waitcnt lgkmcnt(0)
; DI u16 f2bf(float a) { return (u16)(pack2(a, 0.f) & 0xffffu); }
; DI int crow(int reg, int g) { return (reg & 3) + 8 * (reg >> 2) + 4 * g; }
; template <bool TR>
; DI void gemm_in_tile(const P& p, int l, int id, char* smem) {
;     ...
; #pragma unroll
;       for (int rb = 0; rb < 2; ++rb) {
; #pragma unroll
;         for (int reg = 0; reg < 16; ++reg) {
;           const int cl = 32 * rb + crow(reg, g);
;           dst[(size_t)cl * cstride] = f2bf(acc[rb][cb][reg] * rs);
;         }
;       }
	v_mul_f32_e32 v112, v112, v164
	v_lshlrev_b32_e32 v188, 1, v130
	v_cvt_pk_bf16_f32 v112, v112, s0
	v_lshl_add_u64 v[130:131], v[138:139], 0, v[188:189]
	global_store_short v[130:131], v112, off
	v_or_b32_e32 v112, 1, v163
	v_mul_f32_e32 v113, v113, v164
	v_mul_u32_u24_e32 v112, s9, v112
	v_cvt_pk_bf16_f32 v132, v113, s0
	v_lshlrev_b32_e32 v112, 1, v112
	v_mov_b32_e32 v113, v189
	v_lshl_add_u64 v[130:131], v[138:139], 0, v[112:113]
	global_store_short v[130:131], v132, off
	v_or_b32_e32 v130, 2, v163
	v_mul_u32_u24_e32 v130, s9, v130
	v_mul_f32_e32 v114, v114, v164
	v_lshlrev_b32_e32 v130, 1, v130
	v_mov_b32_e32 v131, v189
	v_cvt_pk_bf16_f32 v114, v114, s0
	v_lshl_add_u64 v[132:133], v[138:139], 0, v[130:131]
	global_store_short v[132:133], v114, off
	v_or_b32_e32 v114, 3, v163
	v_mul_f32_e32 v115, v115, v164
	v_mul_u32_u24_e32 v114, s9, v114
	v_cvt_pk_bf16_f32 v134, v115, s0
	v_lshlrev_b32_e32 v114, 1, v114
	v_mov_b32_e32 v115, v189
	v_lshl_add_u64 v[132:133], v[138:139], 0, v[114:115]
	global_store_short v[132:133], v134, off
	v_or_b32_e32 v132, 8, v163
	v_mul_u32_u24_e32 v132, s9, v132
	v_mul_f32_e32 v116, v116, v164
	v_lshlrev_b32_e32 v132, 1, v132
	v_mov_b32_e32 v133, v189
	v_cvt_pk_bf16_f32 v116, v116, s0
	v_lshl_add_u64 v[134:135], v[138:139], 0, v[132:133]
	global_store_short v[134:135], v116, off
	v_or_b32_e32 v116, 9, v163
	v_mul_f32_e32 v117, v117, v164
	v_mul_u32_u24_e32 v116, s9, v116
	v_cvt_pk_bf16_f32 v136, v117, s0
	v_lshlrev_b32_e32 v116, 1, v116
	v_mov_b32_e32 v117, v189
	v_lshl_add_u64 v[134:135], v[138:139], 0, v[116:117]
	global_store_short v[134:135], v136, off
	v_or_b32_e32 v134, 10, v163
	v_mul_u32_u24_e32 v134, s9, v134
	v_mul_f32_e32 v118, v118, v164
	v_lshlrev_b32_e32 v134, 1, v134
	v_mov_b32_e32 v135, v189
	v_cvt_pk_bf16_f32 v118, v118, s0
	v_lshl_add_u64 v[136:137], v[138:139], 0, v[134:135]
	global_store_short v[136:137], v118, off
	v_or_b32_e32 v118, 11, v163
	v_mul_f32_e32 v119, v119, v164
	v_mul_u32_u24_e32 v118, s9, v118
	v_cvt_pk_bf16_f32 v140, v119, s0
	v_lshlrev_b32_e32 v118, 1, v118
	v_mov_b32_e32 v119, v189
	v_lshl_add_u64 v[136:137], v[138:139], 0, v[118:119]
	global_store_short v[136:137], v140, off
	v_or_b32_e32 v136, 16, v163
	v_mul_u32_u24_e32 v136, s9, v136
	v_mul_f32_e32 v120, v120, v164
	v_lshlrev_b32_e32 v136, 1, v136
	v_mov_b32_e32 v137, v189
	v_cvt_pk_bf16_f32 v120, v120, s0
	v_lshl_add_u64 v[140:141], v[138:139], 0, v[136:137]
	global_store_short v[140:141], v120, off
	v_or_b32_e32 v120, 17, v163
	v_mul_f32_e32 v121, v121, v164
	v_mul_u32_u24_e32 v120, s9, v120
	v_cvt_pk_bf16_f32 v142, v121, s0
	v_lshlrev_b32_e32 v120, 1, v120
	v_mov_b32_e32 v121, v189
	v_lshl_add_u64 v[140:141], v[138:139], 0, v[120:121]
	global_store_short v[140:141], v142, off
	v_or_b32_e32 v140, 18, v163
	v_mul_u32_u24_e32 v140, s9, v140
	v_mul_f32_e32 v122, v122, v164
	v_lshlrev_b32_e32 v140, 1, v140
	v_mov_b32_e32 v141, v189
	v_cvt_pk_bf16_f32 v122, v122, s0
	v_lshl_add_u64 v[142:143], v[138:139], 0, v[140:141]
	global_store_short v[142:143], v122, off
	v_or_b32_e32 v122, 19, v163
	v_mul_f32_e32 v123, v123, v164
	v_mul_u32_u24_e32 v122, s9, v122
	v_cvt_pk_bf16_f32 v144, v123, s0
	v_lshlrev_b32_e32 v122, 1, v122
	v_mov_b32_e32 v123, v189
	v_lshl_add_u64 v[142:143], v[138:139], 0, v[122:123]
	global_store_short v[142:143], v144, off
	v_or_b32_e32 v142, 24, v163
	v_mul_u32_u24_e32 v142, s9, v142
	v_mul_f32_e32 v124, v124, v164
	v_lshlrev_b32_e32 v142, 1, v142
	v_mov_b32_e32 v143, v189
	v_cvt_pk_bf16_f32 v124, v124, s0
	v_lshl_add_u64 v[144:145], v[138:139], 0, v[142:143]
	global_store_short v[144:145], v124, off
	v_or_b32_e32 v124, 25, v163
	v_mul_f32_e32 v125, v125, v164
	v_mul_u32_u24_e32 v124, s9, v124
	v_cvt_pk_bf16_f32 v146, v125, s0
	v_lshlrev_b32_e32 v124, 1, v124
	v_mov_b32_e32 v125, v189
	v_lshl_add_u64 v[144:145], v[138:139], 0, v[124:125]
	global_store_short v[144:145], v146, off
	v_or_b32_e32 v144, 26, v163
	v_mul_u32_u24_e32 v144, s9, v144
	v_mul_f32_e32 v126, v126, v164
	v_lshlrev_b32_e32 v144, 1, v144
	v_mov_b32_e32 v145, v189
	v_cvt_pk_bf16_f32 v126, v126, s0
	v_lshl_add_u64 v[146:147], v[138:139], 0, v[144:145]
	global_store_short v[146:147], v126, off
	v_or_b32_e32 v126, 27, v163
	v_mul_f32_e32 v127, v127, v164
	v_mul_u32_u24_e32 v126, s9, v126
	v_cvt_pk_bf16_f32 v148, v127, s0
	v_lshlrev_b32_e32 v126, 1, v126
	v_mov_b32_e32 v127, v189
	v_lshl_add_u64 v[146:147], v[138:139], 0, v[126:127]
	global_store_short v[146:147], v148, off
	v_or_b32_e32 v146, 32, v163
	v_mul_u32_u24_e32 v146, s9, v146
	v_mul_f32_e32 v96, v96, v164
	v_lshlrev_b32_e32 v146, 1, v146
	v_mov_b32_e32 v147, v189
	v_cvt_pk_bf16_f32 v96, v96, s0
	v_lshl_add_u64 v[148:149], v[138:139], 0, v[146:147]
	global_store_short v[148:149], v96, off
	v_or_b32_e32 v96, 33, v163
	v_mul_f32_e32 v97, v97, v164
	v_mul_u32_u24_e32 v96, s9, v96
	v_cvt_pk_bf16_f32 v150, v97, s0
	v_lshlrev_b32_e32 v96, 1, v96
	v_mov_b32_e32 v97, v189
	v_lshl_add_u64 v[148:149], v[138:139], 0, v[96:97]
	global_store_short v[148:149], v150, off
	v_or_b32_e32 v148, 34, v163
	v_mul_u32_u24_e32 v148, s9, v148
	v_mul_f32_e32 v98, v98, v164
	v_lshlrev_b32_e32 v148, 1, v148
	v_mov_b32_e32 v149, v189
	v_cvt_pk_bf16_f32 v98, v98, s0
	v_lshl_add_u64 v[150:151], v[138:139], 0, v[148:149]
	global_store_short v[150:151], v98, off
	v_or_b32_e32 v98, 35, v163
	v_mul_f32_e32 v99, v99, v164
	v_mul_u32_u24_e32 v98, s9, v98
	v_cvt_pk_bf16_f32 v152, v99, s0
	v_lshlrev_b32_e32 v98, 1, v98
	v_mov_b32_e32 v99, v189
	v_lshl_add_u64 v[150:151], v[138:139], 0, v[98:99]
	global_store_short v[150:151], v152, off
	v_or_b32_e32 v150, 40, v163
	v_mul_u32_u24_e32 v150, s9, v150
	v_mul_f32_e32 v100, v100, v164
; DI u16 f2bf(float a) { return (u16)(pack2(a, 0.f) & 0xffffu); }
; DI int crow(int reg, int g) { return (reg & 3) + 8 * (reg >> 2) + 4 * g; }
; template <bool TR>
; DI void gemm_in_tile(const P& p, int l, int id, char* smem) {
;     ...
;     for (int cb = 0; cb < 4; ++cb) {
;       asm volatile("" ::: "memory");
;       const int tl = 128 * wc + 32 * cb + li;
;       const int tok = m0 + tl;
;       const float rs = rs_s[tl];
;       u16* dst = hy ? (p.hyT + (size_t)(n0 + 64 * wr) * HYP + tok)
;                     : (p.VT + (size_t)((tok >> 13) * 512 + (n0 - 3072) + 64 * wr) * VTP + (tok & 8191));
;       const size_t cstride = hy ? (size_t)HYP : (size_t)VTP;
; #pragma unroll
;       for (int rb = 0; rb < 2; ++rb) {
; #pragma unroll
;         for (int reg = 0; reg < 16; ++reg) {
;           const int cl = 32 * rb + crow(reg, g);
;           dst[(size_t)cl * cstride] = f2bf(acc[rb][cb][reg] * rs);
;         }
;       }
	v_lshlrev_b32_e32 v150, 1, v150
	v_mov_b32_e32 v151, v189
	v_cvt_pk_bf16_f32 v100, v100, s0
	v_lshl_add_u64 v[152:153], v[138:139], 0, v[150:151]
	global_store_short v[152:153], v100, off
	v_or_b32_e32 v100, 41, v163
	v_mul_f32_e32 v101, v101, v164
	v_mul_u32_u24_e32 v100, s9, v100
	v_cvt_pk_bf16_f32 v154, v101, s0
	v_lshlrev_b32_e32 v100, 1, v100
	v_mov_b32_e32 v101, v189
	v_lshl_add_u64 v[152:153], v[138:139], 0, v[100:101]
	global_store_short v[152:153], v154, off
	v_or_b32_e32 v152, 42, v163
	v_mul_u32_u24_e32 v152, s9, v152
	v_mul_f32_e32 v102, v102, v164
	v_lshlrev_b32_e32 v152, 1, v152
	v_mov_b32_e32 v153, v189
	v_cvt_pk_bf16_f32 v102, v102, s0
	v_lshl_add_u64 v[154:155], v[138:139], 0, v[152:153]
	global_store_short v[154:155], v102, off
	v_or_b32_e32 v102, 43, v163
	v_mul_f32_e32 v103, v103, v164
	v_mul_u32_u24_e32 v102, s9, v102
	v_cvt_pk_bf16_f32 v156, v103, s0
	v_lshlrev_b32_e32 v102, 1, v102
	v_mov_b32_e32 v103, v189
	v_lshl_add_u64 v[154:155], v[138:139], 0, v[102:103]
	global_store_short v[154:155], v156, off
	v_or_b32_e32 v154, 48, v163
	v_mul_u32_u24_e32 v154, s9, v154
	v_mul_f32_e32 v104, v104, v164
	v_lshlrev_b32_e32 v154, 1, v154
	v_mov_b32_e32 v155, v189
	v_cvt_pk_bf16_f32 v104, v104, s0
	v_lshl_add_u64 v[156:157], v[138:139], 0, v[154:155]
	global_store_short v[156:157], v104, off
	v_or_b32_e32 v104, 49, v163
	v_mul_f32_e32 v105, v105, v164
	v_mul_u32_u24_e32 v104, s9, v104
	v_cvt_pk_bf16_f32 v158, v105, s0
	v_lshlrev_b32_e32 v104, 1, v104
	v_mov_b32_e32 v105, v189
	v_lshl_add_u64 v[156:157], v[138:139], 0, v[104:105]
	global_store_short v[156:157], v158, off
	v_or_b32_e32 v156, 50, v163
	v_mul_u32_u24_e32 v156, s9, v156
	v_mul_f32_e32 v106, v106, v164
	v_lshlrev_b32_e32 v156, 1, v156
	v_mov_b32_e32 v157, v189
	v_cvt_pk_bf16_f32 v106, v106, s0
	v_lshl_add_u64 v[158:159], v[138:139], 0, v[156:157]
	global_store_short v[158:159], v106, off
	v_or_b32_e32 v106, 51, v163
	v_mul_f32_e32 v107, v107, v164
	v_mul_u32_u24_e32 v106, s9, v106
	v_cvt_pk_bf16_f32 v160, v107, s0
	v_lshlrev_b32_e32 v106, 1, v106
	v_mov_b32_e32 v107, v189
	v_lshl_add_u64 v[158:159], v[138:139], 0, v[106:107]
	global_store_short v[158:159], v160, off
	v_or_b32_e32 v158, 56, v163
	v_mul_u32_u24_e32 v158, s9, v158
	v_mul_f32_e32 v108, v108, v164
	v_lshlrev_b32_e32 v158, 1, v158
	v_mov_b32_e32 v159, v189
	v_cvt_pk_bf16_f32 v108, v108, s0
	v_lshl_add_u64 v[160:161], v[138:139], 0, v[158:159]
	global_store_short v[160:161], v108, off
	v_or_b32_e32 v108, 57, v163
	v_mul_f32_e32 v109, v109, v164
	v_mul_u32_u24_e32 v108, s9, v108
	v_cvt_pk_bf16_f32 v165, v109, s0
	v_lshlrev_b32_e32 v108, 1, v108
	v_mov_b32_e32 v109, v189
	v_lshl_add_u64 v[160:161], v[138:139], 0, v[108:109]
	global_store_short v[160:161], v165, off
	v_or_b32_e32 v160, 58, v163
	v_mul_u32_u24_e32 v160, s9, v160
	v_mul_f32_e32 v110, v110, v164
	v_lshlrev_b32_e32 v160, 1, v160
	v_mov_b32_e32 v161, v189
	v_cvt_pk_bf16_f32 v110, v110, s0
	v_lshl_add_u64 v[166:167], v[138:139], 0, v[160:161]
	global_store_short v[166:167], v110, off
	v_or_b32_e32 v110, 59, v163
	v_mul_f32_e32 v111, v111, v164
	v_mul_u32_u24_e32 v110, s9, v110
	v_cvt_pk_bf16_f32 v163, v111, s0
	v_lshlrev_b32_e32 v110, 1, v110
	v_mov_b32_e32 v111, v189
	v_lshl_add_u64 v[138:139], v[138:139], 0, v[110:111]
	global_store_short v[138:139], v163, off
	v_or_b32_e32 v138, 32, v176
	v_lshl_add_u32 v163, v138, 2, s8
	ds_read_b32 v163, v163
	s_movk_i32 s9, 0x1fbf
	v_or_b32_e32 v139, s56, v138
	v_bitop3_b32 v138, v138, s9, v162 bitop3:0xc8
	v_cndmask_b32_e64 v138, v138, v139, s[6:7]
	v_lshlrev_b32_e32 v138, 1, v138
	v_mov_b32_e32 v139, v189
	v_lshl_add_u64 v[138:139], v[128:129], 0, v[138:139]
	s_waitcnt lgkmcnt(0)
	v_mul_f32_e32 v80, v80, v163
	v_cvt_pk_bf16_f32 v80, v80, s0
	v_lshl_add_u64 v[164:165], v[138:139], 0, v[188:189]
	global_store_short v[164:165], v80, off
	v_mul_f32_e32 v80, v81, v163
	v_cvt_pk_bf16_f32 v164, v80, s0
	v_lshl_add_u64 v[80:81], v[138:139], 0, v[112:113]
	global_store_short v[80:81], v164, off
	v_mul_f32_e32 v80, v82, v163
	v_cvt_pk_bf16_f32 v82, v80, s0
	v_lshl_add_u64 v[80:81], v[138:139], 0, v[130:131]
	global_store_short v[80:81], v82, off
	v_mul_f32_e32 v80, v83, v163
	v_cvt_pk_bf16_f32 v82, v80, s0
	v_lshl_add_u64 v[80:81], v[138:139], 0, v[114:115]
	global_store_short v[80:81], v82, off
	v_mul_f32_e32 v80, v84, v163
	v_cvt_pk_bf16_f32 v82, v80, s0
	v_lshl_add_u64 v[80:81], v[138:139], 0, v[132:133]
	global_store_short v[80:81], v82, off
	v_mul_f32_e32 v80, v85, v163
	v_cvt_pk_bf16_f32 v82, v80, s0
	v_lshl_add_u64 v[80:81], v[138:139], 0, v[116:117]
	global_store_short v[80:81], v82, off
	v_mul_f32_e32 v80, v86, v163
	v_cvt_pk_bf16_f32 v82, v80, s0
	v_lshl_add_u64 v[80:81], v[138:139], 0, v[134:135]
	global_store_short v[80:81], v82, off
	v_mul_f32_e32 v80, v87, v163
	v_cvt_pk_bf16_f32 v82, v80, s0
	v_lshl_add_u64 v[80:81], v[138:139], 0, v[118:119]
	global_store_short v[80:81], v82, off
	v_mul_f32_e32 v80, v88, v163
	v_cvt_pk_bf16_f32 v82, v80, s0
	v_lshl_add_u64 v[80:81], v[138:139], 0, v[136:137]
	global_store_short v[80:81], v82, off
	v_mul_f32_e32 v80, v89, v163
	v_cvt_pk_bf16_f32 v82, v80, s0
	v_lshl_add_u64 v[80:81], v[138:139], 0, v[120:121]
	global_store_short v[80:81], v82, off
	v_mul_f32_e32 v80, v90, v163
	v_cvt_pk_bf16_f32 v82, v80, s0
	v_lshl_add_u64 v[80:81], v[138:139], 0, v[140:141]
	global_store_short v[80:81], v82, off
	v_mul_f32_e32 v80, v91, v163
	v_cvt_pk_bf16_f32 v82, v80, s0
	v_lshl_add_u64 v[80:81], v[138:139], 0, v[122:123]
	global_store_short v[80:81], v82, off
	v_mul_f32_e32 v80, v92, v163
	v_cvt_pk_bf16_f32 v82, v80, s0
	v_lshl_add_u64 v[80:81], v[138:139], 0, v[142:143]
; DI u16 f2bf(float a) { return (u16)(pack2(a, 0.f) & 0xffffu); }
; DI int crow(int reg, int g) { return (reg & 3) + 8 * (reg >> 2) + 4 * g; }
; template <bool TR>
; DI void gemm_in_tile(const P& p, int l, int id, char* smem) {
;     ...
;     for (int cb = 0; cb < 4; ++cb) {
;       asm volatile("" ::: "memory");
;       const int tl = 128 * wc + 32 * cb + li;
;       const int tok = m0 + tl;
;       const float rs = rs_s[tl];
;       u16* dst = hy ? (p.hyT + (size_t)(n0 + 64 * wr) * HYP + tok)
;                     : (p.VT + (size_t)((tok >> 13) * 512 + (n0 - 3072) + 64 * wr) * VTP + (tok & 8191));
;       const size_t cstride = hy ? (size_t)HYP : (size_t)VTP;
; #pragma unroll
;       for (int rb = 0; rb < 2; ++rb) {
; #pragma unroll
;         for (int reg = 0; reg < 16; ++reg) {
;           const int cl = 32 * rb + crow(reg, g);
;           dst[(size_t)cl * cstride] = f2bf(acc[rb][cb][reg] * rs);
;         }
;       }
	global_store_short v[80:81], v82, off
	v_mul_f32_e32 v80, v93, v163
	v_cvt_pk_bf16_f32 v82, v80, s0
	v_lshl_add_u64 v[80:81], v[138:139], 0, v[124:125]
	global_store_short v[80:81], v82, off
	v_mul_f32_e32 v80, v94, v163
	v_cvt_pk_bf16_f32 v82, v80, s0
	v_lshl_add_u64 v[80:81], v[138:139], 0, v[144:145]
	global_store_short v[80:81], v82, off
	v_mul_f32_e32 v80, v95, v163
	v_cvt_pk_bf16_f32 v82, v80, s0
	v_lshl_add_u64 v[80:81], v[138:139], 0, v[126:127]
	v_mul_f32_e32 v64, v64, v163
	global_store_short v[80:81], v82, off
	v_cvt_pk_bf16_f32 v64, v64, s0
	v_lshl_add_u64 v[80:81], v[138:139], 0, v[146:147]
	global_store_short v[80:81], v64, off
	v_mul_f32_e32 v64, v65, v163
	v_cvt_pk_bf16_f32 v80, v64, s0
	v_lshl_add_u64 v[64:65], v[138:139], 0, v[96:97]
	global_store_short v[64:65], v80, off
	v_mul_f32_e32 v64, v66, v163
	v_cvt_pk_bf16_f32 v66, v64, s0
	v_lshl_add_u64 v[64:65], v[138:139], 0, v[148:149]
	global_store_short v[64:65], v66, off
	v_mul_f32_e32 v64, v67, v163
	v_cvt_pk_bf16_f32 v66, v64, s0
	v_lshl_add_u64 v[64:65], v[138:139], 0, v[98:99]
	global_store_short v[64:65], v66, off
	v_mul_f32_e32 v64, v68, v163
	v_cvt_pk_bf16_f32 v66, v64, s0
	v_lshl_add_u64 v[64:65], v[138:139], 0, v[150:151]
	global_store_short v[64:65], v66, off
	v_mul_f32_e32 v64, v69, v163
	v_cvt_pk_bf16_f32 v66, v64, s0
	v_lshl_add_u64 v[64:65], v[138:139], 0, v[100:101]
	global_store_short v[64:65], v66, off
	v_mul_f32_e32 v64, v70, v163
	v_cvt_pk_bf16_f32 v66, v64, s0
	v_lshl_add_u64 v[64:65], v[138:139], 0, v[152:153]
	global_store_short v[64:65], v66, off
	v_mul_f32_e32 v64, v71, v163
	v_cvt_pk_bf16_f32 v66, v64, s0
	v_lshl_add_u64 v[64:65], v[138:139], 0, v[102:103]
	global_store_short v[64:65], v66, off
	v_mul_f32_e32 v64, v72, v163
	v_cvt_pk_bf16_f32 v66, v64, s0
	v_lshl_add_u64 v[64:65], v[138:139], 0, v[154:155]
	global_store_short v[64:65], v66, off
	v_mul_f32_e32 v64, v73, v163
	v_cvt_pk_bf16_f32 v66, v64, s0
	v_lshl_add_u64 v[64:65], v[138:139], 0, v[104:105]
	global_store_short v[64:65], v66, off
	v_mul_f32_e32 v64, v74, v163
	v_cvt_pk_bf16_f32 v66, v64, s0
	v_lshl_add_u64 v[64:65], v[138:139], 0, v[156:157]
	global_store_short v[64:65], v66, off
	v_mul_f32_e32 v64, v75, v163
	v_cvt_pk_bf16_f32 v66, v64, s0
	v_lshl_add_u64 v[64:65], v[138:139], 0, v[106:107]
	global_store_short v[64:65], v66, off
	v_mul_f32_e32 v64, v76, v163
	v_cvt_pk_bf16_f32 v66, v64, s0
	v_lshl_add_u64 v[64:65], v[138:139], 0, v[158:159]
	global_store_short v[64:65], v66, off
	v_mul_f32_e32 v64, v77, v163
	v_cvt_pk_bf16_f32 v66, v64, s0
	v_lshl_add_u64 v[64:65], v[138:139], 0, v[108:109]
	global_store_short v[64:65], v66, off
	v_mul_f32_e32 v64, v78, v163
	v_cvt_pk_bf16_f32 v66, v64, s0
	v_lshl_add_u64 v[64:65], v[138:139], 0, v[160:161]
	global_store_short v[64:65], v66, off
	v_mul_f32_e32 v64, v79, v163
	v_cvt_pk_bf16_f32 v66, v64, s0
	v_lshl_add_u64 v[64:65], v[138:139], 0, v[110:111]
	global_store_short v[64:65], v66, off
	v_or_b32_e32 v64, 64, v176
	v_lshl_add_u32 v66, v64, 2, s8
	ds_read_b32 v68, v66
	s_movk_i32 s9, 0x1fdf
	v_or_b32_e32 v65, s56, v64
	v_bitop3_b32 v64, v64, s9, v162 bitop3:0xc8
	v_cndmask_b32_e64 v64, v64, v65, s[6:7]
	v_lshlrev_b32_e32 v64, 1, v64
	v_mov_b32_e32 v65, v189
	v_lshl_add_u64 v[64:65], v[128:129], 0, v[64:65]
	s_waitcnt lgkmcnt(0)
	v_mul_f32_e32 v48, v48, v68
	v_cvt_pk_bf16_f32 v48, v48, s0
	v_lshl_add_u64 v[66:67], v[64:65], 0, v[188:189]
	global_store_short v[66:67], v48, off
	v_mul_f32_e32 v48, v49, v68
	v_cvt_pk_bf16_f32 v66, v48, s0
	v_lshl_add_u64 v[48:49], v[64:65], 0, v[112:113]
	global_store_short v[48:49], v66, off
	v_mul_f32_e32 v48, v50, v68
	v_cvt_pk_bf16_f32 v50, v48, s0
	v_lshl_add_u64 v[48:49], v[64:65], 0, v[130:131]
	global_store_short v[48:49], v50, off
	v_mul_f32_e32 v48, v51, v68
	v_cvt_pk_bf16_f32 v50, v48, s0
	v_lshl_add_u64 v[48:49], v[64:65], 0, v[114:115]
	global_store_short v[48:49], v50, off
	v_mul_f32_e32 v48, v52, v68
	v_cvt_pk_bf16_f32 v50, v48, s0
	v_lshl_add_u64 v[48:49], v[64:65], 0, v[132:133]
	global_store_short v[48:49], v50, off
	v_mul_f32_e32 v48, v53, v68
	v_cvt_pk_bf16_f32 v50, v48, s0
	v_lshl_add_u64 v[48:49], v[64:65], 0, v[116:117]
	global_store_short v[48:49], v50, off
	v_mul_f32_e32 v48, v54, v68
	v_cvt_pk_bf16_f32 v50, v48, s0
	v_lshl_add_u64 v[48:49], v[64:65], 0, v[134:135]
	global_store_short v[48:49], v50, off
	v_mul_f32_e32 v48, v55, v68
	v_cvt_pk_bf16_f32 v50, v48, s0
	v_lshl_add_u64 v[48:49], v[64:65], 0, v[118:119]
	global_store_short v[48:49], v50, off
	v_mul_f32_e32 v48, v56, v68
	v_cvt_pk_bf16_f32 v50, v48, s0
	v_lshl_add_u64 v[48:49], v[64:65], 0, v[136:137]
	global_store_short v[48:49], v50, off
	v_mul_f32_e32 v48, v57, v68
	v_cvt_pk_bf16_f32 v50, v48, s0
	v_lshl_add_u64 v[48:49], v[64:65], 0, v[120:121]
	global_store_short v[48:49], v50, off
	v_mul_f32_e32 v48, v58, v68
	v_cvt_pk_bf16_f32 v50, v48, s0
	v_lshl_add_u64 v[48:49], v[64:65], 0, v[140:141]
	global_store_short v[48:49], v50, off
	v_mul_f32_e32 v48, v59, v68
	v_cvt_pk_bf16_f32 v50, v48, s0
	v_lshl_add_u64 v[48:49], v[64:65], 0, v[122:123]
	global_store_short v[48:49], v50, off
	v_mul_f32_e32 v48, v60, v68
	v_cvt_pk_bf16_f32 v50, v48, s0
	v_lshl_add_u64 v[48:49], v[64:65], 0, v[142:143]
	global_store_short v[48:49], v50, off
	v_mul_f32_e32 v48, v61, v68
	v_cvt_pk_bf16_f32 v50, v48, s0
	v_lshl_add_u64 v[48:49], v[64:65], 0, v[124:125]
	global_store_short v[48:49], v50, off
	v_mul_f32_e32 v48, v62, v68
	v_cvt_pk_bf16_f32 v50, v48, s0
	v_lshl_add_u64 v[48:49], v[64:65], 0, v[144:145]
	global_store_short v[48:49], v50, off
	v_mul_f32_e32 v48, v63, v68
	v_cvt_pk_bf16_f32 v50, v48, s0
	v_lshl_add_u64 v[48:49], v[64:65], 0, v[126:127]
; DI u16 f2bf(float a) { return (u16)(pack2(a, 0.f) & 0xffffu); }
; DI int crow(int reg, int g) { return (reg & 3) + 8 * (reg >> 2) + 4 * g; }
; template <bool TR>
; DI void gemm_in_tile(const P& p, int l, int id, char* smem) {
;     ...
;     for (int cb = 0; cb < 4; ++cb) {
;       asm volatile("" ::: "memory");
;       const int tl = 128 * wc + 32 * cb + li;
;       const int tok = m0 + tl;
;       const float rs = rs_s[tl];
;       u16* dst = hy ? (p.hyT + (size_t)(n0 + 64 * wr) * HYP + tok)
;                     : (p.VT + (size_t)((tok >> 13) * 512 + (n0 - 3072) + 64 * wr) * VTP + (tok & 8191));
;       const size_t cstride = hy ? (size_t)HYP : (size_t)VTP;
; #pragma unroll
;       for (int rb = 0; rb < 2; ++rb) {
; #pragma unroll
;         for (int reg = 0; reg < 16; ++reg) {
;           const int cl = 32 * rb + crow(reg, g);
;           dst[(size_t)cl * cstride] = f2bf(acc[rb][cb][reg] * rs);
;         }
;       }
	v_mul_f32_e32 v32, v32, v68
	global_store_short v[48:49], v50, off
	v_cvt_pk_bf16_f32 v32, v32, s0
	v_lshl_add_u64 v[48:49], v[64:65], 0, v[146:147]
	global_store_short v[48:49], v32, off
	v_mul_f32_e32 v32, v33, v68
	v_cvt_pk_bf16_f32 v48, v32, s0
	v_lshl_add_u64 v[32:33], v[64:65], 0, v[96:97]
	global_store_short v[32:33], v48, off
	v_mul_f32_e32 v32, v34, v68
	v_cvt_pk_bf16_f32 v34, v32, s0
	v_lshl_add_u64 v[32:33], v[64:65], 0, v[148:149]
	global_store_short v[32:33], v34, off
	v_mul_f32_e32 v32, v35, v68
	v_cvt_pk_bf16_f32 v34, v32, s0
	v_lshl_add_u64 v[32:33], v[64:65], 0, v[98:99]
	global_store_short v[32:33], v34, off
	v_mul_f32_e32 v32, v36, v68
	v_cvt_pk_bf16_f32 v34, v32, s0
	v_lshl_add_u64 v[32:33], v[64:65], 0, v[150:151]
	global_store_short v[32:33], v34, off
	v_mul_f32_e32 v32, v37, v68
	v_cvt_pk_bf16_f32 v34, v32, s0
	v_lshl_add_u64 v[32:33], v[64:65], 0, v[100:101]
	global_store_short v[32:33], v34, off
	v_mul_f32_e32 v32, v38, v68
	v_cvt_pk_bf16_f32 v34, v32, s0
	v_lshl_add_u64 v[32:33], v[64:65], 0, v[152:153]
	global_store_short v[32:33], v34, off
	v_mul_f32_e32 v32, v39, v68
	v_cvt_pk_bf16_f32 v34, v32, s0
	v_lshl_add_u64 v[32:33], v[64:65], 0, v[102:103]
	global_store_short v[32:33], v34, off
	v_mul_f32_e32 v32, v40, v68
	v_cvt_pk_bf16_f32 v34, v32, s0
	v_lshl_add_u64 v[32:33], v[64:65], 0, v[154:155]
	global_store_short v[32:33], v34, off
	v_mul_f32_e32 v32, v41, v68
	v_cvt_pk_bf16_f32 v34, v32, s0
	v_lshl_add_u64 v[32:33], v[64:65], 0, v[104:105]
	global_store_short v[32:33], v34, off
	v_mul_f32_e32 v32, v42, v68
	v_cvt_pk_bf16_f32 v34, v32, s0
	v_lshl_add_u64 v[32:33], v[64:65], 0, v[156:157]
	global_store_short v[32:33], v34, off
	v_mul_f32_e32 v32, v43, v68
	v_cvt_pk_bf16_f32 v34, v32, s0
	v_lshl_add_u64 v[32:33], v[64:65], 0, v[106:107]
	global_store_short v[32:33], v34, off
	v_mul_f32_e32 v32, v44, v68
	v_cvt_pk_bf16_f32 v34, v32, s0
	v_lshl_add_u64 v[32:33], v[64:65], 0, v[158:159]
	global_store_short v[32:33], v34, off
	v_mul_f32_e32 v32, v45, v68
	v_cvt_pk_bf16_f32 v34, v32, s0
	v_lshl_add_u64 v[32:33], v[64:65], 0, v[108:109]
	global_store_short v[32:33], v34, off
	v_mul_f32_e32 v32, v46, v68
	v_cvt_pk_bf16_f32 v34, v32, s0
	v_lshl_add_u64 v[32:33], v[64:65], 0, v[160:161]
	global_store_short v[32:33], v34, off
	v_mul_f32_e32 v32, v47, v68
	v_cvt_pk_bf16_f32 v34, v32, s0
	v_lshl_add_u64 v[32:33], v[64:65], 0, v[110:111]
	global_store_short v[32:33], v34, off
	v_or_b32_e32 v32, 0x60, v176
	v_lshl_add_u32 v34, v32, 2, s8
	ds_read_b32 v36, v34
	s_movk_i32 s8, 0x1fff
	v_or_b32_e32 v33, s56, v32
	v_bitop3_b32 v32, v32, s8, v162 bitop3:0xc8
	v_cndmask_b32_e64 v32, v32, v33, s[6:7]
	v_lshlrev_b32_e32 v32, 1, v32
	v_mov_b32_e32 v33, v189
	v_lshl_add_u64 v[32:33], v[128:129], 0, v[32:33]
	s_waitcnt lgkmcnt(0)
; DI u16 f2bf(float a) { return (u16)(pack2(a, 0.f) & 0xffffu); }
; DI int crow(int reg, int g) { return (reg & 3) + 8 * (reg >> 2) + 4 * g; }
; template <bool TR>
; DI void gemm_in_tile(const P& p, int l, int id, char* smem) {
;     ...
;     for (int cb = 0; cb < 4; ++cb) {
;       asm volatile("" ::: "memory");
;       const int tl = 128 * wc + 32 * cb + li;
;       const int tok = m0 + tl;
;       const float rs = rs_s[tl];
;       u16* dst = hy ? (p.hyT + (size_t)(n0 + 64 * wr) * HYP + tok)
;                     : (p.VT + (size_t)((tok >> 13) * 512 + (n0 - 3072) + 64 * wr) * VTP + (tok & 8191));
;       const size_t cstride = hy ? (size_t)HYP : (size_t)VTP;
; #pragma unroll
;       for (int rb = 0; rb < 2; ++rb) {
; #pragma unroll
;         for (int reg = 0; reg < 16; ++reg) {
;           const int cl = 32 * rb + crow(reg, g);
;           dst[(size_t)cl * cstride] = f2bf(acc[rb][cb][reg] * rs);
;         }
;       }
	v_mul_f32_e32 v16, v16, v36
	v_cvt_pk_bf16_f32 v16, v16, s0
	v_lshl_add_u64 v[34:35], v[32:33], 0, v[188:189]
	global_store_short v[34:35], v16, off
	v_mul_f32_e32 v16, v17, v36
	v_cvt_pk_bf16_f32 v34, v16, s0
	v_lshl_add_u64 v[16:17], v[32:33], 0, v[112:113]
	global_store_short v[16:17], v34, off
	v_mul_f32_e32 v16, v18, v36
	v_cvt_pk_bf16_f32 v18, v16, s0
	v_lshl_add_u64 v[16:17], v[32:33], 0, v[130:131]
	global_store_short v[16:17], v18, off
	v_mul_f32_e32 v16, v19, v36
	v_cvt_pk_bf16_f32 v18, v16, s0
	v_lshl_add_u64 v[16:17], v[32:33], 0, v[114:115]
	global_store_short v[16:17], v18, off
	v_mul_f32_e32 v16, v20, v36
	v_cvt_pk_bf16_f32 v18, v16, s0
	v_lshl_add_u64 v[16:17], v[32:33], 0, v[132:133]
	global_store_short v[16:17], v18, off
	v_mul_f32_e32 v16, v21, v36
	v_cvt_pk_bf16_f32 v18, v16, s0
	v_lshl_add_u64 v[16:17], v[32:33], 0, v[116:117]
	global_store_short v[16:17], v18, off
	v_mul_f32_e32 v16, v22, v36
	v_cvt_pk_bf16_f32 v18, v16, s0
	v_lshl_add_u64 v[16:17], v[32:33], 0, v[134:135]
	global_store_short v[16:17], v18, off
	v_mul_f32_e32 v16, v23, v36
	v_cvt_pk_bf16_f32 v18, v16, s0
	v_lshl_add_u64 v[16:17], v[32:33], 0, v[118:119]
	global_store_short v[16:17], v18, off
	v_mul_f32_e32 v16, v24, v36
	v_cvt_pk_bf16_f32 v18, v16, s0
	v_lshl_add_u64 v[16:17], v[32:33], 0, v[136:137]
	global_store_short v[16:17], v18, off
	v_mul_f32_e32 v16, v25, v36
	v_cvt_pk_bf16_f32 v18, v16, s0
	v_lshl_add_u64 v[16:17], v[32:33], 0, v[120:121]
	global_store_short v[16:17], v18, off
	v_mul_f32_e32 v16, v26, v36
	v_cvt_pk_bf16_f32 v18, v16, s0
	v_lshl_add_u64 v[16:17], v[32:33], 0, v[140:141]
	global_store_short v[16:17], v18, off
	v_mul_f32_e32 v16, v27, v36
	v_cvt_pk_bf16_f32 v18, v16, s0
	v_lshl_add_u64 v[16:17], v[32:33], 0, v[122:123]
	global_store_short v[16:17], v18, off
	v_mul_f32_e32 v16, v28, v36
	v_cvt_pk_bf16_f32 v18, v16, s0
	v_lshl_add_u64 v[16:17], v[32:33], 0, v[142:143]
	global_store_short v[16:17], v18, off
	v_mul_f32_e32 v16, v29, v36
	v_cvt_pk_bf16_f32 v18, v16, s0
	v_lshl_add_u64 v[16:17], v[32:33], 0, v[124:125]
	global_store_short v[16:17], v18, off
	v_mul_f32_e32 v16, v30, v36
	v_cvt_pk_bf16_f32 v18, v16, s0
	v_lshl_add_u64 v[16:17], v[32:33], 0, v[144:145]
	global_store_short v[16:17], v18, off
	v_mul_f32_e32 v16, v31, v36
	v_cvt_pk_bf16_f32 v18, v16, s0
	v_lshl_add_u64 v[16:17], v[32:33], 0, v[126:127]
	v_mul_f32_e32 v0, v0, v36
	global_store_short v[16:17], v18, off
	v_cvt_pk_bf16_f32 v0, v0, s0
	v_lshl_add_u64 v[16:17], v[32:33], 0, v[146:147]
	global_store_short v[16:17], v0, off
	v_mul_f32_e32 v0, v1, v36
	v_cvt_pk_bf16_f32 v16, v0, s0
	v_lshl_add_u64 v[0:1], v[32:33], 0, v[96:97]
	global_store_short v[0:1], v16, off
	v_mul_f32_e32 v0, v2, v36
	v_cvt_pk_bf16_f32 v2, v0, s0
	v_lshl_add_u64 v[0:1], v[32:33], 0, v[148:149]
	global_store_short v[0:1], v2, off
	v_mul_f32_e32 v0, v3, v36
	v_cvt_pk_bf16_f32 v2, v0, s0
	v_lshl_add_u64 v[0:1], v[32:33], 0, v[98:99]
	global_store_short v[0:1], v2, off
	v_mul_f32_e32 v0, v4, v36
	v_cvt_pk_bf16_f32 v2, v0, s0
	v_lshl_add_u64 v[0:1], v[32:33], 0, v[150:151]
	global_store_short v[0:1], v2, off
	v_mul_f32_e32 v0, v5, v36
	v_cvt_pk_bf16_f32 v2, v0, s0
	v_lshl_add_u64 v[0:1], v[32:33], 0, v[100:101]
	global_store_short v[0:1], v2, off
	v_mul_f32_e32 v0, v6, v36
	v_cvt_pk_bf16_f32 v2, v0, s0
	v_lshl_add_u64 v[0:1], v[32:33], 0, v[152:153]
	global_store_short v[0:1], v2, off
	v_mul_f32_e32 v0, v7, v36
	v_cvt_pk_bf16_f32 v2, v0, s0
	v_lshl_add_u64 v[0:1], v[32:33], 0, v[102:103]
	global_store_short v[0:1], v2, off
	v_mul_f32_e32 v0, v8, v36
	v_cvt_pk_bf16_f32 v2, v0, s0
	v_lshl_add_u64 v[0:1], v[32:33], 0, v[154:155]
	global_store_short v[0:1], v2, off
	v_mul_f32_e32 v0, v9, v36
	v_cvt_pk_bf16_f32 v2, v0, s0
	v_lshl_add_u64 v[0:1], v[32:33], 0, v[104:105]
	global_store_short v[0:1], v2, off
	v_mul_f32_e32 v0, v10, v36
	v_cvt_pk_bf16_f32 v2, v0, s0
	v_lshl_add_u64 v[0:1], v[32:33], 0, v[156:157]
	global_store_short v[0:1], v2, off
	v_mul_f32_e32 v0, v11, v36
	v_cvt_pk_bf16_f32 v2, v0, s0
	v_lshl_add_u64 v[0:1], v[32:33], 0, v[106:107]
	global_store_short v[0:1], v2, off
	v_mul_f32_e32 v0, v12, v36
	v_cvt_pk_bf16_f32 v2, v0, s0
	v_lshl_add_u64 v[0:1], v[32:33], 0, v[158:159]
	global_store_short v[0:1], v2, off
	v_mul_f32_e32 v0, v13, v36
	v_cvt_pk_bf16_f32 v2, v0, s0
	v_lshl_add_u64 v[0:1], v[32:33], 0, v[108:109]
	global_store_short v[0:1], v2, off
	v_mul_f32_e32 v0, v14, v36
	v_cvt_pk_bf16_f32 v2, v0, s0
	v_lshl_add_u64 v[0:1], v[32:33], 0, v[160:161]
	global_store_short v[0:1], v2, off
	v_mul_f32_e32 v0, v15, v36
	v_cvt_pk_bf16_f32 v2, v0, s0
	v_lshl_add_u64 v[0:1], v[32:33], 0, v[110:111]
	global_store_short v[0:1], v2, off
	s_branch .LBB0_102

; __global__ void __launch_bounds__(NT) mega(P p) {
	.amdhsa_kernel _Z4mega1P
		.amdhsa_group_segment_fixed_size 0
		.amdhsa_private_segment_fixed_size 0
		.amdhsa_kernarg_size 560
		.amdhsa_user_sgpr_count 2
		.amdhsa_user_sgpr_dispatch_ptr 0
		.amdhsa_user_sgpr_queue_ptr 0
		.amdhsa_user_sgpr_kernarg_segment_ptr 1
		.amdhsa_user_sgpr_dispatch_id 0
		.amdhsa_user_sgpr_kernarg_preload_length 0
		.amdhsa_user_sgpr_kernarg_preload_offset 0
		.amdhsa_user_sgpr_private_segment_size 0
		.amdhsa_uses_dynamic_stack 0
		.amdhsa_enable_private_segment 0
		.amdhsa_system_sgpr_workgroup_id_x 1
		.amdhsa_system_sgpr_workgroup_id_y 0
		.amdhsa_system_sgpr_workgroup_id_z 0
		.amdhsa_system_sgpr_workgroup_info 0
		.amdhsa_system_vgpr_workitem_id 2
		.amdhsa_next_free_vgpr 252
		.amdhsa_next_free_sgpr 102
		.amdhsa_accum_offset 252
		.amdhsa_reserve_vcc 1
		.amdhsa_float_round_mode_32 0
		.amdhsa_float_round_mode_16_64 0
		.amdhsa_float_denorm_mode_32 3
		.amdhsa_float_denorm_mode_16_64 3
		.amdhsa_dx10_clamp 1
		.amdhsa_ieee_mode 1
		.amdhsa_fp16_overflow 0
		.amdhsa_tg_split 0
		.amdhsa_exception_fp_ieee_invalid_op 0
		.amdhsa_exception_fp_denorm_src 0
		.amdhsa_exception_fp_ieee_div_zero 0
		.amdhsa_exception_fp_ieee_overflow 0
		.amdhsa_exception_fp_ieee_underflow 0
		.amdhsa_exception_fp_ieee_inexact 0
		.amdhsa_exception_int_div_zero 0
	.end_amdhsa_kernel

; __global__ void __launch_bounds__(NT) mega(P p) {
amdhsa.kernels:
  - .agpr_count:     0
    .args:
      - .offset:         0
        .size:           304
        .value_kind:     by_value
      - .offset:         304
        .size:           4
        .value_kind:     hidden_block_count_x
      - .offset:         308
        .size:           4
        .value_kind:     hidden_block_count_y
      - .offset:         312
        .size:           4
        .value_kind:     hidden_block_count_z
      - .offset:         316
        .size:           2
        .value_kind:     hidden_group_size_x
      - .offset:         318
        .size:           2
        .value_kind:     hidden_group_size_y
      - .offset:         320
        .size:           2
        .value_kind:     hidden_group_size_z
      - .offset:         322
        .size:           2
        .value_kind:     hidden_remainder_x
      - .offset:         324
        .size:           2
        .value_kind:     hidden_remainder_y
      - .offset:         326
        .size:           2
        .value_kind:     hidden_remainder_z
      - .offset:         344
        .size:           8
        .value_kind:     hidden_global_offset_x
      - .offset:         352
        .size:           8
        .value_kind:     hidden_global_offset_y
      - .offset:         360
        .size:           8
        .value_kind:     hidden_global_offset_z
      - .offset:         368
        .size:           2
        .value_kind:     hidden_grid_dims
      - .offset:         392
        .size:           8
        .value_kind:     hidden_multigrid_sync_arg
      - .offset:         424
        .size:           4
        .value_kind:     hidden_dynamic_lds_size
    .group_segment_fixed_size: 0
    .kernarg_segment_align: 8
    .kernarg_segment_size: 560
    .language:       OpenCL C
    .language_version:
      - 2
      - 0
    .max_flat_workgroup_size: 512
    .name:           _Z4mega1P
    .private_segment_fixed_size: 0
    .sgpr_count:     108
    .sgpr_spill_count: 54
    .symbol:         _Z4mega1P.kd
    .uniform_work_group_size: 1
    .uses_dynamic_stack: false
    .vgpr_count:     252
    .vgpr_spill_count: 0
    .wavefront_size: 64
